# v111_kloop_dma_address_adds_moved_off_the_segment_head
# baseline (speedup 1.0000x reference)
.LBB0_188:
	ds_read_b128 v[152:155], v147
	ds_read_b128 v[156:159], v147 offset:1024
	ds_read_b128 v[160:163], v147 offset:2048
	ds_read_b128 v[164:167], v147 offset:3072
	ds_read_b128 v[168:171], v149
	ds_read_b128 v[172:175], v149 offset:1024
	ds_read_b128 v[176:179], v149 offset:2048
	ds_read_b128 v[180:183], v149 offset:3072
	s_cmp_eq_u32 s8, 12
	s_cselect_b32 s49, s0, s3
	s_cselect_b32 s48, s1, s2
	s_or_b32 s9, s49, 0x80
	v_mov_b32_e32 v136, v135
	ds_read_b128 v[188:191], v150
	ds_read_b128 v[192:195], v150 offset:1024
	ds_read_b128 v[196:199], v150 offset:2048
	ds_read_b128 v[200:203], v150 offset:3072
	ds_read_b128 v[204:207], v150 offset:4096
	ds_read_b128 v[208:211], v150 offset:5120
	ds_read_b128 v[212:215], v150 offset:6144
	ds_read_b128 v[216:219], v150 offset:7168
	s_add_i32 m0, s25, 0xc000
	s_nop 0
	global_load_lds_dwordx4 v136, s[10:11]
	v_mov_b32_e32 v136, v134
	s_add_i32 m0, s25, 0xe000
	s_nop 0
	global_load_lds_dwordx4 v136, s[10:11]
	s_waitcnt vmcnt(8)
	s_waitcnt lgkmcnt(0)
	s_barrier
	s_waitcnt lgkmcnt(0)
	v_mfma_f32_16x16x32_bf16 v[124:127], v[152:155], v[188:191], v[124:127]
	v_mfma_f32_16x16x32_bf16 v[120:123], v[160:163], v[188:191], v[120:123]
	v_mfma_f32_16x16x32_bf16 v[108:111], v[152:155], v[196:199], v[108:111]
	v_mfma_f32_16x16x32_bf16 v[104:107], v[160:163], v[196:199], v[104:107]
	v_mfma_f32_16x16x32_bf16 v[92:95], v[152:155], v[204:207], v[92:95]
	v_mfma_f32_16x16x32_bf16 v[88:91], v[160:163], v[204:207], v[88:91]
	v_mfma_f32_16x16x32_bf16 v[76:79], v[152:155], v[212:215], v[76:79]
	v_mfma_f32_16x16x32_bf16 v[72:75], v[160:163], v[212:215], v[72:75]
	v_mfma_f32_16x16x32_bf16 v[124:127], v[156:159], v[192:195], v[124:127]
	v_mfma_f32_16x16x32_bf16 v[120:123], v[164:167], v[192:195], v[120:123]
	v_mfma_f32_16x16x32_bf16 v[108:111], v[156:159], v[200:203], v[108:111]
	v_mfma_f32_16x16x32_bf16 v[104:107], v[164:167], v[200:203], v[104:107]
	v_mfma_f32_16x16x32_bf16 v[92:95], v[156:159], v[208:211], v[92:95]
	v_mfma_f32_16x16x32_bf16 v[88:91], v[164:167], v[208:211], v[88:91]
	v_mfma_f32_16x16x32_bf16 v[76:79], v[156:159], v[216:219], v[76:79]
	v_mfma_f32_16x16x32_bf16 v[72:75], v[164:167], v[216:219], v[72:75]
	v_mfma_f32_16x16x32_bf16 v[116:119], v[168:171], v[188:191], v[116:119]
	v_mfma_f32_16x16x32_bf16 v[112:115], v[176:179], v[188:191], v[112:115]
	v_mfma_f32_16x16x32_bf16 v[100:103], v[168:171], v[196:199], v[100:103]
	v_mfma_f32_16x16x32_bf16 v[96:99], v[176:179], v[196:199], v[96:99]
	v_mfma_f32_16x16x32_bf16 v[84:87], v[168:171], v[204:207], v[84:87]
	v_mfma_f32_16x16x32_bf16 v[80:83], v[176:179], v[204:207], v[80:83]
	v_mfma_f32_16x16x32_bf16 v[68:71], v[168:171], v[212:215], v[68:71]
	v_mfma_f32_16x16x32_bf16 v[64:67], v[176:179], v[212:215], v[64:67]
	v_mfma_f32_16x16x32_bf16 v[116:119], v[172:175], v[192:195], v[116:119]
	v_mfma_f32_16x16x32_bf16 v[112:115], v[180:183], v[192:195], v[112:115]
	v_mfma_f32_16x16x32_bf16 v[100:103], v[172:175], v[200:203], v[100:103]
	v_mfma_f32_16x16x32_bf16 v[96:99], v[180:183], v[200:203], v[96:99]
	v_mfma_f32_16x16x32_bf16 v[84:87], v[172:175], v[208:211], v[84:87]
	v_mfma_f32_16x16x32_bf16 v[80:83], v[180:183], v[208:211], v[80:83]
	v_mfma_f32_16x16x32_bf16 v[68:71], v[172:175], v[216:219], v[68:71]
	v_mfma_f32_16x16x32_bf16 v[64:67], v[180:183], v[216:219], v[64:67]
	s_barrier
	s_add_i32 s50, s41, s24
	ds_read_b128 v[188:191], v150 offset:16384
	ds_read_b128 v[192:195], v150 offset:17408
	ds_read_b128 v[196:199], v150 offset:18432
	ds_read_b128 v[200:203], v150 offset:19456
	ds_read_b128 v[204:207], v150 offset:20480
	ds_read_b128 v[208:211], v150 offset:21504
	ds_read_b128 v[212:215], v150 offset:22528
	ds_read_b128 v[216:219], v150 offset:23552
	v_add_u32_e32 v136, s48, v139
	s_mov_b32 m0, s50
	s_add_i32 s51, s42, s24
	global_load_lds_dwordx4 v136, s[12:13]
	v_add_u32_e32 v136, s48, v141
	s_add_i32 m0, s50, 0x2000
	s_add_i32 s50, s48, 0x40000
	global_load_lds_dwordx4 v136, s[12:13]
	v_add_u32_e32 v136, s50, v139
	s_mov_b32 m0, s51
	s_nop 0
	global_load_lds_dwordx4 v136, s[12:13]
	v_add_u32_e32 v136, s50, v141
	s_add_i32 m0, s51, 0x2000
	s_nop 0
	global_load_lds_dwordx4 v136, s[12:13]
	v_add_u32_e32 v136, s49, v138
	s_mov_b32 m0, s25
	s_nop 0
	global_load_lds_dwordx4 v136, s[10:11]
	v_add_u32_e32 v136, s49, v140
	s_mov_b32 m0, s26
	s_nop 0
	global_load_lds_dwordx4 v136, s[10:11]
	s_waitcnt vmcnt(8)
	s_waitcnt lgkmcnt(0)
	s_barrier
	s_waitcnt lgkmcnt(0)
	v_mfma_f32_16x16x32_bf16 v[60:63], v[152:155], v[188:191], v[60:63]
	v_mfma_f32_16x16x32_bf16 v[56:59], v[160:163], v[188:191], v[56:59]
	v_mfma_f32_16x16x32_bf16 v[44:47], v[152:155], v[196:199], v[44:47]
	v_mfma_f32_16x16x32_bf16 v[40:43], v[160:163], v[196:199], v[40:43]
	v_mfma_f32_16x16x32_bf16 v[28:31], v[152:155], v[204:207], v[28:31]
	v_mfma_f32_16x16x32_bf16 v[24:27], v[160:163], v[204:207], v[24:27]
	v_mfma_f32_16x16x32_bf16 v[12:15], v[152:155], v[212:215], v[12:15]
	v_mfma_f32_16x16x32_bf16 v[8:11], v[160:163], v[212:215], v[8:11]
	v_mfma_f32_16x16x32_bf16 v[60:63], v[156:159], v[192:195], v[60:63]
	v_mfma_f32_16x16x32_bf16 v[56:59], v[164:167], v[192:195], v[56:59]
	v_mfma_f32_16x16x32_bf16 v[44:47], v[156:159], v[200:203], v[44:47]
	v_mfma_f32_16x16x32_bf16 v[40:43], v[164:167], v[200:203], v[40:43]
	v_mfma_f32_16x16x32_bf16 v[28:31], v[156:159], v[208:211], v[28:31]
	v_mfma_f32_16x16x32_bf16 v[24:27], v[164:167], v[208:211], v[24:27]
	v_mfma_f32_16x16x32_bf16 v[12:15], v[156:159], v[216:219], v[12:15]
	v_mfma_f32_16x16x32_bf16 v[8:11], v[164:167], v[216:219], v[8:11]
	v_mfma_f32_16x16x32_bf16 v[52:55], v[168:171], v[188:191], v[52:55]
	v_mfma_f32_16x16x32_bf16 v[48:51], v[176:179], v[188:191], v[48:51]
	v_mfma_f32_16x16x32_bf16 v[36:39], v[168:171], v[196:199], v[36:39]
	v_mfma_f32_16x16x32_bf16 v[32:35], v[176:179], v[196:199], v[32:35]
	v_mfma_f32_16x16x32_bf16 v[20:23], v[168:171], v[204:207], v[20:23]
	v_mfma_f32_16x16x32_bf16 v[16:19], v[176:179], v[204:207], v[16:19]
	v_mfma_f32_16x16x32_bf16 v[4:7], v[168:171], v[212:215], v[4:7]
	v_mfma_f32_16x16x32_bf16 v[0:3], v[176:179], v[212:215], v[0:3]
	v_mfma_f32_16x16x32_bf16 v[52:55], v[172:175], v[192:195], v[52:55]
	v_mfma_f32_16x16x32_bf16 v[48:51], v[180:183], v[192:195], v[48:51]
	v_mfma_f32_16x16x32_bf16 v[36:39], v[172:175], v[200:203], v[36:39]
	v_mfma_f32_16x16x32_bf16 v[32:35], v[180:183], v[200:203], v[32:35]
	v_mfma_f32_16x16x32_bf16 v[20:23], v[172:175], v[208:211], v[20:23]
	v_mfma_f32_16x16x32_bf16 v[16:19], v[180:183], v[208:211], v[16:19]
	v_mfma_f32_16x16x32_bf16 v[4:7], v[172:175], v[216:219], v[4:7]
	v_mfma_f32_16x16x32_bf16 v[0:3], v[180:183], v[216:219], v[0:3]
	s_barrier
	s_add_i32 s50, 0, 0x18000
	v_add_u32_e32 v136, s50, v143
	s_add_i32 s51, 0, 0x1c000
	ds_read_b128 v[152:155], v136
	ds_read_b128 v[156:159], v136 offset:1024
	ds_read_b128 v[160:163], v136 offset:2048
	ds_read_b128 v[164:167], v136 offset:3072
	v_add_u32_e32 v136, s51, v143
	ds_read_b128 v[168:171], v136
	ds_read_b128 v[172:175], v136 offset:1024
	ds_read_b128 v[176:179], v136 offset:2048
	ds_read_b128 v[180:183], v136 offset:3072
	s_add_i32 s49, s49, 0x40000
	v_add_u32_e32 v136, s49, v138
	s_mov_b32 m0, s27
	ds_read_b128 v[188:191], v150 offset:32768
	ds_read_b128 v[192:195], v150 offset:33792
	ds_read_b128 v[196:199], v150 offset:34816
	ds_read_b128 v[200:203], v150 offset:35840
	ds_read_b128 v[204:207], v150 offset:36864
	ds_read_b128 v[208:211], v150 offset:37888
	ds_read_b128 v[212:215], v150 offset:38912
	ds_read_b128 v[216:219], v150 offset:39936
	s_nop 0
	global_load_lds_dwordx4 v136, s[10:11]
	v_add_u32_e32 v136, s49, v140
	s_mov_b32 m0, s28
	s_nop 0
	global_load_lds_dwordx4 v136, s[10:11]
	s_waitcnt vmcnt(8)
	s_waitcnt lgkmcnt(0)
	s_barrier
	s_waitcnt lgkmcnt(0)
	v_mfma_f32_16x16x32_bf16 v[124:127], v[152:155], v[188:191], v[124:127]
	v_mfma_f32_16x16x32_bf16 v[120:123], v[160:163], v[188:191], v[120:123]
	v_mfma_f32_16x16x32_bf16 v[108:111], v[152:155], v[196:199], v[108:111]
	v_mfma_f32_16x16x32_bf16 v[104:107], v[160:163], v[196:199], v[104:107]
	v_mfma_f32_16x16x32_bf16 v[92:95], v[152:155], v[204:207], v[92:95]
	v_mfma_f32_16x16x32_bf16 v[88:91], v[160:163], v[204:207], v[88:91]
	v_mfma_f32_16x16x32_bf16 v[76:79], v[152:155], v[212:215], v[76:79]
	v_mfma_f32_16x16x32_bf16 v[72:75], v[160:163], v[212:215], v[72:75]
	v_mfma_f32_16x16x32_bf16 v[124:127], v[156:159], v[192:195], v[124:127]
	v_mfma_f32_16x16x32_bf16 v[120:123], v[164:167], v[192:195], v[120:123]
	v_mfma_f32_16x16x32_bf16 v[108:111], v[156:159], v[200:203], v[108:111]
	v_mfma_f32_16x16x32_bf16 v[104:107], v[164:167], v[200:203], v[104:107]
	v_mfma_f32_16x16x32_bf16 v[92:95], v[156:159], v[208:211], v[92:95]
	v_mfma_f32_16x16x32_bf16 v[88:91], v[164:167], v[208:211], v[88:91]
	v_mfma_f32_16x16x32_bf16 v[76:79], v[156:159], v[216:219], v[76:79]
	v_mfma_f32_16x16x32_bf16 v[72:75], v[164:167], v[216:219], v[72:75]
	v_mfma_f32_16x16x32_bf16 v[116:119], v[168:171], v[188:191], v[116:119]
	v_mfma_f32_16x16x32_bf16 v[112:115], v[176:179], v[188:191], v[112:115]
	v_mfma_f32_16x16x32_bf16 v[100:103], v[168:171], v[196:199], v[100:103]
	v_mfma_f32_16x16x32_bf16 v[96:99], v[176:179], v[196:199], v[96:99]
	v_mfma_f32_16x16x32_bf16 v[84:87], v[168:171], v[204:207], v[84:87]
	v_mfma_f32_16x16x32_bf16 v[80:83], v[176:179], v[204:207], v[80:83]
	v_mfma_f32_16x16x32_bf16 v[68:71], v[168:171], v[212:215], v[68:71]
	v_mfma_f32_16x16x32_bf16 v[64:67], v[176:179], v[212:215], v[64:67]
	v_mfma_f32_16x16x32_bf16 v[116:119], v[172:175], v[192:195], v[116:119]
	v_mfma_f32_16x16x32_bf16 v[112:115], v[180:183], v[192:195], v[112:115]
	v_mfma_f32_16x16x32_bf16 v[100:103], v[172:175], v[200:203], v[100:103]
	v_mfma_f32_16x16x32_bf16 v[96:99], v[180:183], v[200:203], v[96:99]
	v_mfma_f32_16x16x32_bf16 v[84:87], v[172:175], v[208:211], v[84:87]
	v_mfma_f32_16x16x32_bf16 v[80:83], v[180:183], v[208:211], v[80:83]
	v_mfma_f32_16x16x32_bf16 v[68:71], v[172:175], v[216:219], v[68:71]
	v_mfma_f32_16x16x32_bf16 v[64:67], v[180:183], v[216:219], v[64:67]
	s_barrier
	s_or_b32 s49, s48, 0x80
	v_add_u32_e32 v136, s49, v139
	s_add_i32 s50, s50, s24
	ds_read_b128 v[188:191], v150 offset:49152
	ds_read_b128 v[192:195], v150 offset:50176
	ds_read_b128 v[196:199], v150 offset:51200
	ds_read_b128 v[200:203], v150 offset:52224
	ds_read_b128 v[204:207], v150 offset:53248
	ds_read_b128 v[208:211], v150 offset:54272
	ds_read_b128 v[212:215], v150 offset:55296
	ds_read_b128 v[216:219], v150 offset:56320
	s_mov_b32 m0, s50
	s_add_i32 s48, s48, 0x40080
	global_load_lds_dwordx4 v136, s[12:13]
	v_add_u32_e32 v136, s49, v141
	s_add_i32 m0, s50, 0x2000
	s_add_i32 s49, s51, s24
	global_load_lds_dwordx4 v136, s[12:13]
	v_add_u32_e32 v136, s48, v139
	s_mov_b32 m0, s49
	s_nop 0
	global_load_lds_dwordx4 v136, s[12:13]
	v_add_u32_e32 v136, s48, v141
	s_add_i32 m0, s49, 0x2000
	s_nop 0
	global_load_lds_dwordx4 v136, s[12:13]
	v_add_u32_e32 v136, s9, v138
	s_mov_b32 m0, s30
	s_nop 0
	global_load_lds_dwordx4 v136, s[10:11]
	v_add_u32_e32 v136, s9, v140
	s_mov_b32 m0, s31
	s_nop 0
	global_load_lds_dwordx4 v136, s[10:11]
	s_waitcnt vmcnt(8)
	s_waitcnt lgkmcnt(0)
	s_barrier
	s_waitcnt lgkmcnt(0)
	v_mfma_f32_16x16x32_bf16 v[60:63], v[152:155], v[188:191], v[60:63]
	v_mfma_f32_16x16x32_bf16 v[56:59], v[160:163], v[188:191], v[56:59]
	v_mfma_f32_16x16x32_bf16 v[44:47], v[152:155], v[196:199], v[44:47]
	v_mfma_f32_16x16x32_bf16 v[40:43], v[160:163], v[196:199], v[40:43]
	v_mfma_f32_16x16x32_bf16 v[28:31], v[152:155], v[204:207], v[28:31]
	v_mfma_f32_16x16x32_bf16 v[24:27], v[160:163], v[204:207], v[24:27]
	v_mfma_f32_16x16x32_bf16 v[12:15], v[152:155], v[212:215], v[12:15]
	v_mfma_f32_16x16x32_bf16 v[8:11], v[160:163], v[212:215], v[8:11]
	v_mfma_f32_16x16x32_bf16 v[60:63], v[156:159], v[192:195], v[60:63]
	v_mfma_f32_16x16x32_bf16 v[56:59], v[164:167], v[192:195], v[56:59]
	v_mfma_f32_16x16x32_bf16 v[44:47], v[156:159], v[200:203], v[44:47]
	v_mfma_f32_16x16x32_bf16 v[40:43], v[164:167], v[200:203], v[40:43]
	v_mfma_f32_16x16x32_bf16 v[28:31], v[156:159], v[208:211], v[28:31]
	v_mfma_f32_16x16x32_bf16 v[24:27], v[164:167], v[208:211], v[24:27]
	v_mfma_f32_16x16x32_bf16 v[12:15], v[156:159], v[216:219], v[12:15]
	v_mfma_f32_16x16x32_bf16 v[8:11], v[164:167], v[216:219], v[8:11]
	v_mfma_f32_16x16x32_bf16 v[52:55], v[168:171], v[188:191], v[52:55]
	v_mfma_f32_16x16x32_bf16 v[48:51], v[176:179], v[188:191], v[48:51]
	v_mfma_f32_16x16x32_bf16 v[36:39], v[168:171], v[196:199], v[36:39]
	v_mfma_f32_16x16x32_bf16 v[32:35], v[176:179], v[196:199], v[32:35]
	v_mfma_f32_16x16x32_bf16 v[20:23], v[168:171], v[204:207], v[20:23]
	v_mfma_f32_16x16x32_bf16 v[16:19], v[176:179], v[204:207], v[16:19]
	v_mfma_f32_16x16x32_bf16 v[4:7], v[168:171], v[212:215], v[4:7]
	v_mfma_f32_16x16x32_bf16 v[0:3], v[176:179], v[212:215], v[0:3]
	v_mfma_f32_16x16x32_bf16 v[52:55], v[172:175], v[192:195], v[52:55]
	v_mfma_f32_16x16x32_bf16 v[48:51], v[180:183], v[192:195], v[48:51]
	v_mfma_f32_16x16x32_bf16 v[36:39], v[172:175], v[200:203], v[36:39]
	v_mfma_f32_16x16x32_bf16 v[32:35], v[180:183], v[200:203], v[32:35]
	v_mfma_f32_16x16x32_bf16 v[20:23], v[172:175], v[208:211], v[20:23]
	v_mfma_f32_16x16x32_bf16 v[16:19], v[180:183], v[208:211], v[16:19]
	v_mfma_f32_16x16x32_bf16 v[4:7], v[172:175], v[216:219], v[4:7]
	v_mfma_f32_16x16x32_bf16 v[0:3], v[180:183], v[216:219], v[0:3]
	s_barrier
	s_add_i32 s8, s8, 2
	s_addk_i32 s2, 0x100
	s_addk_i32 s3, 0x100
	v_add_u32_e32 v134, 0x100, v134
	s_cmp_gt_u32 s8, 13
	v_add_u32_e32 v135, 0x100, v135
	s_cbranch_scc0 .LBB0_188
	s_and_b64 vcc, exec, s[18:19]
	s_cbranch_vccz .LBB0_191
	s_barrier

.LBB0_468:
	ds_read_b128 v[148:151], v145
	ds_read_b128 v[152:155], v145 offset:1024
	ds_read_b128 v[156:159], v145 offset:2048
	ds_read_b128 v[160:163], v145 offset:3072
	ds_read_b128 v[164:167], v146
	ds_read_b128 v[168:171], v146 offset:1024
	ds_read_b128 v[172:175], v146 offset:2048
	ds_read_b128 v[176:179], v146 offset:3072
	s_cmp_eq_u32 s44, 12
	s_cselect_b32 s47, s0, s43
	s_cselect_b32 s46, s1, s42
	s_or_b32 s45, s47, 0x80
	v_mov_b32_e32 v135, v134
	ds_read_b128 v[180:183], v147
	ds_read_b128 v[192:195], v147 offset:1024
	ds_read_b128 v[196:199], v147 offset:2048
	ds_read_b128 v[200:203], v147 offset:3072
	ds_read_b128 v[204:207], v147 offset:4096
	ds_read_b128 v[208:211], v147 offset:5120
	ds_read_b128 v[212:215], v147 offset:6144
	ds_read_b128 v[216:219], v147 offset:7168
	s_add_i32 m0, s22, 0xc000
	s_nop 0
	global_load_lds_dwordx4 v135, s[10:11]
	v_mov_b32_e32 v135, v132
	s_add_i32 m0, s22, 0xe000
	s_nop 0
	global_load_lds_dwordx4 v135, s[10:11]
	s_waitcnt vmcnt(8)
	s_waitcnt lgkmcnt(0)
	s_barrier
	s_waitcnt lgkmcnt(0)
	v_mfma_f32_16x16x32_bf16 v[124:127], v[148:151], v[180:183], v[124:127]
	v_mfma_f32_16x16x32_bf16 v[120:123], v[156:159], v[180:183], v[120:123]
	v_mfma_f32_16x16x32_bf16 v[108:111], v[148:151], v[196:199], v[108:111]
	v_mfma_f32_16x16x32_bf16 v[104:107], v[156:159], v[196:199], v[104:107]
	v_mfma_f32_16x16x32_bf16 v[92:95], v[148:151], v[204:207], v[92:95]
	v_mfma_f32_16x16x32_bf16 v[88:91], v[156:159], v[204:207], v[88:91]
	v_mfma_f32_16x16x32_bf16 v[76:79], v[148:151], v[212:215], v[76:79]
	v_mfma_f32_16x16x32_bf16 v[72:75], v[156:159], v[212:215], v[72:75]
	v_mfma_f32_16x16x32_bf16 v[124:127], v[152:155], v[192:195], v[124:127]
	v_mfma_f32_16x16x32_bf16 v[120:123], v[160:163], v[192:195], v[120:123]
	v_mfma_f32_16x16x32_bf16 v[108:111], v[152:155], v[200:203], v[108:111]
	v_mfma_f32_16x16x32_bf16 v[104:107], v[160:163], v[200:203], v[104:107]
	v_mfma_f32_16x16x32_bf16 v[92:95], v[152:155], v[208:211], v[92:95]
	v_mfma_f32_16x16x32_bf16 v[88:91], v[160:163], v[208:211], v[88:91]
	v_mfma_f32_16x16x32_bf16 v[76:79], v[152:155], v[216:219], v[76:79]
	v_mfma_f32_16x16x32_bf16 v[72:75], v[160:163], v[216:219], v[72:75]
	v_mfma_f32_16x16x32_bf16 v[116:119], v[164:167], v[180:183], v[116:119]
	v_mfma_f32_16x16x32_bf16 v[112:115], v[172:175], v[180:183], v[112:115]
	v_mfma_f32_16x16x32_bf16 v[100:103], v[164:167], v[196:199], v[100:103]
	v_mfma_f32_16x16x32_bf16 v[96:99], v[172:175], v[196:199], v[96:99]
	v_mfma_f32_16x16x32_bf16 v[84:87], v[164:167], v[204:207], v[84:87]
	v_mfma_f32_16x16x32_bf16 v[80:83], v[172:175], v[204:207], v[80:83]
	v_mfma_f32_16x16x32_bf16 v[68:71], v[164:167], v[212:215], v[68:71]
	v_mfma_f32_16x16x32_bf16 v[64:67], v[172:175], v[212:215], v[64:67]
	v_mfma_f32_16x16x32_bf16 v[116:119], v[168:171], v[192:195], v[116:119]
	v_mfma_f32_16x16x32_bf16 v[112:115], v[176:179], v[192:195], v[112:115]
	v_mfma_f32_16x16x32_bf16 v[100:103], v[168:171], v[200:203], v[100:103]
	v_mfma_f32_16x16x32_bf16 v[96:99], v[176:179], v[200:203], v[96:99]
	v_mfma_f32_16x16x32_bf16 v[84:87], v[168:171], v[208:211], v[84:87]
	v_mfma_f32_16x16x32_bf16 v[80:83], v[176:179], v[208:211], v[80:83]
	v_mfma_f32_16x16x32_bf16 v[68:71], v[168:171], v[216:219], v[68:71]
	v_mfma_f32_16x16x32_bf16 v[64:67], v[176:179], v[216:219], v[64:67]
	s_barrier
	s_add_i32 s48, s35, s19
	ds_read_b128 v[180:183], v147 offset:16384
	ds_read_b128 v[192:195], v147 offset:17408
	ds_read_b128 v[196:199], v147 offset:18432
	ds_read_b128 v[200:203], v147 offset:19456
	ds_read_b128 v[204:207], v147 offset:20480
	ds_read_b128 v[208:211], v147 offset:21504
	ds_read_b128 v[212:215], v147 offset:22528
	ds_read_b128 v[216:219], v147 offset:23552
	v_add_u32_e32 v135, s46, v137
	s_mov_b32 m0, s48
	s_add_i32 s49, s36, s19
	global_load_lds_dwordx4 v135, s[12:13]
	v_add_u32_e32 v135, s46, v139
	s_add_i32 m0, s48, 0x2000
	s_add_i32 s48, s46, 0x40000
	global_load_lds_dwordx4 v135, s[12:13]
	v_add_u32_e32 v135, s48, v137
	s_mov_b32 m0, s49
	s_nop 0
	global_load_lds_dwordx4 v135, s[12:13]
	v_add_u32_e32 v135, s48, v139
	s_add_i32 m0, s49, 0x2000
	s_nop 0
	global_load_lds_dwordx4 v135, s[12:13]
	v_add_u32_e32 v135, s47, v136
	s_mov_b32 m0, s22
	s_nop 0
	global_load_lds_dwordx4 v135, s[10:11]
	v_add_u32_e32 v135, s47, v138
	s_mov_b32 m0, s23
	s_nop 0
	global_load_lds_dwordx4 v135, s[10:11]
	s_waitcnt vmcnt(8)
	s_waitcnt lgkmcnt(0)
	s_barrier
	s_waitcnt lgkmcnt(0)
	v_mfma_f32_16x16x32_bf16 v[60:63], v[148:151], v[180:183], v[60:63]
	v_mfma_f32_16x16x32_bf16 v[56:59], v[156:159], v[180:183], v[56:59]
	v_mfma_f32_16x16x32_bf16 v[44:47], v[148:151], v[196:199], v[44:47]
	v_mfma_f32_16x16x32_bf16 v[40:43], v[156:159], v[196:199], v[40:43]
	v_mfma_f32_16x16x32_bf16 v[28:31], v[148:151], v[204:207], v[28:31]
	v_mfma_f32_16x16x32_bf16 v[24:27], v[156:159], v[204:207], v[24:27]
	v_mfma_f32_16x16x32_bf16 v[12:15], v[148:151], v[212:215], v[12:15]
	v_mfma_f32_16x16x32_bf16 v[8:11], v[156:159], v[212:215], v[8:11]
	v_mfma_f32_16x16x32_bf16 v[60:63], v[152:155], v[192:195], v[60:63]
	v_mfma_f32_16x16x32_bf16 v[56:59], v[160:163], v[192:195], v[56:59]
	v_mfma_f32_16x16x32_bf16 v[44:47], v[152:155], v[200:203], v[44:47]
	v_mfma_f32_16x16x32_bf16 v[40:43], v[160:163], v[200:203], v[40:43]
	v_mfma_f32_16x16x32_bf16 v[28:31], v[152:155], v[208:211], v[28:31]
	v_mfma_f32_16x16x32_bf16 v[24:27], v[160:163], v[208:211], v[24:27]
	v_mfma_f32_16x16x32_bf16 v[12:15], v[152:155], v[216:219], v[12:15]
	v_mfma_f32_16x16x32_bf16 v[8:11], v[160:163], v[216:219], v[8:11]
	v_mfma_f32_16x16x32_bf16 v[52:55], v[164:167], v[180:183], v[52:55]
	v_mfma_f32_16x16x32_bf16 v[48:51], v[172:175], v[180:183], v[48:51]
	v_mfma_f32_16x16x32_bf16 v[36:39], v[164:167], v[196:199], v[36:39]
	v_mfma_f32_16x16x32_bf16 v[32:35], v[172:175], v[196:199], v[32:35]
	v_mfma_f32_16x16x32_bf16 v[20:23], v[164:167], v[204:207], v[20:23]
	v_mfma_f32_16x16x32_bf16 v[16:19], v[172:175], v[204:207], v[16:19]
	v_mfma_f32_16x16x32_bf16 v[4:7], v[164:167], v[212:215], v[4:7]
	v_mfma_f32_16x16x32_bf16 v[0:3], v[172:175], v[212:215], v[0:3]
	v_mfma_f32_16x16x32_bf16 v[52:55], v[168:171], v[192:195], v[52:55]
	v_mfma_f32_16x16x32_bf16 v[48:51], v[176:179], v[192:195], v[48:51]
	v_mfma_f32_16x16x32_bf16 v[36:39], v[168:171], v[200:203], v[36:39]
	v_mfma_f32_16x16x32_bf16 v[32:35], v[176:179], v[200:203], v[32:35]
	v_mfma_f32_16x16x32_bf16 v[20:23], v[168:171], v[208:211], v[20:23]
	v_mfma_f32_16x16x32_bf16 v[16:19], v[176:179], v[208:211], v[16:19]
	v_mfma_f32_16x16x32_bf16 v[4:7], v[168:171], v[216:219], v[4:7]
	v_mfma_f32_16x16x32_bf16 v[0:3], v[176:179], v[216:219], v[0:3]
	s_barrier
	s_add_i32 s48, 0, 0x18000
	v_add_u32_e32 v135, s48, v141
	s_add_i32 s49, 0, 0x1c000
	ds_read_b128 v[148:151], v135
	ds_read_b128 v[152:155], v135 offset:1024
	ds_read_b128 v[156:159], v135 offset:2048
	ds_read_b128 v[160:163], v135 offset:3072
	v_add_u32_e32 v135, s49, v141
	ds_read_b128 v[164:167], v135
	ds_read_b128 v[168:171], v135 offset:1024
	ds_read_b128 v[172:175], v135 offset:2048
	ds_read_b128 v[176:179], v135 offset:3072
	s_add_i32 s47, s47, 0x40000
	v_add_u32_e32 v135, s47, v136
	s_mov_b32 m0, s24
	ds_read_b128 v[180:183], v147 offset:32768
	ds_read_b128 v[192:195], v147 offset:33792
	ds_read_b128 v[196:199], v147 offset:34816
	ds_read_b128 v[200:203], v147 offset:35840
	ds_read_b128 v[204:207], v147 offset:36864
	ds_read_b128 v[208:211], v147 offset:37888
	ds_read_b128 v[212:215], v147 offset:38912
	ds_read_b128 v[216:219], v147 offset:39936
	s_nop 0
	global_load_lds_dwordx4 v135, s[10:11]
	v_add_u32_e32 v135, s47, v138
	s_mov_b32 m0, s25
	s_nop 0
	global_load_lds_dwordx4 v135, s[10:11]
	s_waitcnt vmcnt(8)
	s_waitcnt lgkmcnt(0)
	s_barrier
	s_waitcnt lgkmcnt(0)
	v_mfma_f32_16x16x32_bf16 v[124:127], v[148:151], v[180:183], v[124:127]
	v_mfma_f32_16x16x32_bf16 v[120:123], v[156:159], v[180:183], v[120:123]
	v_mfma_f32_16x16x32_bf16 v[108:111], v[148:151], v[196:199], v[108:111]
	v_mfma_f32_16x16x32_bf16 v[104:107], v[156:159], v[196:199], v[104:107]
	v_mfma_f32_16x16x32_bf16 v[92:95], v[148:151], v[204:207], v[92:95]
	v_mfma_f32_16x16x32_bf16 v[88:91], v[156:159], v[204:207], v[88:91]
	v_mfma_f32_16x16x32_bf16 v[76:79], v[148:151], v[212:215], v[76:79]
	v_mfma_f32_16x16x32_bf16 v[72:75], v[156:159], v[212:215], v[72:75]
	v_mfma_f32_16x16x32_bf16 v[124:127], v[152:155], v[192:195], v[124:127]
	v_mfma_f32_16x16x32_bf16 v[120:123], v[160:163], v[192:195], v[120:123]
	v_mfma_f32_16x16x32_bf16 v[108:111], v[152:155], v[200:203], v[108:111]
	v_mfma_f32_16x16x32_bf16 v[104:107], v[160:163], v[200:203], v[104:107]
	v_mfma_f32_16x16x32_bf16 v[92:95], v[152:155], v[208:211], v[92:95]
	v_mfma_f32_16x16x32_bf16 v[88:91], v[160:163], v[208:211], v[88:91]
	v_mfma_f32_16x16x32_bf16 v[76:79], v[152:155], v[216:219], v[76:79]
	v_mfma_f32_16x16x32_bf16 v[72:75], v[160:163], v[216:219], v[72:75]
	v_mfma_f32_16x16x32_bf16 v[116:119], v[164:167], v[180:183], v[116:119]
	v_mfma_f32_16x16x32_bf16 v[112:115], v[172:175], v[180:183], v[112:115]
	v_mfma_f32_16x16x32_bf16 v[100:103], v[164:167], v[196:199], v[100:103]
	v_mfma_f32_16x16x32_bf16 v[96:99], v[172:175], v[196:199], v[96:99]
	v_mfma_f32_16x16x32_bf16 v[84:87], v[164:167], v[204:207], v[84:87]
	v_mfma_f32_16x16x32_bf16 v[80:83], v[172:175], v[204:207], v[80:83]
	v_mfma_f32_16x16x32_bf16 v[68:71], v[164:167], v[212:215], v[68:71]
	v_mfma_f32_16x16x32_bf16 v[64:67], v[172:175], v[212:215], v[64:67]
	v_mfma_f32_16x16x32_bf16 v[116:119], v[168:171], v[192:195], v[116:119]
	v_mfma_f32_16x16x32_bf16 v[112:115], v[176:179], v[192:195], v[112:115]
	v_mfma_f32_16x16x32_bf16 v[100:103], v[168:171], v[200:203], v[100:103]
	v_mfma_f32_16x16x32_bf16 v[96:99], v[176:179], v[200:203], v[96:99]
	v_mfma_f32_16x16x32_bf16 v[84:87], v[168:171], v[208:211], v[84:87]
	v_mfma_f32_16x16x32_bf16 v[80:83], v[176:179], v[208:211], v[80:83]
	v_mfma_f32_16x16x32_bf16 v[68:71], v[168:171], v[216:219], v[68:71]
	v_mfma_f32_16x16x32_bf16 v[64:67], v[176:179], v[216:219], v[64:67]
	s_barrier
	s_or_b32 s47, s46, 0x80
	v_add_u32_e32 v135, s47, v137
	s_add_i32 s48, s48, s19
	ds_read_b128 v[180:183], v147 offset:49152
	ds_read_b128 v[192:195], v147 offset:50176
	ds_read_b128 v[196:199], v147 offset:51200
	ds_read_b128 v[200:203], v147 offset:52224
	ds_read_b128 v[204:207], v147 offset:53248
	ds_read_b128 v[208:211], v147 offset:54272
	ds_read_b128 v[212:215], v147 offset:55296
	ds_read_b128 v[216:219], v147 offset:56320
	s_mov_b32 m0, s48
	s_add_i32 s46, s46, 0x40080
	global_load_lds_dwordx4 v135, s[12:13]
	v_add_u32_e32 v135, s47, v139
	s_add_i32 m0, s48, 0x2000
	s_add_i32 s47, s49, s19
	global_load_lds_dwordx4 v135, s[12:13]
	v_add_u32_e32 v135, s46, v137
	s_mov_b32 m0, s47
	s_nop 0
	global_load_lds_dwordx4 v135, s[12:13]
	v_add_u32_e32 v135, s46, v139
	s_add_i32 m0, s47, 0x2000
	s_nop 0
	global_load_lds_dwordx4 v135, s[12:13]
	v_add_u32_e32 v135, s45, v136
	s_mov_b32 m0, s30
	s_nop 0
	global_load_lds_dwordx4 v135, s[10:11]
	v_add_u32_e32 v135, s45, v138
	s_mov_b32 m0, s31
	s_nop 0
	global_load_lds_dwordx4 v135, s[10:11]
	s_waitcnt vmcnt(8)
	s_waitcnt lgkmcnt(0)
	s_barrier
	s_waitcnt lgkmcnt(0)
	v_mfma_f32_16x16x32_bf16 v[60:63], v[148:151], v[180:183], v[60:63]
	v_mfma_f32_16x16x32_bf16 v[56:59], v[156:159], v[180:183], v[56:59]
	v_mfma_f32_16x16x32_bf16 v[44:47], v[148:151], v[196:199], v[44:47]
	v_mfma_f32_16x16x32_bf16 v[40:43], v[156:159], v[196:199], v[40:43]
	v_mfma_f32_16x16x32_bf16 v[28:31], v[148:151], v[204:207], v[28:31]
	v_mfma_f32_16x16x32_bf16 v[24:27], v[156:159], v[204:207], v[24:27]
	v_mfma_f32_16x16x32_bf16 v[12:15], v[148:151], v[212:215], v[12:15]
	v_mfma_f32_16x16x32_bf16 v[8:11], v[156:159], v[212:215], v[8:11]
	v_mfma_f32_16x16x32_bf16 v[60:63], v[152:155], v[192:195], v[60:63]
	v_mfma_f32_16x16x32_bf16 v[56:59], v[160:163], v[192:195], v[56:59]
	v_mfma_f32_16x16x32_bf16 v[44:47], v[152:155], v[200:203], v[44:47]
	v_mfma_f32_16x16x32_bf16 v[40:43], v[160:163], v[200:203], v[40:43]
	v_mfma_f32_16x16x32_bf16 v[28:31], v[152:155], v[208:211], v[28:31]
	v_mfma_f32_16x16x32_bf16 v[24:27], v[160:163], v[208:211], v[24:27]
	v_mfma_f32_16x16x32_bf16 v[12:15], v[152:155], v[216:219], v[12:15]
	v_mfma_f32_16x16x32_bf16 v[8:11], v[160:163], v[216:219], v[8:11]
	v_mfma_f32_16x16x32_bf16 v[52:55], v[164:167], v[180:183], v[52:55]
	v_mfma_f32_16x16x32_bf16 v[48:51], v[172:175], v[180:183], v[48:51]
	v_mfma_f32_16x16x32_bf16 v[36:39], v[164:167], v[196:199], v[36:39]
	v_mfma_f32_16x16x32_bf16 v[32:35], v[172:175], v[196:199], v[32:35]
	v_mfma_f32_16x16x32_bf16 v[20:23], v[164:167], v[204:207], v[20:23]
	v_mfma_f32_16x16x32_bf16 v[16:19], v[172:175], v[204:207], v[16:19]
	v_mfma_f32_16x16x32_bf16 v[4:7], v[164:167], v[212:215], v[4:7]
	v_mfma_f32_16x16x32_bf16 v[0:3], v[172:175], v[212:215], v[0:3]
	v_mfma_f32_16x16x32_bf16 v[52:55], v[168:171], v[192:195], v[52:55]
	v_mfma_f32_16x16x32_bf16 v[48:51], v[176:179], v[192:195], v[48:51]
	v_mfma_f32_16x16x32_bf16 v[36:39], v[168:171], v[200:203], v[36:39]
	v_mfma_f32_16x16x32_bf16 v[32:35], v[176:179], v[200:203], v[32:35]
	v_mfma_f32_16x16x32_bf16 v[20:23], v[168:171], v[208:211], v[20:23]
	v_mfma_f32_16x16x32_bf16 v[16:19], v[176:179], v[208:211], v[16:19]
	v_mfma_f32_16x16x32_bf16 v[4:7], v[168:171], v[216:219], v[4:7]
	v_mfma_f32_16x16x32_bf16 v[0:3], v[176:179], v[216:219], v[0:3]
	s_barrier
	s_add_i32 s44, s44, 2
	s_addk_i32 s42, 0x100
	s_addk_i32 s43, 0x100
	v_add_u32_e32 v132, 0x100, v132
	s_cmp_gt_u32 s44, 13
	v_add_u32_e32 v134, 0x100, v134
	s_cbranch_scc0 .LBB0_468
	s_and_b64 vcc, exec, s[16:17]
	s_cbranch_vccz .LBB0_471
	s_barrier

.LBB0_523:
	ds_read_b128 v[148:151], v145
	ds_read_b128 v[152:155], v145 offset:1024
	ds_read_b128 v[156:159], v145 offset:2048
	ds_read_b128 v[160:163], v145 offset:3072
	ds_read_b128 v[164:167], v146
	ds_read_b128 v[168:171], v146 offset:1024
	ds_read_b128 v[172:175], v146 offset:2048
	ds_read_b128 v[176:179], v146 offset:3072
	s_cmp_eq_u32 s40, 12
	s_cselect_b32 s43, s0, s39
	s_cselect_b32 s42, s1, s38
	s_or_b32 s41, s43, 0x80
	v_mov_b32_e32 v135, v134
	ds_read_b128 v[180:183], v147
	ds_read_b128 v[192:195], v147 offset:1024
	ds_read_b128 v[196:199], v147 offset:2048
	ds_read_b128 v[200:203], v147 offset:3072
	ds_read_b128 v[204:207], v147 offset:4096
	ds_read_b128 v[208:211], v147 offset:5120
	ds_read_b128 v[212:215], v147 offset:6144
	ds_read_b128 v[216:219], v147 offset:7168
	s_add_i32 m0, s18, 0xc000
	s_nop 0
	global_load_lds_dwordx4 v135, s[8:9]
	v_mov_b32_e32 v135, v132
	s_add_i32 m0, s18, 0xe000
	s_nop 0
	global_load_lds_dwordx4 v135, s[8:9]
	s_waitcnt vmcnt(8)
	s_waitcnt lgkmcnt(0)
	s_barrier
	s_waitcnt lgkmcnt(0)
	v_mfma_f32_16x16x32_bf16 v[124:127], v[148:151], v[180:183], v[124:127]
	v_mfma_f32_16x16x32_bf16 v[120:123], v[156:159], v[180:183], v[120:123]
	v_mfma_f32_16x16x32_bf16 v[108:111], v[148:151], v[196:199], v[108:111]
	v_mfma_f32_16x16x32_bf16 v[104:107], v[156:159], v[196:199], v[104:107]
	v_mfma_f32_16x16x32_bf16 v[92:95], v[148:151], v[204:207], v[92:95]
	v_mfma_f32_16x16x32_bf16 v[88:91], v[156:159], v[204:207], v[88:91]
	v_mfma_f32_16x16x32_bf16 v[76:79], v[148:151], v[212:215], v[76:79]
	v_mfma_f32_16x16x32_bf16 v[72:75], v[156:159], v[212:215], v[72:75]
	v_mfma_f32_16x16x32_bf16 v[124:127], v[152:155], v[192:195], v[124:127]
	v_mfma_f32_16x16x32_bf16 v[120:123], v[160:163], v[192:195], v[120:123]
	v_mfma_f32_16x16x32_bf16 v[108:111], v[152:155], v[200:203], v[108:111]
	v_mfma_f32_16x16x32_bf16 v[104:107], v[160:163], v[200:203], v[104:107]
	v_mfma_f32_16x16x32_bf16 v[92:95], v[152:155], v[208:211], v[92:95]
	v_mfma_f32_16x16x32_bf16 v[88:91], v[160:163], v[208:211], v[88:91]
	v_mfma_f32_16x16x32_bf16 v[76:79], v[152:155], v[216:219], v[76:79]
	v_mfma_f32_16x16x32_bf16 v[72:75], v[160:163], v[216:219], v[72:75]
	v_mfma_f32_16x16x32_bf16 v[116:119], v[164:167], v[180:183], v[116:119]
	v_mfma_f32_16x16x32_bf16 v[112:115], v[172:175], v[180:183], v[112:115]
	v_mfma_f32_16x16x32_bf16 v[100:103], v[164:167], v[196:199], v[100:103]
	v_mfma_f32_16x16x32_bf16 v[96:99], v[172:175], v[196:199], v[96:99]
	v_mfma_f32_16x16x32_bf16 v[84:87], v[164:167], v[204:207], v[84:87]
	v_mfma_f32_16x16x32_bf16 v[80:83], v[172:175], v[204:207], v[80:83]
	v_mfma_f32_16x16x32_bf16 v[68:71], v[164:167], v[212:215], v[68:71]
	v_mfma_f32_16x16x32_bf16 v[64:67], v[172:175], v[212:215], v[64:67]
	v_mfma_f32_16x16x32_bf16 v[116:119], v[168:171], v[192:195], v[116:119]
	v_mfma_f32_16x16x32_bf16 v[112:115], v[176:179], v[192:195], v[112:115]
	v_mfma_f32_16x16x32_bf16 v[100:103], v[168:171], v[200:203], v[100:103]
	v_mfma_f32_16x16x32_bf16 v[96:99], v[176:179], v[200:203], v[96:99]
	v_mfma_f32_16x16x32_bf16 v[84:87], v[168:171], v[208:211], v[84:87]
	v_mfma_f32_16x16x32_bf16 v[80:83], v[176:179], v[208:211], v[80:83]
	v_mfma_f32_16x16x32_bf16 v[68:71], v[168:171], v[216:219], v[68:71]
	v_mfma_f32_16x16x32_bf16 v[64:67], v[176:179], v[216:219], v[64:67]
	s_barrier
	s_add_i32 s44, s30, s17
	ds_read_b128 v[180:183], v147 offset:16384
	ds_read_b128 v[192:195], v147 offset:17408
	ds_read_b128 v[196:199], v147 offset:18432
	ds_read_b128 v[200:203], v147 offset:19456
	ds_read_b128 v[204:207], v147 offset:20480
	ds_read_b128 v[208:211], v147 offset:21504
	ds_read_b128 v[212:215], v147 offset:22528
	ds_read_b128 v[216:219], v147 offset:23552
	v_add_u32_e32 v135, s42, v137
	s_mov_b32 m0, s44
	s_add_i32 s45, s31, s17
	global_load_lds_dwordx4 v135, s[10:11]
	v_add_u32_e32 v135, s42, v139
	s_add_i32 m0, s44, 0x2000
	s_add_i32 s44, s42, 0x40000
	global_load_lds_dwordx4 v135, s[10:11]
	v_add_u32_e32 v135, s44, v137
	s_mov_b32 m0, s45
	s_nop 0
	global_load_lds_dwordx4 v135, s[10:11]
	v_add_u32_e32 v135, s44, v139
	s_add_i32 m0, s45, 0x2000
	s_nop 0
	global_load_lds_dwordx4 v135, s[10:11]
	v_add_u32_e32 v135, s43, v136
	s_mov_b32 m0, s18
	s_nop 0
	global_load_lds_dwordx4 v135, s[8:9]
	v_add_u32_e32 v135, s43, v138
	s_mov_b32 m0, s19
	s_nop 0
	global_load_lds_dwordx4 v135, s[8:9]
	s_waitcnt vmcnt(8)
	s_waitcnt lgkmcnt(0)
	s_barrier
	s_waitcnt lgkmcnt(0)
	v_mfma_f32_16x16x32_bf16 v[60:63], v[148:151], v[180:183], v[60:63]
	v_mfma_f32_16x16x32_bf16 v[56:59], v[156:159], v[180:183], v[56:59]
	v_mfma_f32_16x16x32_bf16 v[44:47], v[148:151], v[196:199], v[44:47]
	v_mfma_f32_16x16x32_bf16 v[40:43], v[156:159], v[196:199], v[40:43]
	v_mfma_f32_16x16x32_bf16 v[28:31], v[148:151], v[204:207], v[28:31]
	v_mfma_f32_16x16x32_bf16 v[24:27], v[156:159], v[204:207], v[24:27]
	v_mfma_f32_16x16x32_bf16 v[12:15], v[148:151], v[212:215], v[12:15]
	v_mfma_f32_16x16x32_bf16 v[8:11], v[156:159], v[212:215], v[8:11]
	v_mfma_f32_16x16x32_bf16 v[60:63], v[152:155], v[192:195], v[60:63]
	v_mfma_f32_16x16x32_bf16 v[56:59], v[160:163], v[192:195], v[56:59]
	v_mfma_f32_16x16x32_bf16 v[44:47], v[152:155], v[200:203], v[44:47]
	v_mfma_f32_16x16x32_bf16 v[40:43], v[160:163], v[200:203], v[40:43]
	v_mfma_f32_16x16x32_bf16 v[28:31], v[152:155], v[208:211], v[28:31]
	v_mfma_f32_16x16x32_bf16 v[24:27], v[160:163], v[208:211], v[24:27]
	v_mfma_f32_16x16x32_bf16 v[12:15], v[152:155], v[216:219], v[12:15]
	v_mfma_f32_16x16x32_bf16 v[8:11], v[160:163], v[216:219], v[8:11]
	v_mfma_f32_16x16x32_bf16 v[52:55], v[164:167], v[180:183], v[52:55]
	v_mfma_f32_16x16x32_bf16 v[48:51], v[172:175], v[180:183], v[48:51]
	v_mfma_f32_16x16x32_bf16 v[36:39], v[164:167], v[196:199], v[36:39]
	v_mfma_f32_16x16x32_bf16 v[32:35], v[172:175], v[196:199], v[32:35]
	v_mfma_f32_16x16x32_bf16 v[20:23], v[164:167], v[204:207], v[20:23]
	v_mfma_f32_16x16x32_bf16 v[16:19], v[172:175], v[204:207], v[16:19]
	v_mfma_f32_16x16x32_bf16 v[4:7], v[164:167], v[212:215], v[4:7]
	v_mfma_f32_16x16x32_bf16 v[0:3], v[172:175], v[212:215], v[0:3]
	v_mfma_f32_16x16x32_bf16 v[52:55], v[168:171], v[192:195], v[52:55]
	v_mfma_f32_16x16x32_bf16 v[48:51], v[176:179], v[192:195], v[48:51]
	v_mfma_f32_16x16x32_bf16 v[36:39], v[168:171], v[200:203], v[36:39]
	v_mfma_f32_16x16x32_bf16 v[32:35], v[176:179], v[200:203], v[32:35]
	v_mfma_f32_16x16x32_bf16 v[20:23], v[168:171], v[208:211], v[20:23]
	v_mfma_f32_16x16x32_bf16 v[16:19], v[176:179], v[208:211], v[16:19]
	v_mfma_f32_16x16x32_bf16 v[4:7], v[168:171], v[216:219], v[4:7]
	v_mfma_f32_16x16x32_bf16 v[0:3], v[176:179], v[216:219], v[0:3]
	s_barrier
	s_add_i32 s44, 0, 0x18000
	v_add_u32_e32 v135, s44, v141
	s_add_i32 s45, 0, 0x1c000
	ds_read_b128 v[148:151], v135
	ds_read_b128 v[152:155], v135 offset:1024
	ds_read_b128 v[156:159], v135 offset:2048
	ds_read_b128 v[160:163], v135 offset:3072
	v_add_u32_e32 v135, s45, v141
	ds_read_b128 v[164:167], v135
	ds_read_b128 v[168:171], v135 offset:1024
	ds_read_b128 v[172:175], v135 offset:2048
	ds_read_b128 v[176:179], v135 offset:3072
	s_add_i32 s43, s43, 0x40000
	v_add_u32_e32 v135, s43, v136
	s_mov_b32 m0, s20
	ds_read_b128 v[180:183], v147 offset:32768
	ds_read_b128 v[192:195], v147 offset:33792
	ds_read_b128 v[196:199], v147 offset:34816
	ds_read_b128 v[200:203], v147 offset:35840
	ds_read_b128 v[204:207], v147 offset:36864
	ds_read_b128 v[208:211], v147 offset:37888
	ds_read_b128 v[212:215], v147 offset:38912
	ds_read_b128 v[216:219], v147 offset:39936
	s_nop 0
	global_load_lds_dwordx4 v135, s[8:9]
	v_add_u32_e32 v135, s43, v138
	s_mov_b32 m0, s21
	s_nop 0
	global_load_lds_dwordx4 v135, s[8:9]
	s_waitcnt vmcnt(8)
	s_waitcnt lgkmcnt(0)
	s_barrier
	s_waitcnt lgkmcnt(0)
	v_mfma_f32_16x16x32_bf16 v[124:127], v[148:151], v[180:183], v[124:127]
	v_mfma_f32_16x16x32_bf16 v[120:123], v[156:159], v[180:183], v[120:123]
	v_mfma_f32_16x16x32_bf16 v[108:111], v[148:151], v[196:199], v[108:111]
	v_mfma_f32_16x16x32_bf16 v[104:107], v[156:159], v[196:199], v[104:107]
	v_mfma_f32_16x16x32_bf16 v[92:95], v[148:151], v[204:207], v[92:95]
	v_mfma_f32_16x16x32_bf16 v[88:91], v[156:159], v[204:207], v[88:91]
	v_mfma_f32_16x16x32_bf16 v[76:79], v[148:151], v[212:215], v[76:79]
	v_mfma_f32_16x16x32_bf16 v[72:75], v[156:159], v[212:215], v[72:75]
	v_mfma_f32_16x16x32_bf16 v[124:127], v[152:155], v[192:195], v[124:127]
	v_mfma_f32_16x16x32_bf16 v[120:123], v[160:163], v[192:195], v[120:123]
	v_mfma_f32_16x16x32_bf16 v[108:111], v[152:155], v[200:203], v[108:111]
	v_mfma_f32_16x16x32_bf16 v[104:107], v[160:163], v[200:203], v[104:107]
	v_mfma_f32_16x16x32_bf16 v[92:95], v[152:155], v[208:211], v[92:95]
	v_mfma_f32_16x16x32_bf16 v[88:91], v[160:163], v[208:211], v[88:91]
	v_mfma_f32_16x16x32_bf16 v[76:79], v[152:155], v[216:219], v[76:79]
	v_mfma_f32_16x16x32_bf16 v[72:75], v[160:163], v[216:219], v[72:75]
	v_mfma_f32_16x16x32_bf16 v[116:119], v[164:167], v[180:183], v[116:119]
	v_mfma_f32_16x16x32_bf16 v[112:115], v[172:175], v[180:183], v[112:115]
	v_mfma_f32_16x16x32_bf16 v[100:103], v[164:167], v[196:199], v[100:103]
	v_mfma_f32_16x16x32_bf16 v[96:99], v[172:175], v[196:199], v[96:99]
	v_mfma_f32_16x16x32_bf16 v[84:87], v[164:167], v[204:207], v[84:87]
	v_mfma_f32_16x16x32_bf16 v[80:83], v[172:175], v[204:207], v[80:83]
	v_mfma_f32_16x16x32_bf16 v[68:71], v[164:167], v[212:215], v[68:71]
	v_mfma_f32_16x16x32_bf16 v[64:67], v[172:175], v[212:215], v[64:67]
	v_mfma_f32_16x16x32_bf16 v[116:119], v[168:171], v[192:195], v[116:119]
	v_mfma_f32_16x16x32_bf16 v[112:115], v[176:179], v[192:195], v[112:115]
	v_mfma_f32_16x16x32_bf16 v[100:103], v[168:171], v[200:203], v[100:103]
	v_mfma_f32_16x16x32_bf16 v[96:99], v[176:179], v[200:203], v[96:99]
	v_mfma_f32_16x16x32_bf16 v[84:87], v[168:171], v[208:211], v[84:87]
	v_mfma_f32_16x16x32_bf16 v[80:83], v[176:179], v[208:211], v[80:83]
	v_mfma_f32_16x16x32_bf16 v[68:71], v[168:171], v[216:219], v[68:71]
	v_mfma_f32_16x16x32_bf16 v[64:67], v[176:179], v[216:219], v[64:67]
	s_barrier
	s_or_b32 s43, s42, 0x80
	v_add_u32_e32 v135, s43, v137
	s_add_i32 s44, s44, s17
	ds_read_b128 v[180:183], v147 offset:49152
	ds_read_b128 v[192:195], v147 offset:50176
	ds_read_b128 v[196:199], v147 offset:51200
	ds_read_b128 v[200:203], v147 offset:52224
	ds_read_b128 v[204:207], v147 offset:53248
	ds_read_b128 v[208:211], v147 offset:54272
	ds_read_b128 v[212:215], v147 offset:55296
	ds_read_b128 v[216:219], v147 offset:56320
	s_mov_b32 m0, s44
	s_add_i32 s42, s42, 0x40080
	global_load_lds_dwordx4 v135, s[10:11]
	v_add_u32_e32 v135, s43, v139
	s_add_i32 m0, s44, 0x2000
	s_add_i32 s43, s45, s17
	global_load_lds_dwordx4 v135, s[10:11]
	v_add_u32_e32 v135, s42, v137
	s_mov_b32 m0, s43
	s_nop 0
	global_load_lds_dwordx4 v135, s[10:11]
	v_add_u32_e32 v135, s42, v139
	s_add_i32 m0, s43, 0x2000
	s_nop 0
	global_load_lds_dwordx4 v135, s[10:11]
	v_add_u32_e32 v135, s41, v136
	s_mov_b32 m0, s26
	s_nop 0
	global_load_lds_dwordx4 v135, s[8:9]
	v_add_u32_e32 v135, s41, v138
	s_mov_b32 m0, s27
	s_nop 0
	global_load_lds_dwordx4 v135, s[8:9]
	s_waitcnt vmcnt(8)
	s_waitcnt lgkmcnt(0)
	s_barrier
	s_waitcnt lgkmcnt(0)
	v_mfma_f32_16x16x32_bf16 v[60:63], v[148:151], v[180:183], v[60:63]
	v_mfma_f32_16x16x32_bf16 v[56:59], v[156:159], v[180:183], v[56:59]
	v_mfma_f32_16x16x32_bf16 v[44:47], v[148:151], v[196:199], v[44:47]
	v_mfma_f32_16x16x32_bf16 v[40:43], v[156:159], v[196:199], v[40:43]
	v_mfma_f32_16x16x32_bf16 v[28:31], v[148:151], v[204:207], v[28:31]
	v_mfma_f32_16x16x32_bf16 v[24:27], v[156:159], v[204:207], v[24:27]
	v_mfma_f32_16x16x32_bf16 v[12:15], v[148:151], v[212:215], v[12:15]
	v_mfma_f32_16x16x32_bf16 v[8:11], v[156:159], v[212:215], v[8:11]
	v_mfma_f32_16x16x32_bf16 v[60:63], v[152:155], v[192:195], v[60:63]
	v_mfma_f32_16x16x32_bf16 v[56:59], v[160:163], v[192:195], v[56:59]
	v_mfma_f32_16x16x32_bf16 v[44:47], v[152:155], v[200:203], v[44:47]
	v_mfma_f32_16x16x32_bf16 v[40:43], v[160:163], v[200:203], v[40:43]
	v_mfma_f32_16x16x32_bf16 v[28:31], v[152:155], v[208:211], v[28:31]
	v_mfma_f32_16x16x32_bf16 v[24:27], v[160:163], v[208:211], v[24:27]
	v_mfma_f32_16x16x32_bf16 v[12:15], v[152:155], v[216:219], v[12:15]
	v_mfma_f32_16x16x32_bf16 v[8:11], v[160:163], v[216:219], v[8:11]
	v_mfma_f32_16x16x32_bf16 v[52:55], v[164:167], v[180:183], v[52:55]
	v_mfma_f32_16x16x32_bf16 v[48:51], v[172:175], v[180:183], v[48:51]
	v_mfma_f32_16x16x32_bf16 v[36:39], v[164:167], v[196:199], v[36:39]
	v_mfma_f32_16x16x32_bf16 v[32:35], v[172:175], v[196:199], v[32:35]
	v_mfma_f32_16x16x32_bf16 v[20:23], v[164:167], v[204:207], v[20:23]
	v_mfma_f32_16x16x32_bf16 v[16:19], v[172:175], v[204:207], v[16:19]
	v_mfma_f32_16x16x32_bf16 v[4:7], v[164:167], v[212:215], v[4:7]
	v_mfma_f32_16x16x32_bf16 v[0:3], v[172:175], v[212:215], v[0:3]
	v_mfma_f32_16x16x32_bf16 v[52:55], v[168:171], v[192:195], v[52:55]
	v_mfma_f32_16x16x32_bf16 v[48:51], v[176:179], v[192:195], v[48:51]
	v_mfma_f32_16x16x32_bf16 v[36:39], v[168:171], v[200:203], v[36:39]
	v_mfma_f32_16x16x32_bf16 v[32:35], v[176:179], v[200:203], v[32:35]
	v_mfma_f32_16x16x32_bf16 v[20:23], v[168:171], v[208:211], v[20:23]
	v_mfma_f32_16x16x32_bf16 v[16:19], v[176:179], v[208:211], v[16:19]
	v_mfma_f32_16x16x32_bf16 v[4:7], v[168:171], v[216:219], v[4:7]
	v_mfma_f32_16x16x32_bf16 v[0:3], v[176:179], v[216:219], v[0:3]
	s_barrier
	s_add_i32 s40, s40, 2
	s_addk_i32 s38, 0x100
	s_addk_i32 s39, 0x100
	v_add_u32_e32 v132, 0x100, v132
	s_cmp_gt_u32 s40, 13
	v_add_u32_e32 v134, 0x100, v134
	s_cbranch_scc0 .LBB0_523
	s_and_b64 vcc, exec, s[14:15]
	s_cbranch_vccz .LBB0_526
	s_barrier

.LBB0_598:
	ds_read_b128 v[0:3], v195
	ds_read_b128 v[4:7], v195 offset:1024
	ds_read_b128 v[8:11], v195 offset:2048
	ds_read_b128 v[12:15], v195 offset:3072
	ds_read_b128 v[16:19], v196
	ds_read_b128 v[20:23], v196 offset:1024
	ds_read_b128 v[24:27], v196 offset:2048
	ds_read_b128 v[28:31], v196 offset:3072
	s_mul_i32 s37, s36, 0x2a0000
	s_mul_i32 s38, s35, 0xa0000
	s_add_i32 s1, s44, 0x150880
	s_or_b32 s45, s44, 0x900
	s_or_b32 s51, s44, 0x980
	s_or_b32 s40, s43, 0x100
	v_add_u32_e32 v64, s1, v180
	s_add_i32 s0, s23, 0xc000
	ds_read_b128 v[32:35], v191
	ds_read_b128 v[36:39], v191 offset:1024
	ds_read_b128 v[40:43], v191 offset:2048
	ds_read_b128 v[44:47], v191 offset:3072
	ds_read_b128 v[48:51], v191 offset:4096
	ds_read_b128 v[52:55], v191 offset:5120
	ds_read_b128 v[56:59], v191 offset:6144
	ds_read_b128 v[60:63], v191 offset:7168
	s_mov_b32 m0, s0
	s_nop 0
	global_load_lds_dwordx4 v64, s[12:13]
	v_add_u32_e32 v64, s1, v182
	s_add_i32 s1, s23, 0xe000
	s_mov_b32 m0, s1
	s_nop 0
	global_load_lds_dwordx4 v64, s[12:13]
	s_waitcnt vmcnt(8)
	s_waitcnt lgkmcnt(0)
	s_barrier
	s_waitcnt lgkmcnt(0)
	v_mfma_f32_16x16x32_bf16 v[64:67], v[0:3], v[32:35], 0
	v_mfma_f32_16x16x32_bf16 v[68:71], v[8:11], v[32:35], 0
	v_mfma_f32_16x16x32_bf16 v[72:75], v[0:3], v[40:43], 0
	v_mfma_f32_16x16x32_bf16 v[76:79], v[8:11], v[40:43], 0
	v_mfma_f32_16x16x32_bf16 v[80:83], v[0:3], v[48:51], 0
	v_mfma_f32_16x16x32_bf16 v[84:87], v[8:11], v[48:51], 0
	v_mfma_f32_16x16x32_bf16 v[88:91], v[0:3], v[56:59], 0
	v_mfma_f32_16x16x32_bf16 v[92:95], v[8:11], v[56:59], 0
	v_mfma_f32_16x16x32_bf16 v[64:67], v[4:7], v[36:39], v[64:67]
	v_mfma_f32_16x16x32_bf16 v[68:71], v[12:15], v[36:39], v[68:71]
	v_mfma_f32_16x16x32_bf16 v[72:75], v[4:7], v[44:47], v[72:75]
	v_mfma_f32_16x16x32_bf16 v[76:79], v[12:15], v[44:47], v[76:79]
	v_mfma_f32_16x16x32_bf16 v[80:83], v[4:7], v[52:55], v[80:83]
	v_mfma_f32_16x16x32_bf16 v[84:87], v[12:15], v[52:55], v[84:87]
	v_mfma_f32_16x16x32_bf16 v[88:91], v[4:7], v[60:63], v[88:91]
	v_mfma_f32_16x16x32_bf16 v[92:95], v[12:15], v[60:63], v[92:95]
	v_mfma_f32_16x16x32_bf16 v[96:99], v[16:19], v[32:35], 0
	v_mfma_f32_16x16x32_bf16 v[32:35], v[24:27], v[32:35], 0
	v_mfma_f32_16x16x32_bf16 v[96:99], v[20:23], v[36:39], v[96:99]
	v_mfma_f32_16x16x32_bf16 v[32:35], v[28:31], v[36:39], v[32:35]
	v_mfma_f32_16x16x32_bf16 v[36:39], v[16:19], v[40:43], 0
	v_mfma_f32_16x16x32_bf16 v[40:43], v[24:27], v[40:43], 0
	v_mfma_f32_16x16x32_bf16 v[36:39], v[20:23], v[44:47], v[36:39]
	v_mfma_f32_16x16x32_bf16 v[40:43], v[28:31], v[44:47], v[40:43]
	v_mfma_f32_16x16x32_bf16 v[44:47], v[16:19], v[48:51], 0
	v_mfma_f32_16x16x32_bf16 v[48:51], v[24:27], v[48:51], 0
	v_mfma_f32_16x16x32_bf16 v[44:47], v[20:23], v[52:55], v[44:47]
	v_mfma_f32_16x16x32_bf16 v[48:51], v[28:31], v[52:55], v[48:51]
	v_mfma_f32_16x16x32_bf16 v[52:55], v[16:19], v[56:59], 0
	v_mfma_f32_16x16x32_bf16 v[56:59], v[24:27], v[56:59], 0
	v_mfma_f32_16x16x32_bf16 v[52:55], v[20:23], v[60:63], v[52:55]
	v_mfma_f32_16x16x32_bf16 v[56:59], v[28:31], v[60:63], v[56:59]
	s_barrier
	s_add_i32 s39, s33, s3
	ds_read_b128 v[60:63], v191 offset:16384
	ds_read_b128 v[100:103], v191 offset:17408
	ds_read_b128 v[104:107], v191 offset:18432
	ds_read_b128 v[108:111], v191 offset:19456
	ds_read_b128 v[112:115], v191 offset:20480
	ds_read_b128 v[116:119], v191 offset:21504
	ds_read_b128 v[120:123], v191 offset:22528
	ds_read_b128 v[124:127], v191 offset:23552
	v_add_u32_e32 v128, s40, v181
	s_mov_b32 m0, s39
	s_add_i32 s42, s43, 0x50100
	global_load_lds_dwordx4 v128, s[14:15]
	v_add_u32_e32 v128, s40, v183
	s_add_i32 s40, s39, 0x2000
	s_mov_b32 m0, s40
	s_add_i32 s41, s34, s3
	global_load_lds_dwordx4 v128, s[14:15]
	v_add_u32_e32 v128, s42, v181
	s_mov_b32 m0, s41
	s_nop 0
	global_load_lds_dwordx4 v128, s[14:15]
	v_add_u32_e32 v128, s42, v183
	s_add_i32 s42, s41, 0x2000
	s_mov_b32 m0, s42
	s_nop 0
	global_load_lds_dwordx4 v128, s[14:15]
	v_add_u32_e32 v128, s45, v180
	s_mov_b32 m0, s23
	s_nop 0
	global_load_lds_dwordx4 v128, s[12:13]
	v_add_u32_e32 v128, s45, v182
	s_mov_b32 m0, s24
	s_nop 0
	global_load_lds_dwordx4 v128, s[12:13]
	s_waitcnt vmcnt(8)
	s_waitcnt lgkmcnt(0)
	s_barrier
	s_waitcnt lgkmcnt(0)
	v_mfma_f32_16x16x32_bf16 v[128:131], v[0:3], v[60:63], 0
	v_mfma_f32_16x16x32_bf16 v[136:139], v[0:3], v[104:107], 0
	v_mfma_f32_16x16x32_bf16 v[144:147], v[0:3], v[112:115], 0
	v_mfma_f32_16x16x32_bf16 v[0:3], v[0:3], v[120:123], 0
	v_mfma_f32_16x16x32_bf16 v[128:131], v[4:7], v[100:103], v[128:131]
	v_mfma_f32_16x16x32_bf16 v[136:139], v[4:7], v[108:111], v[136:139]
	v_mfma_f32_16x16x32_bf16 v[144:147], v[4:7], v[116:119], v[144:147]
	v_mfma_f32_16x16x32_bf16 v[0:3], v[4:7], v[124:127], v[0:3]
	v_mfma_f32_16x16x32_bf16 v[4:7], v[8:11], v[120:123], 0
	v_mfma_f32_16x16x32_bf16 v[132:135], v[8:11], v[60:63], 0
	v_mfma_f32_16x16x32_bf16 v[140:143], v[8:11], v[104:107], 0
	v_mfma_f32_16x16x32_bf16 v[148:151], v[8:11], v[112:115], 0
	v_mfma_f32_16x16x32_bf16 v[4:7], v[12:15], v[124:127], v[4:7]
	v_mfma_f32_16x16x32_bf16 v[132:135], v[12:15], v[100:103], v[132:135]
	v_mfma_f32_16x16x32_bf16 v[140:143], v[12:15], v[108:111], v[140:143]
	v_mfma_f32_16x16x32_bf16 v[148:151], v[12:15], v[116:119], v[148:151]
	v_mfma_f32_16x16x32_bf16 v[8:11], v[16:19], v[60:63], 0
	v_mfma_f32_16x16x32_bf16 v[12:15], v[24:27], v[60:63], 0
	v_mfma_f32_16x16x32_bf16 v[8:11], v[20:23], v[100:103], v[8:11]
	v_mfma_f32_16x16x32_bf16 v[12:15], v[28:31], v[100:103], v[12:15]
	v_mfma_f32_16x16x32_bf16 v[60:63], v[16:19], v[104:107], 0
	v_mfma_f32_16x16x32_bf16 v[100:103], v[24:27], v[104:107], 0
	v_mfma_f32_16x16x32_bf16 v[104:107], v[16:19], v[112:115], 0
	v_mfma_f32_16x16x32_bf16 v[16:19], v[16:19], v[120:123], 0
	v_mfma_f32_16x16x32_bf16 v[60:63], v[20:23], v[108:111], v[60:63]
	v_mfma_f32_16x16x32_bf16 v[100:103], v[28:31], v[108:111], v[100:103]
	v_mfma_f32_16x16x32_bf16 v[104:107], v[20:23], v[116:119], v[104:107]
	v_mfma_f32_16x16x32_bf16 v[108:111], v[24:27], v[112:115], 0
	v_mfma_f32_16x16x32_bf16 v[16:19], v[20:23], v[124:127], v[16:19]
	v_mfma_f32_16x16x32_bf16 v[20:23], v[24:27], v[120:123], 0
	v_mfma_f32_16x16x32_bf16 v[108:111], v[28:31], v[116:119], v[108:111]
	v_mfma_f32_16x16x32_bf16 v[20:23], v[28:31], v[124:127], v[20:23]
	s_barrier
	s_add_i32 s45, 0, 0x18000
	s_add_i32 s47, 0, 0x1c000
	v_add_u32_e32 v167, s45, v185
	v_add_u32_e32 v169, s47, v185
	ds_read_b128 v[24:27], v167
	ds_read_b128 v[28:31], v167 offset:1024
	ds_read_b128 v[112:115], v167 offset:2048
	ds_read_b128 v[116:119], v167 offset:3072
	ds_read_b128 v[120:123], v169
	ds_read_b128 v[124:127], v169 offset:1024
	ds_read_b128 v[152:155], v169 offset:2048
	ds_read_b128 v[156:159], v169 offset:3072
	s_add_i32 s46, s44, 0x150900
	v_add_u32_e32 v160, s46, v180
	s_mov_b32 m0, s25
	ds_read_b128 v[170:173], v191 offset:32768
	ds_read_b128 v[174:177], v191 offset:33792
	ds_read_b128 v[198:201], v191 offset:34816
	ds_read_b128 v[202:205], v191 offset:35840
	ds_read_b128 v[206:209], v191 offset:36864
	ds_read_b128 v[210:213], v191 offset:37888
	ds_read_b128 v[214:217], v191 offset:38912
	ds_read_b128 v[218:221], v191 offset:39936
	s_nop 0
	global_load_lds_dwordx4 v160, s[12:13]
	v_add_u32_e32 v160, s46, v182
	s_mov_b32 m0, s26
	s_nop 0
	global_load_lds_dwordx4 v160, s[12:13]
	s_waitcnt vmcnt(8)
	s_waitcnt lgkmcnt(0)
	s_barrier
	s_waitcnt lgkmcnt(0)
	v_mfma_f32_16x16x32_bf16 v[64:67], v[24:27], v[170:173], v[64:67]
	v_mfma_f32_16x16x32_bf16 v[68:71], v[112:115], v[170:173], v[68:71]
	v_mfma_f32_16x16x32_bf16 v[72:75], v[24:27], v[198:201], v[72:75]
	v_mfma_f32_16x16x32_bf16 v[76:79], v[112:115], v[198:201], v[76:79]
	v_mfma_f32_16x16x32_bf16 v[80:83], v[24:27], v[206:209], v[80:83]
	v_mfma_f32_16x16x32_bf16 v[84:87], v[112:115], v[206:209], v[84:87]
	v_mfma_f32_16x16x32_bf16 v[88:91], v[24:27], v[214:217], v[88:91]
	v_mfma_f32_16x16x32_bf16 v[92:95], v[112:115], v[214:217], v[92:95]
	v_mfma_f32_16x16x32_bf16 v[64:67], v[28:31], v[174:177], v[64:67]
	v_mfma_f32_16x16x32_bf16 v[68:71], v[116:119], v[174:177], v[68:71]
	v_mfma_f32_16x16x32_bf16 v[72:75], v[28:31], v[202:205], v[72:75]
	v_mfma_f32_16x16x32_bf16 v[76:79], v[116:119], v[202:205], v[76:79]
	v_mfma_f32_16x16x32_bf16 v[80:83], v[28:31], v[210:213], v[80:83]
	v_mfma_f32_16x16x32_bf16 v[84:87], v[116:119], v[210:213], v[84:87]
	v_mfma_f32_16x16x32_bf16 v[88:91], v[28:31], v[218:221], v[88:91]
	v_mfma_f32_16x16x32_bf16 v[92:95], v[116:119], v[218:221], v[92:95]
	v_mfma_f32_16x16x32_bf16 v[96:99], v[120:123], v[170:173], v[96:99]
	v_mfma_f32_16x16x32_bf16 v[32:35], v[152:155], v[170:173], v[32:35]
	v_mfma_f32_16x16x32_bf16 v[40:43], v[152:155], v[198:201], v[40:43]
	v_mfma_f32_16x16x32_bf16 v[44:47], v[120:123], v[206:209], v[44:47]
	v_mfma_f32_16x16x32_bf16 v[48:51], v[152:155], v[206:209], v[48:51]
	v_mfma_f32_16x16x32_bf16 v[52:55], v[120:123], v[214:217], v[52:55]
	v_mfma_f32_16x16x32_bf16 v[56:59], v[152:155], v[214:217], v[56:59]
	v_mfma_f32_16x16x32_bf16 v[96:99], v[124:127], v[174:177], v[96:99]
	v_mfma_f32_16x16x32_bf16 v[32:35], v[156:159], v[174:177], v[32:35]
	v_mfma_f32_16x16x32_bf16 v[36:39], v[120:123], v[198:201], v[36:39]
	v_mfma_f32_16x16x32_bf16 v[40:43], v[156:159], v[202:205], v[40:43]
	v_mfma_f32_16x16x32_bf16 v[44:47], v[124:127], v[210:213], v[44:47]
	v_mfma_f32_16x16x32_bf16 v[48:51], v[156:159], v[210:213], v[48:51]
	v_mfma_f32_16x16x32_bf16 v[52:55], v[124:127], v[218:221], v[52:55]
	v_mfma_f32_16x16x32_bf16 v[56:59], v[156:159], v[218:221], v[56:59]
	v_mfma_f32_16x16x32_bf16 v[36:39], v[124:127], v[202:205], v[36:39]
	s_barrier
	s_or_b32 s46, s43, 0x180
	v_add_u32_e32 v160, s46, v181
	s_add_i32 s45, s45, s3
	ds_read_b128 v[170:173], v191 offset:49152
	ds_read_b128 v[174:177], v191 offset:50176
	ds_read_b128 v[198:201], v191 offset:51200
	ds_read_b128 v[202:205], v191 offset:52224
	ds_read_b128 v[206:209], v191 offset:53248
	ds_read_b128 v[210:213], v191 offset:54272
	ds_read_b128 v[214:217], v191 offset:55296
	ds_read_b128 v[218:221], v191 offset:56320
	s_mov_b32 m0, s45
	s_add_i32 s48, s43, 0x50180
	global_load_lds_dwordx4 v160, s[14:15]
	v_add_u32_e32 v160, s46, v183
	s_add_i32 s46, s45, 0x2000
	s_mov_b32 m0, s46
	s_add_i32 s47, s47, s3
	global_load_lds_dwordx4 v160, s[14:15]
	v_add_u32_e32 v160, s48, v181
	s_mov_b32 m0, s47
	s_nop 0
	global_load_lds_dwordx4 v160, s[14:15]
	v_add_u32_e32 v160, s48, v183
	s_add_i32 s48, s47, 0x2000
	s_mov_b32 m0, s48
	s_nop 0
	global_load_lds_dwordx4 v160, s[14:15]
	v_add_u32_e32 v160, s51, v180
	s_mov_b32 m0, s28
	s_nop 0
	global_load_lds_dwordx4 v160, s[12:13]
	v_add_u32_e32 v160, s51, v182
	s_mov_b32 m0, s29
	s_nop 0
	global_load_lds_dwordx4 v160, s[12:13]
	s_waitcnt vmcnt(8)
	s_waitcnt lgkmcnt(0)
	s_barrier
	s_waitcnt lgkmcnt(0)
	v_mfma_f32_16x16x32_bf16 v[128:131], v[24:27], v[170:173], v[128:131]
	v_mfma_f32_16x16x32_bf16 v[136:139], v[24:27], v[198:201], v[136:139]
	v_mfma_f32_16x16x32_bf16 v[0:3], v[24:27], v[214:217], v[0:3]
	v_mfma_f32_16x16x32_bf16 v[4:7], v[112:115], v[214:217], v[4:7]
	v_mfma_f32_16x16x32_bf16 v[128:131], v[28:31], v[174:177], v[128:131]
	v_mfma_f32_16x16x32_bf16 v[132:135], v[112:115], v[170:173], v[132:135]
	v_mfma_f32_16x16x32_bf16 v[136:139], v[28:31], v[202:205], v[136:139]
	v_mfma_f32_16x16x32_bf16 v[140:143], v[112:115], v[198:201], v[140:143]
	v_mfma_f32_16x16x32_bf16 v[144:147], v[24:27], v[206:209], v[144:147]
	v_mfma_f32_16x16x32_bf16 v[148:151], v[112:115], v[206:209], v[148:151]
	v_mfma_f32_16x16x32_bf16 v[0:3], v[28:31], v[218:221], v[0:3]
	v_mfma_f32_16x16x32_bf16 v[4:7], v[116:119], v[218:221], v[4:7]
	v_mfma_f32_16x16x32_bf16 v[132:135], v[116:119], v[174:177], v[132:135]
	v_mfma_f32_16x16x32_bf16 v[140:143], v[116:119], v[202:205], v[140:143]
	v_mfma_f32_16x16x32_bf16 v[144:147], v[28:31], v[210:213], v[144:147]
	v_mfma_f32_16x16x32_bf16 v[148:151], v[116:119], v[210:213], v[148:151]
	v_mfma_f32_16x16x32_bf16 v[8:11], v[120:123], v[170:173], v[8:11]
	v_mfma_f32_16x16x32_bf16 v[12:15], v[152:155], v[170:173], v[12:15]
	v_mfma_f32_16x16x32_bf16 v[24:27], v[120:123], v[198:201], v[60:63]
	v_mfma_f32_16x16x32_bf16 v[28:31], v[152:155], v[198:201], v[100:103]
	v_mfma_f32_16x16x32_bf16 v[60:63], v[120:123], v[206:209], v[104:107]
	v_mfma_f32_16x16x32_bf16 v[100:103], v[152:155], v[206:209], v[108:111]
	v_mfma_f32_16x16x32_bf16 v[16:19], v[120:123], v[214:217], v[16:19]
	v_mfma_f32_16x16x32_bf16 v[20:23], v[152:155], v[214:217], v[20:23]
	v_mfma_f32_16x16x32_bf16 v[8:11], v[124:127], v[174:177], v[8:11]
	v_mfma_f32_16x16x32_bf16 v[12:15], v[156:159], v[174:177], v[12:15]
	v_mfma_f32_16x16x32_bf16 v[24:27], v[124:127], v[202:205], v[24:27]
	v_mfma_f32_16x16x32_bf16 v[28:31], v[156:159], v[202:205], v[28:31]
	v_mfma_f32_16x16x32_bf16 v[60:63], v[124:127], v[210:213], v[60:63]
	v_mfma_f32_16x16x32_bf16 v[100:103], v[156:159], v[210:213], v[100:103]
	v_mfma_f32_16x16x32_bf16 v[16:19], v[124:127], v[218:221], v[16:19]
	v_mfma_f32_16x16x32_bf16 v[20:23], v[156:159], v[218:221], v[20:23]
	s_barrier
	ds_read_b128 v[104:107], v195
	ds_read_b128 v[108:111], v195 offset:1024
	ds_read_b128 v[112:115], v195 offset:2048
	ds_read_b128 v[116:119], v195 offset:3072
	ds_read_b128 v[120:123], v196
	ds_read_b128 v[124:127], v196 offset:1024
	ds_read_b128 v[152:155], v196 offset:2048
	ds_read_b128 v[156:159], v196 offset:3072
	s_or_b32 s51, s44, 0x80
	s_or_b32 s52, s43, 0x200
	s_add_i32 s53, s44, 0x150980
	v_add_u32_e32 v160, s53, v180
	s_mov_b32 m0, s0
	ds_read_b128 v[170:173], v191
	ds_read_b128 v[174:177], v191 offset:1024
	ds_read_b128 v[198:201], v191 offset:2048
	ds_read_b128 v[202:205], v191 offset:3072
	ds_read_b128 v[206:209], v191 offset:4096
	ds_read_b128 v[210:213], v191 offset:5120
	ds_read_b128 v[214:217], v191 offset:6144
	ds_read_b128 v[218:221], v191 offset:7168
	s_nop 0
	global_load_lds_dwordx4 v160, s[12:13]
	v_add_u32_e32 v160, s53, v182
	s_mov_b32 m0, s1
	s_nop 0
	global_load_lds_dwordx4 v160, s[12:13]
	s_waitcnt vmcnt(8)
	s_waitcnt lgkmcnt(0)
	s_barrier
	s_waitcnt lgkmcnt(0)
	v_mfma_f32_16x16x32_bf16 v[64:67], v[104:107], v[170:173], v[64:67]
	v_mfma_f32_16x16x32_bf16 v[68:71], v[112:115], v[170:173], v[68:71]
	v_mfma_f32_16x16x32_bf16 v[72:75], v[104:107], v[198:201], v[72:75]
	v_mfma_f32_16x16x32_bf16 v[76:79], v[112:115], v[198:201], v[76:79]
	v_mfma_f32_16x16x32_bf16 v[80:83], v[104:107], v[206:209], v[80:83]
	v_mfma_f32_16x16x32_bf16 v[84:87], v[112:115], v[206:209], v[84:87]
	v_mfma_f32_16x16x32_bf16 v[88:91], v[104:107], v[214:217], v[88:91]
	v_mfma_f32_16x16x32_bf16 v[92:95], v[112:115], v[214:217], v[92:95]
	v_mfma_f32_16x16x32_bf16 v[64:67], v[108:111], v[174:177], v[64:67]
	v_mfma_f32_16x16x32_bf16 v[68:71], v[116:119], v[174:177], v[68:71]
	v_mfma_f32_16x16x32_bf16 v[72:75], v[108:111], v[202:205], v[72:75]
	v_mfma_f32_16x16x32_bf16 v[76:79], v[116:119], v[202:205], v[76:79]
	v_mfma_f32_16x16x32_bf16 v[80:83], v[108:111], v[210:213], v[80:83]
	v_mfma_f32_16x16x32_bf16 v[84:87], v[116:119], v[210:213], v[84:87]
	v_mfma_f32_16x16x32_bf16 v[88:91], v[108:111], v[218:221], v[88:91]
	v_mfma_f32_16x16x32_bf16 v[92:95], v[116:119], v[218:221], v[92:95]
	v_mfma_f32_16x16x32_bf16 v[48:51], v[152:155], v[206:209], v[48:51]
	v_mfma_f32_16x16x32_bf16 v[96:99], v[120:123], v[170:173], v[96:99]
	v_mfma_f32_16x16x32_bf16 v[32:35], v[152:155], v[170:173], v[32:35]
	v_mfma_f32_16x16x32_bf16 v[40:43], v[152:155], v[198:201], v[40:43]
	v_mfma_f32_16x16x32_bf16 v[44:47], v[120:123], v[206:209], v[44:47]
	v_mfma_f32_16x16x32_bf16 v[170:173], v[156:159], v[210:213], v[48:51]
	v_mfma_f32_16x16x32_bf16 v[48:51], v[120:123], v[214:217], v[52:55]
	v_mfma_f32_16x16x32_bf16 v[96:99], v[124:127], v[174:177], v[96:99]
	v_mfma_f32_16x16x32_bf16 v[32:35], v[156:159], v[174:177], v[32:35]
	v_mfma_f32_16x16x32_bf16 v[36:39], v[120:123], v[198:201], v[36:39]
	v_mfma_f32_16x16x32_bf16 v[40:43], v[156:159], v[202:205], v[40:43]
	v_mfma_f32_16x16x32_bf16 v[44:47], v[124:127], v[210:213], v[44:47]
	v_mfma_f32_16x16x32_bf16 v[174:177], v[124:127], v[218:221], v[48:51]
	v_mfma_f32_16x16x32_bf16 v[48:51], v[152:155], v[214:217], v[56:59]
	v_mfma_f32_16x16x32_bf16 v[36:39], v[124:127], v[202:205], v[36:39]
	v_mfma_f32_16x16x32_bf16 v[198:201], v[156:159], v[218:221], v[48:51]
	s_barrier
	s_mov_b32 m0, s39
	s_nop 1
	ds_read_b128 v[48:51], v191 offset:16384
	ds_read_b128 v[52:55], v191 offset:17408
	ds_read_b128 v[56:59], v191 offset:18432
	ds_read_b128 v[202:205], v191 offset:19456
	ds_read_b128 v[206:209], v191 offset:20480
	ds_read_b128 v[210:213], v191 offset:21504
	ds_read_b128 v[214:217], v191 offset:22528
	ds_read_b128 v[218:221], v191 offset:23552
	v_add_u32_e32 v160, s52, v181
	s_nop 0
	global_load_lds_dwordx4 v160, s[14:15]
	v_add_u32_e32 v160, s52, v183
	s_mov_b32 m0, s40
	s_add_i32 s52, s43, 0x50200
	global_load_lds_dwordx4 v160, s[14:15]
	v_add_u32_e32 v160, s52, v181
	s_mov_b32 m0, s41
	s_nop 0
	global_load_lds_dwordx4 v160, s[14:15]
	v_add_u32_e32 v160, s52, v183
	s_mov_b32 m0, s42
	s_nop 0
	global_load_lds_dwordx4 v160, s[14:15]
	v_add_u32_e32 v160, s44, v180
	s_mov_b32 m0, s23
	s_nop 0
	global_load_lds_dwordx4 v160, s[12:13]
	v_add_u32_e32 v160, s44, v182
	s_mov_b32 m0, s24
	s_nop 0
	global_load_lds_dwordx4 v160, s[12:13]
	s_waitcnt vmcnt(8)
	s_waitcnt lgkmcnt(0)
	s_barrier
	s_waitcnt lgkmcnt(0)
	v_mfma_f32_16x16x32_bf16 v[0:3], v[104:107], v[214:217], v[0:3]
	v_mfma_f32_16x16x32_bf16 v[128:131], v[104:107], v[48:51], v[128:131]
	v_mfma_f32_16x16x32_bf16 v[136:139], v[104:107], v[56:59], v[136:139]
	v_mfma_f32_16x16x32_bf16 v[222:225], v[108:111], v[218:221], v[0:3]
	v_mfma_f32_16x16x32_bf16 v[0:3], v[112:115], v[214:217], v[4:7]
	v_mfma_f32_16x16x32_bf16 v[128:131], v[108:111], v[52:55], v[128:131]
	v_mfma_f32_16x16x32_bf16 v[132:135], v[112:115], v[48:51], v[132:135]
	v_mfma_f32_16x16x32_bf16 v[136:139], v[108:111], v[202:205], v[136:139]
	v_mfma_f32_16x16x32_bf16 v[140:143], v[112:115], v[56:59], v[140:143]
	v_mfma_f32_16x16x32_bf16 v[144:147], v[104:107], v[206:209], v[144:147]
	v_mfma_f32_16x16x32_bf16 v[148:151], v[112:115], v[206:209], v[148:151]
	v_mfma_f32_16x16x32_bf16 v[4:7], v[116:119], v[218:221], v[0:3]
	v_mfma_f32_16x16x32_bf16 v[132:135], v[116:119], v[52:55], v[132:135]
	v_mfma_f32_16x16x32_bf16 v[140:143], v[116:119], v[202:205], v[140:143]
	v_mfma_f32_16x16x32_bf16 v[144:147], v[108:111], v[210:213], v[144:147]
	v_mfma_f32_16x16x32_bf16 v[148:151], v[116:119], v[210:213], v[148:151]
	v_mfma_f32_16x16x32_bf16 v[0:3], v[120:123], v[48:51], v[8:11]
	v_mfma_f32_16x16x32_bf16 v[226:229], v[124:127], v[52:55], v[0:3]
	v_mfma_f32_16x16x32_bf16 v[0:3], v[152:155], v[48:51], v[12:15]
	v_mfma_f32_16x16x32_bf16 v[230:233], v[156:159], v[52:55], v[0:3]
	v_mfma_f32_16x16x32_bf16 v[0:3], v[120:123], v[56:59], v[24:27]
	v_mfma_f32_16x16x32_bf16 v[234:237], v[124:127], v[202:205], v[0:3]
	v_mfma_f32_16x16x32_bf16 v[0:3], v[152:155], v[56:59], v[28:31]
	v_mfma_f32_16x16x32_bf16 v[202:205], v[156:159], v[202:205], v[0:3]
	v_mfma_f32_16x16x32_bf16 v[0:3], v[120:123], v[206:209], v[60:63]
	v_mfma_f32_16x16x32_bf16 v[238:241], v[124:127], v[210:213], v[0:3]
	v_mfma_f32_16x16x32_bf16 v[0:3], v[152:155], v[206:209], v[100:103]
	v_mfma_f32_16x16x32_bf16 v[206:209], v[156:159], v[210:213], v[0:3]
	v_mfma_f32_16x16x32_bf16 v[0:3], v[120:123], v[214:217], v[16:19]
	v_mfma_f32_16x16x32_bf16 v[16:19], v[124:127], v[218:221], v[0:3]
	v_mfma_f32_16x16x32_bf16 v[0:3], v[152:155], v[214:217], v[20:23]
	v_mfma_f32_16x16x32_bf16 v[152:155], v[156:159], v[218:221], v[0:3]
	s_barrier
	ds_read_b128 v[20:23], v167
	ds_read_b128 v[120:123], v167 offset:1024
	ds_read_b128 v[156:159], v167 offset:2048
	ds_read_b128 v[210:213], v167 offset:3072
	ds_read_b128 v[214:217], v169
	ds_read_b128 v[218:221], v169 offset:1024
	ds_read_b128 v[242:245], v169 offset:2048
	ds_read_b128 v[246:249], v169 offset:3072
	s_add_i32 s52, s44, 0x150000
	v_add_u32_e32 v0, s52, v180
	s_mov_b32 m0, s25
	ds_read_b128 v[28:31], v191 offset:32768
	ds_read_b128 v[48:51], v191 offset:33792
	ds_read_b128 v[60:63], v191 offset:34816
	ds_read_b128 v[104:107], v191 offset:35840
	ds_read_b128 v[108:111], v191 offset:36864
	ds_read_b128 v[112:115], v191 offset:37888
	ds_read_b128 v[116:119], v191 offset:38912
	ds_read_b128 v[124:127], v191 offset:39936
	s_nop 0
	global_load_lds_dwordx4 v0, s[12:13]
	v_add_u32_e32 v0, s52, v182
	s_mov_b32 m0, s26
	s_nop 0
	global_load_lds_dwordx4 v0, s[12:13]
	s_waitcnt vmcnt(8)
	s_waitcnt lgkmcnt(0)
	s_barrier
	s_waitcnt lgkmcnt(0)
	v_mfma_f32_16x16x32_bf16 v[8:11], v[156:159], v[28:31], v[68:71]
	v_mfma_f32_16x16x32_bf16 v[12:15], v[210:213], v[48:51], v[8:11]
	v_mfma_f32_16x16x32_bf16 v[8:11], v[20:23], v[60:63], v[72:75]
	v_mfma_f32_16x16x32_bf16 v[24:27], v[120:123], v[104:107], v[8:11]
	v_mfma_f32_16x16x32_bf16 v[8:11], v[156:159], v[60:63], v[76:79]
	v_mfma_f32_16x16x32_bf16 v[52:55], v[210:213], v[104:107], v[8:11]
	v_mfma_f32_16x16x32_bf16 v[8:11], v[20:23], v[108:111], v[80:83]
	v_mfma_f32_16x16x32_bf16 v[56:59], v[120:123], v[112:115], v[8:11]
	v_mfma_f32_16x16x32_bf16 v[8:11], v[156:159], v[108:111], v[84:87]
	v_mfma_f32_16x16x32_bf16 v[76:79], v[210:213], v[112:115], v[8:11]
	v_mfma_f32_16x16x32_bf16 v[8:11], v[20:23], v[116:119], v[88:91]
	v_mfma_f32_16x16x32_bf16 v[0:3], v[20:23], v[28:31], v[64:67]
	v_mfma_f32_16x16x32_bf16 v[80:83], v[120:123], v[124:127], v[8:11]
	v_mfma_f32_16x16x32_bf16 v[8:11], v[156:159], v[116:119], v[92:95]
	v_mfma_f32_16x16x32_bf16 v[0:3], v[120:123], v[48:51], v[0:3]
	v_mfma_f32_16x16x32_bf16 v[100:103], v[210:213], v[124:127], v[8:11]
	v_mfma_f32_16x16x32_bf16 v[8:11], v[214:217], v[28:31], v[96:99]
	v_mfma_f32_16x16x32_bf16 v[28:31], v[242:245], v[28:31], v[32:35]
	v_mfma_f32_16x16x32_bf16 v[32:35], v[214:217], v[60:63], v[36:39]
	v_mfma_f32_16x16x32_bf16 v[8:11], v[218:221], v[48:51], v[8:11]
	v_mfma_f32_16x16x32_bf16 v[28:31], v[246:249], v[48:51], v[28:31]
	v_mfma_f32_16x16x32_bf16 v[48:51], v[218:221], v[104:107], v[32:35]
	v_mfma_f32_16x16x32_bf16 v[32:35], v[242:245], v[60:63], v[40:43]
	v_mfma_f32_16x16x32_bf16 v[60:63], v[246:249], v[104:107], v[32:35]
	v_mfma_f32_16x16x32_bf16 v[32:35], v[214:217], v[108:111], v[44:47]
	v_mfma_f32_16x16x32_bf16 v[72:75], v[218:221], v[112:115], v[32:35]
	v_mfma_f32_16x16x32_bf16 v[32:35], v[242:245], v[108:111], v[170:173]
	v_mfma_f32_16x16x32_bf16 v[84:87], v[246:249], v[112:115], v[32:35]
	v_mfma_f32_16x16x32_bf16 v[32:35], v[214:217], v[116:119], v[174:177]
	v_mfma_f32_16x16x32_bf16 v[96:99], v[218:221], v[124:127], v[32:35]
	v_mfma_f32_16x16x32_bf16 v[32:35], v[242:245], v[116:119], v[198:201]
	v_mfma_f32_16x16x32_bf16 v[116:119], v[246:249], v[124:127], v[32:35]
	s_barrier
	s_or_b32 s52, s43, 0x280
	s_nop 3
	v_add_u32_e32 v32, s52, v181
	s_mov_b32 m0, s45
	ds_read_b128 v[40:43], v191 offset:49152
	ds_read_b128 v[44:47], v191 offset:50176
	ds_read_b128 v[92:95], v191 offset:51200
	ds_read_b128 v[170:173], v191 offset:52224
	ds_read_b128 v[174:177], v191 offset:53248
	ds_read_b128 v[198:201], v191 offset:54272
	ds_read_b128 v[250:253], v191 offset:55296
	ds_read_b128 v[160:163], v191 offset:56320
	s_nop 0
	global_load_lds_dwordx4 v32, s[14:15]
	v_add_u32_e32 v32, s52, v183
	s_mov_b32 m0, s46
	s_add_i32 s52, s43, 0x50280
	global_load_lds_dwordx4 v32, s[14:15]
	v_add_u32_e32 v32, s52, v181
	s_mov_b32 m0, s47
	s_nop 0
	global_load_lds_dwordx4 v32, s[14:15]
	v_add_u32_e32 v32, s52, v183
	s_mov_b32 m0, s48
	s_nop 0
	global_load_lds_dwordx4 v32, s[14:15]
	v_add_u32_e32 v32, s51, v180
	s_mov_b32 m0, s28
	s_nop 0
	global_load_lds_dwordx4 v32, s[12:13]
	v_add_u32_e32 v32, s51, v182
	s_mov_b32 m0, s29
	s_nop 0
	global_load_lds_dwordx4 v32, s[12:13]
	s_waitcnt vmcnt(8)
	s_waitcnt lgkmcnt(0)
	s_barrier
	s_waitcnt lgkmcnt(0)
	v_mfma_f32_16x16x32_bf16 v[32:35], v[20:23], v[40:43], v[128:131]
	v_mfma_f32_16x16x32_bf16 v[112:115], v[120:123], v[44:47], v[32:35]
	v_mfma_f32_16x16x32_bf16 v[32:35], v[156:159], v[40:43], v[132:135]
	v_mfma_f32_16x16x32_bf16 v[124:127], v[210:213], v[44:47], v[32:35]
	v_mfma_f32_16x16x32_bf16 v[32:35], v[20:23], v[92:95], v[136:139]
	v_mfma_f32_16x16x32_bf16 v[104:107], v[120:123], v[170:173], v[32:35]
	v_mfma_f32_16x16x32_bf16 v[32:35], v[156:159], v[92:95], v[140:143]
	v_mfma_f32_16x16x32_bf16 v[108:111], v[210:213], v[170:173], v[32:35]
	v_mfma_f32_16x16x32_bf16 v[32:35], v[20:23], v[174:177], v[144:147]
	v_mfma_f32_16x16x32_bf16 v[68:71], v[120:123], v[198:201], v[32:35]
	v_mfma_f32_16x16x32_bf16 v[32:35], v[156:159], v[174:177], v[148:151]
	v_mfma_f32_16x16x32_bf16 v[20:23], v[20:23], v[250:253], v[222:225]
	v_mfma_f32_16x16x32_bf16 v[64:67], v[210:213], v[198:201], v[32:35]
	v_mfma_f32_16x16x32_bf16 v[32:35], v[120:123], v[160:163], v[20:23]
	v_mfma_f32_16x16x32_bf16 v[4:7], v[156:159], v[250:253], v[4:7]
	v_mfma_f32_16x16x32_bf16 v[36:39], v[210:213], v[160:163], v[4:7]
	v_mfma_f32_16x16x32_bf16 v[4:7], v[214:217], v[40:43], v[226:229]
	v_mfma_f32_16x16x32_bf16 v[120:123], v[218:221], v[44:47], v[4:7]
	v_mfma_f32_16x16x32_bf16 v[4:7], v[242:245], v[40:43], v[230:233]
	v_mfma_f32_16x16x32_bf16 v[128:131], v[246:249], v[44:47], v[4:7]
	v_mfma_f32_16x16x32_bf16 v[4:7], v[214:217], v[92:95], v[234:237]
	v_mfma_f32_16x16x32_bf16 v[88:91], v[218:221], v[170:173], v[4:7]
	v_mfma_f32_16x16x32_bf16 v[4:7], v[242:245], v[92:95], v[202:205]
	v_mfma_f32_16x16x32_bf16 v[92:95], v[246:249], v[170:173], v[4:7]
	v_mfma_f32_16x16x32_bf16 v[4:7], v[214:217], v[174:177], v[238:241]
	v_mfma_f32_16x16x32_bf16 v[40:43], v[218:221], v[198:201], v[4:7]
	v_mfma_f32_16x16x32_bf16 v[4:7], v[242:245], v[174:177], v[206:209]
	v_mfma_f32_16x16x32_bf16 v[44:47], v[246:249], v[198:201], v[4:7]
	v_mfma_f32_16x16x32_bf16 v[4:7], v[214:217], v[250:253], v[16:19]
	v_mfma_f32_16x16x32_bf16 v[20:23], v[218:221], v[160:163], v[4:7]
	v_mfma_f32_16x16x32_bf16 v[4:7], v[242:245], v[250:253], v[152:155]
	v_mfma_f32_16x16x32_bf16 v[16:19], v[246:249], v[160:163], v[4:7]
	s_barrier
; __device__ __forceinline__ float lo16(unsigned w) { return __uint_as_float(w << 16); }
; __device__ __forceinline__ float hi16(unsigned w) { return __uint_as_float(w & 0xffff0000u); }
;     __device__ __forceinline__ void mid(f32x4 (&acc)[2][2][4][2], const pg8::Unit& u, int wr, int wc, int fr, int fq) const {
;         const int row0 = u.pm * 256 + wr * 64 + fr, col0 = u.pn * 256 + wc * 32 + 8 * fq;
; #pragma unroll
;         for (int ai = 0; ai < 2; ++ai)
; #pragma unroll
;             for (int m = 0; m < 4; ++m) { const int row = row0 + ai * 128 + m * 16;
; #pragma unroll
;                 for (int bj = 0; bj < 2; ++bj) { const int col = col0 + bj * 128;
;                     const u32x4 aw = *(const u32x4*)((const char*)gA + (unsigned)(row * DM + col) * 2u), bw = *(const u32x4*)((const char*)gB + (unsigned)(row * NMAIN + col) * 2u);
;                     f32x4 r0, r1;
;                     r0[0] = lo16(bw.x) * __builtin_amdgcn_rcpf(fmaxf(lo16(aw.x), 1e-20f)); r0[1] = hi16(bw.x) * __builtin_amdgcn_rcpf(fmaxf(hi16(aw.x), 1e-20f));
;                     r0[2] = lo16(bw.y) * __builtin_amdgcn_rcpf(fmaxf(lo16(aw.y), 1e-20f)); r0[3] = hi16(bw.y) * __builtin_amdgcn_rcpf(fmaxf(hi16(aw.y), 1e-20f));
;                     r1[0] = lo16(bw.z) * __builtin_amdgcn_rcpf(fmaxf(lo16(aw.z), 1e-20f)); r1[1] = hi16(bw.z) * __builtin_amdgcn_rcpf(fmaxf(hi16(aw.z), 1e-20f));
;                     r1[2] = lo16(bw.w) * __builtin_amdgcn_rcpf(fmaxf(lo16(aw.w), 1e-20f)); r1[3] = hi16(bw.w) * __builtin_amdgcn_rcpf(fmaxf(hi16(aw.w), 1e-20f));
;                     acc[ai][bj][m][0] *= r0; acc[ai][bj][m][1] *= r1;
;                     asm volatile("" ::: "memory"); } }
	v_lshl_add_u32 v168, s50, 8, v184
	v_lshl_or_b32 v166, s49, 8, v192
	v_lshlrev_b32_e32 v132, 11, v168
	v_mul_lo_u32 v175, v168, s2
	v_lshlrev_b32_e32 v177, 1, v166
	v_or_b32_e32 v171, 0x80, v166
	v_add_u32_e32 v4, v132, v177
	v_add_lshl_u32 v133, v175, v166, 1
	v_lshlrev_b32_e32 v173, 1, v171
	global_load_dwordx4 v[4:7], v4, s[8:9]
	v_add_u32_e32 v132, v173, v132
	global_load_dwordx4 v[148:151], v133, s[18:19]
	global_load_dwordx4 v[144:147], v132, s[8:9]
	v_add_lshl_u32 v132, v175, v171, 1
	global_load_dwordx4 v[140:143], v132, s[18:19]
	v_or_b32_e32 v170, 16, v168
	v_lshlrev_b32_e32 v172, 11, v170
	v_add_u32_e32 v174, 0x15000, v175
	v_add_u32_e32 v132, v172, v177
	v_add_lshl_u32 v133, v174, v166, 1
	global_load_dwordx4 v[136:139], v132, s[8:9]
	s_nop 0
	global_load_dwordx4 v[132:135], v133, s[18:19]
	v_add_u32_e32 v178, 0x90, v168
	s_and_b64 s[50:51], s[6:7], exec
	s_cselect_b32 s50, s37, s44
	s_cselect_b32 s49, s38, s43
	s_bitset1_b32 s50, 11
	s_add_i32 s44, s44, 0x150080
	s_addk_i32 s43, 0x300
	s_mov_b32 s51, 2
	s_waitcnt vmcnt(0)
	v_lshlrev_b32_e32 v154, 16, v4
	v_and_b32_e32 v155, 0xffff0000, v4
	v_lshlrev_b32_e32 v156, 16, v5
	v_and_b32_e32 v157, 0xffff0000, v5
	v_lshlrev_b32_e32 v152, 16, v148
	v_and_b32_e32 v153, 0xffff0000, v148
	v_lshlrev_b32_e32 v4, 16, v149
	v_and_b32_e32 v5, 0xffff0000, v149
	v_lshlrev_b32_e32 v158, 16, v6
	v_and_b32_e32 v159, 0xffff0000, v6
	v_lshlrev_b32_e32 v148, 16, v150
	v_and_b32_e32 v149, 0xffff0000, v150
	v_lshlrev_b32_e32 v150, 16, v7
	v_and_b32_e32 v160, 0xffff0000, v7
	v_max_f32_e32 v154, v154, v154
	v_max_f32_e32 v155, v155, v155
	v_max_f32_e32 v156, v156, v156
	v_max_f32_e32 v157, v157, v157
	v_lshlrev_b32_e32 v6, 16, v151
	v_and_b32_e32 v7, 0xffff0000, v151
	v_max_f32_e32 v158, v158, v158
	v_max_f32_e32 v159, v159, v159
	v_max_f32_e32 v161, v150, v150
	v_max_f32_e32 v160, v160, v160
	v_lshlrev_b32_e32 v162, 16, v144
	v_and_b32_e32 v144, 0xffff0000, v144
	v_lshlrev_b32_e32 v150, 16, v140
	v_and_b32_e32 v151, 0xffff0000, v140
	v_lshlrev_b32_e32 v140, 16, v145
	v_and_b32_e32 v145, 0xffff0000, v145
	v_max_f32_e32 v154, 0x1e3ce508, v154
	v_max_f32_e32 v155, 0x1e3ce508, v155
	v_max_f32_e32 v156, 0x1e3ce508, v156
	v_max_f32_e32 v157, 0x1e3ce508, v157
	v_max_f32_e32 v158, 0x1e3ce508, v158
	v_max_f32_e32 v159, 0x1e3ce508, v159
	v_max_f32_e32 v161, 0x1e3ce508, v161
	v_max_f32_e32 v160, 0x1e3ce508, v160
	v_max_f32_e32 v162, v162, v162
	v_max_f32_e32 v163, v144, v144
	v_max_f32_e32 v176, v145, v145
	v_rcp_f32_e32 v144, v154
	v_rcp_f32_e32 v145, v155
	v_rcp_f32_e32 v154, v156
	v_rcp_f32_e32 v155, v157
	v_rcp_f32_e32 v156, v158
	v_rcp_f32_e32 v157, v159
	v_rcp_f32_e32 v158, v161
	v_rcp_f32_e32 v159, v160
	v_max_f32_e32 v160, 0x1e3ce508, v162
	v_max_f32_e32 v161, 0x1e3ce508, v163
	v_rcp_f32_e32 v160, v160
	v_rcp_f32_e32 v161, v161
	v_max_f32_e32 v140, v140, v140
	v_pk_mul_f32 v[144:145], v[144:145], v[152:153]
	v_pk_mul_f32 v[4:5], v[154:155], v[4:5]
	v_max_f32_e32 v140, 0x1e3ce508, v140
	v_pk_mul_f32 v[148:149], v[156:157], v[148:149]
	v_pk_mul_f32 v[152:153], v[158:159], v[6:7]
	v_pk_mul_f32 v[6:7], v[2:3], v[4:5]
	v_pk_mul_f32 v[4:5], v[0:1], v[144:145]
	v_add_u32_e32 v144, v172, v173
	v_rcp_f32_e32 v162, v140
	v_pk_mul_f32 v[2:3], v[14:15], v[152:153]
	v_pk_mul_f32 v[0:1], v[12:13], v[148:149]
	v_pk_mul_f32 v[12:13], v[160:161], v[150:151]
	v_lshlrev_b32_e32 v14, 16, v141
	v_and_b32_e32 v15, 0xffff0000, v141
	v_lshlrev_b32_e32 v140, 16, v146
	v_and_b32_e32 v141, 0xffff0000, v146
	global_load_dwordx4 v[148:151], v144, s[8:9]
	v_lshlrev_b32_e32 v144, 16, v142
	v_and_b32_e32 v145, 0xffff0000, v142
	v_lshlrev_b32_e32 v142, 16, v147
	v_max_f32_e32 v140, v140, v140
	v_max_f32_e32 v141, v141, v141
	v_max_f32_e32 v142, v142, v142
	v_max_f32_e32 v140, 0x1e3ce508, v140
	v_max_f32_e32 v141, 0x1e3ce508, v141
	v_add_lshl_u32 v146, v174, v171, 1
	v_max_f32_e32 v142, 0x1e3ce508, v142
	v_rcp_f32_e32 v140, v140
	v_rcp_f32_e32 v141, v141
	global_load_dwordx4 v[154:157], v146, s[18:19]
	v_rcp_f32_e32 v146, v142
	v_and_b32_e32 v142, 0xffff0000, v147
	v_max_f32_e32 v142, v142, v142
	v_max_f32_e32 v163, 0x1e3ce508, v176
	v_max_f32_e32 v142, 0x1e3ce508, v142
	v_rcp_f32_e32 v163, v163
	v_rcp_f32_e32 v147, v142
	v_pk_mul_f32 v[140:141], v[140:141], v[144:145]
	v_pk_mul_f32 v[12:13], v[8:9], v[12:13]
	v_pk_mul_f32 v[8:9], v[28:29], v[140:141]
	v_lshlrev_b32_e32 v28, 16, v136
	v_and_b32_e32 v29, 0xffff0000, v136
	v_lshlrev_b32_e32 v142, 16, v143
	v_and_b32_e32 v143, 0xffff0000, v143
	v_max_f32_e32 v28, v28, v28
	v_max_f32_e32 v29, v29, v29
	v_pk_mul_f32 v[14:15], v[162:163], v[14:15]
	v_pk_mul_f32 v[142:143], v[146:147], v[142:143]
	v_max_f32_e32 v28, 0x1e3ce508, v28
	v_max_f32_e32 v29, 0x1e3ce508, v29
	v_pk_mul_f32 v[14:15], v[10:11], v[14:15]
	v_pk_mul_f32 v[10:11], v[30:31], v[142:143]
	v_rcp_f32_e32 v28, v28
	v_rcp_f32_e32 v29, v29
	v_lshlrev_b32_e32 v30, 16, v132
	v_and_b32_e32 v31, 0xffff0000, v132
	v_lshlrev_b32_e32 v132, 16, v137
	v_max_f32_e32 v132, v132, v132
	v_max_f32_e32 v132, 0x1e3ce508, v132
	v_or_b32_e32 v172, 32, v168
	v_rcp_f32_e32 v136, v132
	v_and_b32_e32 v132, 0xffff0000, v137
	v_lshlrev_b32_e32 v152, 11, v172
	v_max_f32_e32 v132, v132, v132
	v_pk_mul_f32 v[28:29], v[28:29], v[30:31]
	v_lshlrev_b32_e32 v30, 16, v133
	v_and_b32_e32 v31, 0xffff0000, v133
	v_add_u32_e32 v133, v152, v177
	v_max_f32_e32 v132, 0x1e3ce508, v132
	global_load_dwordx4 v[140:143], v133, s[8:9]
	v_rcp_f32_e32 v137, v132
	v_add_u32_e32 v158, 0x2a000, v175
	v_lshlrev_b32_e32 v132, 16, v138
	v_and_b32_e32 v133, 0xffff0000, v138
	v_pk_mul_f32 v[30:31], v[136:137], v[30:31]
	v_add_lshl_u32 v136, v158, v166, 1
	global_load_dwordx4 v[144:147], v136, s[18:19]
	v_max_f32_e32 v132, v132, v132
	v_max_f32_e32 v133, v133, v133
	v_max_f32_e32 v132, 0x1e3ce508, v132
	v_max_f32_e32 v133, 0x1e3ce508, v133
	v_rcp_f32_e32 v132, v132
	v_rcp_f32_e32 v133, v133
	v_lshlrev_b32_e32 v136, 16, v134
	v_and_b32_e32 v137, 0xffff0000, v134
	v_lshlrev_b32_e32 v134, 16, v139
	v_max_f32_e32 v134, v134, v134
	v_max_f32_e32 v134, 0x1e3ce508, v134
	v_rcp_f32_e32 v138, v134
	v_and_b32_e32 v134, 0xffff0000, v139
	v_max_f32_e32 v134, v134, v134
	v_pk_mul_f32 v[132:133], v[132:133], v[136:137]
	v_max_f32_e32 v134, 0x1e3ce508, v134
	v_pk_mul_f32 v[28:29], v[24:25], v[28:29]
	v_pk_mul_f32 v[24:25], v[52:53], v[132:133]
	s_waitcnt vmcnt(3)
; __device__ __forceinline__ float lo16(unsigned w) { return __uint_as_float(w << 16); }
; __device__ __forceinline__ float hi16(unsigned w) { return __uint_as_float(w & 0xffff0000u); }
;     __device__ __forceinline__ void mid(f32x4 (&acc)[2][2][4][2], const pg8::Unit& u, int wr, int wc, int fr, int fq) const {
;     ...
;                     const u32x4 aw = *(const u32x4*)((const char*)gA + (unsigned)(row * DM + col) * 2u), bw = *(const u32x4*)((const char*)gB + (unsigned)(row * NMAIN + col) * 2u);
;                     f32x4 r0, r1;
;                     r0[0] = lo16(bw.x) * __builtin_amdgcn_rcpf(fmaxf(lo16(aw.x), 1e-20f)); r0[1] = hi16(bw.x) * __builtin_amdgcn_rcpf(fmaxf(hi16(aw.x), 1e-20f));
;                     r0[2] = lo16(bw.y) * __builtin_amdgcn_rcpf(fmaxf(lo16(aw.y), 1e-20f)); r0[3] = hi16(bw.y) * __builtin_amdgcn_rcpf(fmaxf(hi16(aw.y), 1e-20f));
;                     r1[0] = lo16(bw.z) * __builtin_amdgcn_rcpf(fmaxf(lo16(aw.z), 1e-20f)); r1[1] = hi16(bw.z) * __builtin_amdgcn_rcpf(fmaxf(hi16(aw.z), 1e-20f));
;                     r1[2] = lo16(bw.w) * __builtin_amdgcn_rcpf(fmaxf(lo16(aw.w), 1e-20f)); r1[3] = hi16(bw.w) * __builtin_amdgcn_rcpf(fmaxf(hi16(aw.w), 1e-20f));
;                     acc[ai][bj][m][0] *= r0; acc[ai][bj][m][1] *= r1;
	v_lshlrev_b32_e32 v52, 16, v148
	v_and_b32_e32 v53, 0xffff0000, v148
	v_rcp_f32_e32 v139, v134
	v_max_f32_e32 v52, v52, v52
	v_max_f32_e32 v53, v53, v53
	v_lshlrev_b32_e32 v132, 16, v149
	v_and_b32_e32 v133, 0xffff0000, v149
	v_max_f32_e32 v52, 0x1e3ce508, v52
	v_max_f32_e32 v53, 0x1e3ce508, v53
	v_max_f32_e32 v132, v132, v132
	v_max_f32_e32 v133, v133, v133
	v_rcp_f32_e32 v52, v52
	v_rcp_f32_e32 v53, v53
	v_max_f32_e32 v132, 0x1e3ce508, v132
	v_max_f32_e32 v133, 0x1e3ce508, v133
	v_lshlrev_b32_e32 v134, 16, v135
	v_and_b32_e32 v135, 0xffff0000, v135
	v_rcp_f32_e32 v132, v132
	v_rcp_f32_e32 v133, v133
	v_pk_mul_f32 v[134:135], v[138:139], v[134:135]
	v_pk_mul_f32 v[30:31], v[26:27], v[30:31]
	v_pk_mul_f32 v[26:27], v[54:55], v[134:135]
	s_waitcnt vmcnt(2)
	v_lshlrev_b32_e32 v54, 16, v154
	v_and_b32_e32 v55, 0xffff0000, v154
	v_pk_mul_f32 v[52:53], v[52:53], v[54:55]
	v_lshlrev_b32_e32 v54, 16, v155
	v_and_b32_e32 v55, 0xffff0000, v155
	v_pk_mul_f32 v[54:55], v[132:133], v[54:55]
	v_lshlrev_b32_e32 v132, 16, v150
	v_and_b32_e32 v133, 0xffff0000, v150
	v_max_f32_e32 v132, v132, v132
	v_max_f32_e32 v133, v133, v133
	v_max_f32_e32 v132, 0x1e3ce508, v132
	v_add_u32_e32 v134, v152, v173
	v_max_f32_e32 v133, 0x1e3ce508, v133
	v_rcp_f32_e32 v132, v132
	global_load_dwordx4 v[152:155], v134, s[8:9]
	v_rcp_f32_e32 v133, v133
	v_add_lshl_u32 v137, v158, v171, 1
	v_lshlrev_b32_e32 v134, 16, v156
	v_and_b32_e32 v135, 0xffff0000, v156
	v_lshlrev_b32_e32 v136, 16, v151
	global_load_dwordx4 v[158:161], v137, s[18:19]
	v_and_b32_e32 v137, 0xffff0000, v151
	v_max_f32_e32 v136, v136, v136
	v_max_f32_e32 v137, v137, v137
	v_pk_mul_f32 v[132:133], v[132:133], v[134:135]
	v_max_f32_e32 v136, 0x1e3ce508, v136
	v_max_f32_e32 v137, 0x1e3ce508, v137
	v_pk_mul_f32 v[52:53], v[48:49], v[52:53]
	v_pk_mul_f32 v[48:49], v[60:61], v[132:133]
	v_rcp_f32_e32 v136, v136
	v_rcp_f32_e32 v137, v137
	s_waitcnt vmcnt(3)
	v_lshlrev_b32_e32 v60, 16, v140
	v_and_b32_e32 v61, 0xffff0000, v140
	v_max_f32_e32 v60, v60, v60
	v_max_f32_e32 v61, v61, v61
	v_lshlrev_b32_e32 v132, 16, v141
	v_and_b32_e32 v133, 0xffff0000, v141
	v_max_f32_e32 v60, 0x1e3ce508, v60
	v_max_f32_e32 v61, 0x1e3ce508, v61
	v_max_f32_e32 v132, v132, v132
	v_max_f32_e32 v133, v133, v133
	v_rcp_f32_e32 v60, v60
	v_rcp_f32_e32 v61, v61
	v_max_f32_e32 v132, 0x1e3ce508, v132
	v_max_f32_e32 v133, 0x1e3ce508, v133
	v_lshlrev_b32_e32 v134, 16, v157
	v_and_b32_e32 v135, 0xffff0000, v157
	v_rcp_f32_e32 v132, v132
	v_rcp_f32_e32 v133, v133
	v_pk_mul_f32 v[134:135], v[136:137], v[134:135]
	v_pk_mul_f32 v[54:55], v[50:51], v[54:55]
	v_pk_mul_f32 v[50:51], v[62:63], v[134:135]
	s_waitcnt vmcnt(2)
	v_lshlrev_b32_e32 v62, 16, v144
	v_and_b32_e32 v63, 0xffff0000, v144
	v_pk_mul_f32 v[60:61], v[60:61], v[62:63]
	v_lshlrev_b32_e32 v62, 16, v145
	v_and_b32_e32 v63, 0xffff0000, v145
	v_pk_mul_f32 v[62:63], v[132:133], v[62:63]
	v_lshlrev_b32_e32 v132, 16, v142
	v_or_b32_e32 v174, 48, v168
	v_max_f32_e32 v132, v132, v132
	v_lshlrev_b32_e32 v148, 11, v174
	v_max_f32_e32 v136, 0x1e3ce508, v132
	v_add_u32_e32 v132, v148, v177
	global_load_dwordx4 v[132:135], v132, s[8:9]
	v_add_u32_e32 v150, 0x3f000, v175
	v_add_lshl_u32 v138, v150, v166, 1
	global_load_dwordx4 v[138:141], v138, s[18:19]
	v_and_b32_e32 v137, 0xffff0000, v142
	v_max_f32_e32 v137, v137, v137
	v_max_f32_e32 v137, 0x1e3ce508, v137
	v_rcp_f32_e32 v136, v136
	v_rcp_f32_e32 v137, v137
	v_lshlrev_b32_e32 v144, 16, v146
	v_and_b32_e32 v145, 0xffff0000, v146
	v_lshlrev_b32_e32 v142, 16, v143
	v_and_b32_e32 v143, 0xffff0000, v143
	v_max_f32_e32 v142, v142, v142
	v_max_f32_e32 v143, v143, v143
	v_pk_mul_f32 v[136:137], v[136:137], v[144:145]
	v_max_f32_e32 v142, 0x1e3ce508, v142
	v_max_f32_e32 v143, 0x1e3ce508, v143
	v_pk_mul_f32 v[60:61], v[56:57], v[60:61]
	v_pk_mul_f32 v[56:57], v[76:77], v[136:137]
	v_rcp_f32_e32 v142, v142
	v_rcp_f32_e32 v143, v143
	v_lshlrev_b32_e32 v144, 16, v147
	v_and_b32_e32 v145, 0xffff0000, v147
	v_pk_mul_f32 v[62:63], v[58:59], v[62:63]
	v_pk_mul_f32 v[142:143], v[142:143], v[144:145]
	v_add_lshl_u32 v145, v150, v171, 1
	v_pk_mul_f32 v[58:59], v[78:79], v[142:143]
	s_waitcnt vmcnt(3)
	v_lshlrev_b32_e32 v76, 16, v152
	v_and_b32_e32 v77, 0xffff0000, v152
	v_max_f32_e32 v76, v76, v76
	v_max_f32_e32 v77, v77, v77
	v_lshlrev_b32_e32 v136, 16, v153
	v_and_b32_e32 v137, 0xffff0000, v153
	v_max_f32_e32 v76, 0x1e3ce508, v76
	v_max_f32_e32 v77, 0x1e3ce508, v77
	v_max_f32_e32 v136, v136, v136
	v_max_f32_e32 v137, v137, v137
	v_rcp_f32_e32 v76, v76
	v_rcp_f32_e32 v77, v77
	v_max_f32_e32 v136, 0x1e3ce508, v136
	v_max_f32_e32 v137, 0x1e3ce508, v137
	v_rcp_f32_e32 v136, v136
	v_rcp_f32_e32 v137, v137
	s_waitcnt vmcnt(2)
	v_lshlrev_b32_e32 v78, 16, v158
	v_and_b32_e32 v79, 0xffff0000, v158
	v_pk_mul_f32 v[76:77], v[76:77], v[78:79]
	v_lshlrev_b32_e32 v78, 16, v159
	v_and_b32_e32 v79, 0xffff0000, v159
	v_pk_mul_f32 v[78:79], v[136:137], v[78:79]
	v_lshlrev_b32_e32 v136, 16, v154
	v_and_b32_e32 v137, 0xffff0000, v154
	v_add_u32_e32 v142, v148, v173
	v_max_f32_e32 v136, v136, v136
	global_load_dwordx4 v[146:149], v142, s[8:9]
	v_max_f32_e32 v137, v137, v137
	v_max_f32_e32 v136, 0x1e3ce508, v136
	v_max_f32_e32 v137, 0x1e3ce508, v137
	v_rcp_f32_e32 v136, v136
	v_rcp_f32_e32 v137, v137
	v_lshlrev_b32_e32 v142, 16, v160
	v_and_b32_e32 v143, 0xffff0000, v160
	v_lshlrev_b32_e32 v144, 16, v155
	global_load_dwordx4 v[156:159], v145, s[18:19]
	v_and_b32_e32 v145, 0xffff0000, v155
	v_max_f32_e32 v144, v144, v144
	v_max_f32_e32 v145, v145, v145
	v_pk_mul_f32 v[136:137], v[136:137], v[142:143]
	v_max_f32_e32 v144, 0x1e3ce508, v144
	v_max_f32_e32 v145, 0x1e3ce508, v145
	v_pk_mul_f32 v[76:77], v[72:73], v[76:77]
	v_pk_mul_f32 v[72:73], v[84:85], v[136:137]
	v_rcp_f32_e32 v144, v144
	v_rcp_f32_e32 v145, v145
	v_lshlrev_b32_e32 v142, 16, v161
	v_and_b32_e32 v143, 0xffff0000, v161
	v_pk_mul_f32 v[78:79], v[74:75], v[78:79]
	v_pk_mul_f32 v[142:143], v[144:145], v[142:143]
	v_add_u32_e32 v176, 0x80, v168
	s_waitcnt vmcnt(3)
; __device__ __forceinline__ float lo16(unsigned w) { return __uint_as_float(w << 16); }
; __device__ __forceinline__ float hi16(unsigned w) { return __uint_as_float(w & 0xffff0000u); }
;     __device__ __forceinline__ void mid(f32x4 (&acc)[2][2][4][2], const pg8::Unit& u, int wr, int wc, int fr, int fq) const {
;     ...
;                     const u32x4 aw = *(const u32x4*)((const char*)gA + (unsigned)(row * DM + col) * 2u), bw = *(const u32x4*)((const char*)gB + (unsigned)(row * NMAIN + col) * 2u);
;                     f32x4 r0, r1;
;                     r0[0] = lo16(bw.x) * __builtin_amdgcn_rcpf(fmaxf(lo16(aw.x), 1e-20f)); r0[1] = hi16(bw.x) * __builtin_amdgcn_rcpf(fmaxf(hi16(aw.x), 1e-20f));
;                     r0[2] = lo16(bw.y) * __builtin_amdgcn_rcpf(fmaxf(lo16(aw.y), 1e-20f)); r0[3] = hi16(bw.y) * __builtin_amdgcn_rcpf(fmaxf(hi16(aw.y), 1e-20f));
;                     r1[0] = lo16(bw.z) * __builtin_amdgcn_rcpf(fmaxf(lo16(aw.z), 1e-20f)); r1[1] = hi16(bw.z) * __builtin_amdgcn_rcpf(fmaxf(hi16(aw.z), 1e-20f));
;                     r1[2] = lo16(bw.w) * __builtin_amdgcn_rcpf(fmaxf(lo16(aw.w), 1e-20f)); r1[3] = hi16(bw.w) * __builtin_amdgcn_rcpf(fmaxf(hi16(aw.w), 1e-20f));
;                     acc[ai][bj][m][0] *= r0; acc[ai][bj][m][1] *= r1;
	v_lshlrev_b32_e32 v84, 16, v132
	v_and_b32_e32 v85, 0xffff0000, v132
	v_max_f32_e32 v84, v84, v84
	v_max_f32_e32 v85, v85, v85
	v_lshlrev_b32_e32 v132, 16, v133
	v_and_b32_e32 v133, 0xffff0000, v133
	v_max_f32_e32 v84, 0x1e3ce508, v84
	v_max_f32_e32 v85, 0x1e3ce508, v85
	v_max_f32_e32 v132, v132, v132
	v_max_f32_e32 v133, v133, v133
	v_rcp_f32_e32 v84, v84
	v_rcp_f32_e32 v85, v85
	v_max_f32_e32 v132, 0x1e3ce508, v132
	v_max_f32_e32 v133, 0x1e3ce508, v133
	v_rcp_f32_e32 v132, v132
	v_rcp_f32_e32 v133, v133
	v_pk_mul_f32 v[74:75], v[86:87], v[142:143]
	s_waitcnt vmcnt(2)
	v_lshlrev_b32_e32 v86, 16, v138
	v_and_b32_e32 v87, 0xffff0000, v138
	v_pk_mul_f32 v[84:85], v[84:85], v[86:87]
	v_lshlrev_b32_e32 v86, 16, v139
	v_and_b32_e32 v87, 0xffff0000, v139
	v_lshlrev_b32_e32 v152, 11, v176
	v_pk_mul_f32 v[86:87], v[132:133], v[86:87]
	v_add_u32_e32 v133, v152, v177
	global_load_dwordx4 v[136:139], v133, s[8:9]
	v_add_u32_e32 v154, 0xa8000, v175
	v_lshlrev_b32_e32 v132, 16, v134
	v_and_b32_e32 v133, 0xffff0000, v134
	v_add_lshl_u32 v134, v154, v166, 1
	global_load_dwordx4 v[142:145], v134, s[18:19]
	v_lshlrev_b32_e32 v134, 16, v135
	v_and_b32_e32 v135, 0xffff0000, v135
	v_max_f32_e32 v134, v134, v134
	v_max_f32_e32 v135, v135, v135
	v_max_f32_e32 v134, 0x1e3ce508, v134
	v_max_f32_e32 v135, 0x1e3ce508, v135
	v_max_f32_e32 v132, v132, v132
	v_max_f32_e32 v133, v133, v133
	v_rcp_f32_e32 v134, v134
	v_rcp_f32_e32 v135, v135
	v_max_f32_e32 v132, 0x1e3ce508, v132
	v_max_f32_e32 v133, 0x1e3ce508, v133
	v_rcp_f32_e32 v132, v132
	v_rcp_f32_e32 v133, v133
	v_lshlrev_b32_e32 v150, 16, v140
	v_and_b32_e32 v151, 0xffff0000, v140
	v_lshlrev_b32_e32 v140, 16, v141
	v_and_b32_e32 v141, 0xffff0000, v141
	v_pk_mul_f32 v[134:135], v[134:135], v[140:141]
	v_pk_mul_f32 v[86:87], v[82:83], v[86:87]
	v_pk_mul_f32 v[82:83], v[102:103], v[134:135]
	v_add_u32_e32 v134, v152, v173
	v_pk_mul_f32 v[132:133], v[132:133], v[150:151]
	global_load_dwordx4 v[150:153], v134, s[8:9]
	v_pk_mul_f32 v[84:85], v[80:81], v[84:85]
	v_pk_mul_f32 v[80:81], v[100:101], v[132:133]
	s_waitcnt vmcnt(4)
	v_lshlrev_b32_e32 v100, 16, v146
	v_and_b32_e32 v101, 0xffff0000, v146
	v_max_f32_e32 v100, v100, v100
	v_max_f32_e32 v101, v101, v101
	v_lshlrev_b32_e32 v132, 16, v147
	v_and_b32_e32 v133, 0xffff0000, v147
	v_max_f32_e32 v100, 0x1e3ce508, v100
	v_max_f32_e32 v101, 0x1e3ce508, v101
	v_max_f32_e32 v132, v132, v132
	v_max_f32_e32 v133, v133, v133
	v_rcp_f32_e32 v100, v100
	v_rcp_f32_e32 v101, v101
	v_max_f32_e32 v132, 0x1e3ce508, v132
	v_max_f32_e32 v133, 0x1e3ce508, v133
	v_rcp_f32_e32 v132, v132
	v_rcp_f32_e32 v133, v133
	s_waitcnt vmcnt(3)
	v_lshlrev_b32_e32 v102, 16, v156
	v_and_b32_e32 v103, 0xffff0000, v156
	v_pk_mul_f32 v[100:101], v[100:101], v[102:103]
	v_lshlrev_b32_e32 v102, 16, v157
	v_and_b32_e32 v103, 0xffff0000, v157
	v_pk_mul_f32 v[102:103], v[132:133], v[102:103]
	v_lshlrev_b32_e32 v132, 16, v148
	v_and_b32_e32 v133, 0xffff0000, v148
	v_max_f32_e32 v132, v132, v132
	v_max_f32_e32 v133, v133, v133
	v_max_f32_e32 v132, 0x1e3ce508, v132
	v_max_f32_e32 v133, 0x1e3ce508, v133
	v_rcp_f32_e32 v132, v132
	v_rcp_f32_e32 v133, v133
	v_add_lshl_u32 v141, v154, v171, 1
	v_lshlrev_b32_e32 v134, 16, v158
	v_and_b32_e32 v135, 0xffff0000, v158
	v_lshlrev_b32_e32 v140, 16, v149
	global_load_dwordx4 v[154:157], v141, s[18:19]
	v_and_b32_e32 v141, 0xffff0000, v149
	v_max_f32_e32 v140, v140, v140
	v_max_f32_e32 v141, v141, v141
	v_pk_mul_f32 v[132:133], v[132:133], v[134:135]
	v_max_f32_e32 v140, 0x1e3ce508, v140
	v_max_f32_e32 v141, 0x1e3ce508, v141
	v_pk_mul_f32 v[100:101], v[96:97], v[100:101]
	v_pk_mul_f32 v[96:97], v[116:117], v[132:133]
	v_rcp_f32_e32 v140, v140
	v_rcp_f32_e32 v141, v141
	v_lshlrev_b32_e32 v134, 16, v159
	v_and_b32_e32 v135, 0xffff0000, v159
	s_waitcnt vmcnt(3)
	v_lshlrev_b32_e32 v116, 16, v136
	v_and_b32_e32 v117, 0xffff0000, v136
	v_max_f32_e32 v116, v116, v116
	v_max_f32_e32 v117, v117, v117
	v_lshlrev_b32_e32 v132, 16, v137
	v_and_b32_e32 v133, 0xffff0000, v137
	v_max_f32_e32 v116, 0x1e3ce508, v116
	v_max_f32_e32 v117, 0x1e3ce508, v117
	v_max_f32_e32 v132, v132, v132
	v_max_f32_e32 v133, v133, v133
	v_rcp_f32_e32 v116, v116
	v_rcp_f32_e32 v117, v117
	v_max_f32_e32 v132, 0x1e3ce508, v132
	v_max_f32_e32 v133, 0x1e3ce508, v133
	v_rcp_f32_e32 v132, v132
	v_rcp_f32_e32 v133, v133
	v_pk_mul_f32 v[134:135], v[140:141], v[134:135]
	v_pk_mul_f32 v[102:103], v[98:99], v[102:103]
	v_pk_mul_f32 v[98:99], v[118:119], v[134:135]
	s_waitcnt vmcnt(2)
	v_lshlrev_b32_e32 v118, 16, v142
	v_and_b32_e32 v119, 0xffff0000, v142
	v_pk_mul_f32 v[116:117], v[116:117], v[118:119]
	v_lshlrev_b32_e32 v118, 16, v143
	v_and_b32_e32 v119, 0xffff0000, v143
	v_pk_mul_f32 v[118:119], v[132:133], v[118:119]
	v_lshlrev_b32_e32 v132, 16, v138
	v_max_f32_e32 v132, v132, v132
	v_lshlrev_b32_e32 v148, 11, v178
	v_max_f32_e32 v136, 0x1e3ce508, v132
	v_add_u32_e32 v132, v148, v177
	global_load_dwordx4 v[132:135], v132, s[8:9]
	v_add_u32_e32 v158, 0xbd000, v175
	v_and_b32_e32 v137, 0xffff0000, v138
	v_add_lshl_u32 v138, v158, v166, 1
	global_load_dwordx4 v[140:143], v138, s[18:19]
	v_lshlrev_b32_e32 v138, 16, v139
	v_and_b32_e32 v139, 0xffff0000, v139
	v_max_f32_e32 v138, v138, v138
	v_max_f32_e32 v139, v139, v139
	v_max_f32_e32 v137, v137, v137
	v_max_f32_e32 v138, 0x1e3ce508, v138
	v_max_f32_e32 v139, 0x1e3ce508, v139
	v_max_f32_e32 v137, 0x1e3ce508, v137
	v_rcp_f32_e32 v138, v138
	v_rcp_f32_e32 v139, v139
	v_rcp_f32_e32 v136, v136
	v_rcp_f32_e32 v137, v137
	v_lshlrev_b32_e32 v146, 16, v144
	v_and_b32_e32 v147, 0xffff0000, v144
	v_lshlrev_b32_e32 v144, 16, v145
	v_and_b32_e32 v145, 0xffff0000, v145
	v_pk_mul_f32 v[138:139], v[138:139], v[144:145]
	v_pk_mul_f32 v[136:137], v[136:137], v[146:147]
	v_pk_mul_f32 v[118:119], v[114:115], v[118:119]
	v_pk_mul_f32 v[114:115], v[126:127], v[138:139]
	v_add_u32_e32 v138, v148, v173
	v_pk_mul_f32 v[116:117], v[112:113], v[116:117]
	v_pk_mul_f32 v[112:113], v[124:125], v[136:137]
	s_waitcnt vmcnt(3)
; __device__ __forceinline__ float lo16(unsigned w) { return __uint_as_float(w << 16); }
; __device__ __forceinline__ float hi16(unsigned w) { return __uint_as_float(w & 0xffff0000u); }
;     __device__ __forceinline__ void mid(f32x4 (&acc)[2][2][4][2], const pg8::Unit& u, int wr, int wc, int fr, int fq) const {
;     ...
;                     const u32x4 aw = *(const u32x4*)((const char*)gA + (unsigned)(row * DM + col) * 2u), bw = *(const u32x4*)((const char*)gB + (unsigned)(row * NMAIN + col) * 2u);
;                     f32x4 r0, r1;
;                     r0[0] = lo16(bw.x) * __builtin_amdgcn_rcpf(fmaxf(lo16(aw.x), 1e-20f)); r0[1] = hi16(bw.x) * __builtin_amdgcn_rcpf(fmaxf(hi16(aw.x), 1e-20f));
;                     r0[2] = lo16(bw.y) * __builtin_amdgcn_rcpf(fmaxf(lo16(aw.y), 1e-20f)); r0[3] = hi16(bw.y) * __builtin_amdgcn_rcpf(fmaxf(hi16(aw.y), 1e-20f));
;                     r1[0] = lo16(bw.z) * __builtin_amdgcn_rcpf(fmaxf(lo16(aw.z), 1e-20f)); r1[1] = hi16(bw.z) * __builtin_amdgcn_rcpf(fmaxf(hi16(aw.z), 1e-20f));
;                     r1[2] = lo16(bw.w) * __builtin_amdgcn_rcpf(fmaxf(lo16(aw.w), 1e-20f)); r1[3] = hi16(bw.w) * __builtin_amdgcn_rcpf(fmaxf(hi16(aw.w), 1e-20f));
;                     acc[ai][bj][m][0] *= r0; acc[ai][bj][m][1] *= r1;
	v_lshlrev_b32_e32 v124, 16, v150
	v_and_b32_e32 v125, 0xffff0000, v150
	v_lshlrev_b32_e32 v136, 16, v151
	v_and_b32_e32 v137, 0xffff0000, v151
	global_load_dwordx4 v[148:151], v138, s[8:9]
	v_add_lshl_u32 v145, v158, v171, 1
	global_load_dwordx4 v[158:161], v145, s[18:19]
	v_max_f32_e32 v124, v124, v124
	v_max_f32_e32 v125, v125, v125
	v_max_f32_e32 v124, 0x1e3ce508, v124
	v_max_f32_e32 v125, 0x1e3ce508, v125
	v_max_f32_e32 v136, v136, v136
	v_max_f32_e32 v137, v137, v137
	v_rcp_f32_e32 v124, v124
	v_rcp_f32_e32 v125, v125
	v_max_f32_e32 v136, 0x1e3ce508, v136
	v_max_f32_e32 v137, 0x1e3ce508, v137
	v_rcp_f32_e32 v136, v136
	v_rcp_f32_e32 v137, v137
	s_waitcnt vmcnt(4)
	v_lshlrev_b32_e32 v126, 16, v154
	v_and_b32_e32 v127, 0xffff0000, v154
	v_pk_mul_f32 v[124:125], v[124:125], v[126:127]
	v_lshlrev_b32_e32 v126, 16, v155
	v_and_b32_e32 v127, 0xffff0000, v155
	v_pk_mul_f32 v[126:127], v[136:137], v[126:127]
	v_lshlrev_b32_e32 v136, 16, v152
	v_and_b32_e32 v137, 0xffff0000, v152
	v_max_f32_e32 v136, v136, v136
	v_max_f32_e32 v137, v137, v137
	v_max_f32_e32 v136, 0x1e3ce508, v136
	v_max_f32_e32 v137, 0x1e3ce508, v137
	v_rcp_f32_e32 v136, v136
	v_rcp_f32_e32 v137, v137
	v_lshlrev_b32_e32 v138, 16, v156
	v_and_b32_e32 v139, 0xffff0000, v156
	v_lshlrev_b32_e32 v144, 16, v153
	v_and_b32_e32 v145, 0xffff0000, v153
	v_max_f32_e32 v144, v144, v144
	v_max_f32_e32 v145, v145, v145
	v_pk_mul_f32 v[136:137], v[136:137], v[138:139]
	v_max_f32_e32 v144, 0x1e3ce508, v144
	v_max_f32_e32 v145, 0x1e3ce508, v145
	v_pk_mul_f32 v[124:125], v[120:121], v[124:125]
	v_pk_mul_f32 v[120:121], v[128:129], v[136:137]
	v_rcp_f32_e32 v144, v144
	v_rcp_f32_e32 v145, v145
	v_lshlrev_b32_e32 v138, 16, v157
	v_and_b32_e32 v139, 0xffff0000, v157
	v_pk_mul_f32 v[126:127], v[122:123], v[126:127]
	v_pk_mul_f32 v[138:139], v[144:145], v[138:139]
	v_add_u32_e32 v152, 0xa0, v168
	s_waitcnt vmcnt(3)
	v_lshlrev_b32_e32 v128, 16, v132
	v_and_b32_e32 v129, 0xffff0000, v132
	v_max_f32_e32 v128, v128, v128
	v_max_f32_e32 v129, v129, v129
	v_lshlrev_b32_e32 v132, 16, v133
	v_and_b32_e32 v133, 0xffff0000, v133
	v_max_f32_e32 v128, 0x1e3ce508, v128
	v_max_f32_e32 v129, 0x1e3ce508, v129
	v_max_f32_e32 v132, v132, v132
	v_max_f32_e32 v133, v133, v133
	v_rcp_f32_e32 v128, v128
	v_rcp_f32_e32 v129, v129
	v_max_f32_e32 v132, 0x1e3ce508, v132
	v_max_f32_e32 v133, 0x1e3ce508, v133
	v_rcp_f32_e32 v132, v132
	v_rcp_f32_e32 v133, v133
	v_pk_mul_f32 v[122:123], v[130:131], v[138:139]
	s_waitcnt vmcnt(2)
	v_lshlrev_b32_e32 v130, 16, v140
	v_and_b32_e32 v131, 0xffff0000, v140
	v_pk_mul_f32 v[128:129], v[128:129], v[130:131]
	v_lshlrev_b32_e32 v130, 16, v141
	v_and_b32_e32 v131, 0xffff0000, v141
	v_lshlrev_b32_e32 v153, 11, v152
	v_pk_mul_f32 v[130:131], v[132:133], v[130:131]
	v_add_u32_e32 v133, v153, v177
	v_lshlrev_b32_e32 v132, 16, v134
	global_load_dwordx4 v[136:139], v133, s[8:9]
	v_and_b32_e32 v133, 0xffff0000, v134
	v_max_f32_e32 v132, v132, v132
	v_max_f32_e32 v133, v133, v133
	v_max_f32_e32 v132, 0x1e3ce508, v132
	v_max_f32_e32 v133, 0x1e3ce508, v133
	v_rcp_f32_e32 v132, v132
	v_rcp_f32_e32 v133, v133
	v_add_u32_e32 v156, 0xd2000, v175
	v_add_lshl_u32 v134, v156, v166, 1
	global_load_dwordx4 v[144:147], v134, s[18:19]
	v_lshlrev_b32_e32 v140, 16, v142
	v_and_b32_e32 v141, 0xffff0000, v142
	v_lshlrev_b32_e32 v134, 16, v135
	v_and_b32_e32 v135, 0xffff0000, v135
	v_max_f32_e32 v134, v134, v134
	v_max_f32_e32 v135, v135, v135
	v_pk_mul_f32 v[132:133], v[132:133], v[140:141]
	v_max_f32_e32 v134, 0x1e3ce508, v134
	v_max_f32_e32 v135, 0x1e3ce508, v135
	v_pk_mul_f32 v[128:129], v[104:105], v[128:129]
	v_pk_mul_f32 v[104:105], v[108:109], v[132:133]
	s_waitcnt vmcnt(3)
	v_lshlrev_b32_e32 v108, 16, v148
	v_and_b32_e32 v109, 0xffff0000, v148
	v_rcp_f32_e32 v134, v134
	v_rcp_f32_e32 v135, v135
	v_max_f32_e32 v108, v108, v108
	v_max_f32_e32 v109, v109, v109
	v_lshlrev_b32_e32 v132, 16, v149
	v_and_b32_e32 v133, 0xffff0000, v149
	v_max_f32_e32 v108, 0x1e3ce508, v108
	v_max_f32_e32 v109, 0x1e3ce508, v109
	v_max_f32_e32 v132, v132, v132
	v_max_f32_e32 v133, v133, v133
	v_rcp_f32_e32 v108, v108
	v_rcp_f32_e32 v109, v109
	v_max_f32_e32 v132, 0x1e3ce508, v132
	v_max_f32_e32 v133, 0x1e3ce508, v133
	v_lshlrev_b32_e32 v140, 16, v143
	v_and_b32_e32 v141, 0xffff0000, v143
	v_rcp_f32_e32 v132, v132
	v_rcp_f32_e32 v133, v133
	v_pk_mul_f32 v[134:135], v[134:135], v[140:141]
	v_pk_mul_f32 v[130:131], v[106:107], v[130:131]
	v_pk_mul_f32 v[106:107], v[110:111], v[134:135]
	s_waitcnt vmcnt(2)
	v_lshlrev_b32_e32 v110, 16, v158
	v_and_b32_e32 v111, 0xffff0000, v158
	v_pk_mul_f32 v[108:109], v[108:109], v[110:111]
	v_lshlrev_b32_e32 v110, 16, v159
	v_and_b32_e32 v111, 0xffff0000, v159
	v_pk_mul_f32 v[110:111], v[132:133], v[110:111]
	v_lshlrev_b32_e32 v132, 16, v150
	v_max_f32_e32 v132, v132, v132
	v_max_f32_e32 v132, 0x1e3ce508, v132
	v_rcp_f32_e32 v148, v132
	v_add_u32_e32 v132, v153, v173
	global_load_dwordx4 v[132:135], v132, s[8:9]
	v_and_b32_e32 v140, 0xffff0000, v150
	v_max_f32_e32 v140, v140, v140
	v_max_f32_e32 v140, 0x1e3ce508, v140
	v_rcp_f32_e32 v149, v140
	v_add_lshl_u32 v140, v156, v171, 1
	global_load_dwordx4 v[140:143], v140, s[18:19]
	v_lshlrev_b32_e32 v154, 16, v160
	v_and_b32_e32 v155, 0xffff0000, v160
	v_lshlrev_b32_e32 v150, 16, v151
	v_and_b32_e32 v151, 0xffff0000, v151
	v_max_f32_e32 v150, v150, v150
	v_max_f32_e32 v151, v151, v151
	v_pk_mul_f32 v[148:149], v[148:149], v[154:155]
	v_max_f32_e32 v150, 0x1e3ce508, v150
	v_max_f32_e32 v151, 0x1e3ce508, v151
	v_pk_mul_f32 v[108:109], v[88:89], v[108:109]
	v_pk_mul_f32 v[88:89], v[92:93], v[148:149]
	v_rcp_f32_e32 v150, v150
	v_rcp_f32_e32 v151, v151
	v_lshlrev_b32_e32 v154, 16, v161
	v_and_b32_e32 v155, 0xffff0000, v161
	v_pk_mul_f32 v[110:111], v[90:91], v[110:111]
	s_waitcnt vmcnt(3)
; __device__ __forceinline__ float lo16(unsigned w) { return __uint_as_float(w << 16); }
; __device__ __forceinline__ float hi16(unsigned w) { return __uint_as_float(w & 0xffff0000u); }
;     __device__ __forceinline__ void mid(f32x4 (&acc)[2][2][4][2], const pg8::Unit& u, int wr, int wc, int fr, int fq) const {
;     ...
;                     const u32x4 aw = *(const u32x4*)((const char*)gA + (unsigned)(row * DM + col) * 2u), bw = *(const u32x4*)((const char*)gB + (unsigned)(row * NMAIN + col) * 2u);
;                     f32x4 r0, r1;
;                     r0[0] = lo16(bw.x) * __builtin_amdgcn_rcpf(fmaxf(lo16(aw.x), 1e-20f)); r0[1] = hi16(bw.x) * __builtin_amdgcn_rcpf(fmaxf(hi16(aw.x), 1e-20f));
;                     r0[2] = lo16(bw.y) * __builtin_amdgcn_rcpf(fmaxf(lo16(aw.y), 1e-20f)); r0[3] = hi16(bw.y) * __builtin_amdgcn_rcpf(fmaxf(hi16(aw.y), 1e-20f));
;                     r1[0] = lo16(bw.z) * __builtin_amdgcn_rcpf(fmaxf(lo16(aw.z), 1e-20f)); r1[1] = hi16(bw.z) * __builtin_amdgcn_rcpf(fmaxf(hi16(aw.z), 1e-20f));
;                     r1[2] = lo16(bw.w) * __builtin_amdgcn_rcpf(fmaxf(lo16(aw.w), 1e-20f)); r1[3] = hi16(bw.w) * __builtin_amdgcn_rcpf(fmaxf(hi16(aw.w), 1e-20f));
;                     acc[ai][bj][m][0] *= r0; acc[ai][bj][m][1] *= r1;
	v_lshlrev_b32_e32 v92, 16, v136
	v_and_b32_e32 v93, 0xffff0000, v136
	v_max_f32_e32 v92, v92, v92
	v_max_f32_e32 v93, v93, v93
	v_lshlrev_b32_e32 v136, 16, v137
	v_and_b32_e32 v137, 0xffff0000, v137
	v_max_f32_e32 v92, 0x1e3ce508, v92
	v_max_f32_e32 v93, 0x1e3ce508, v93
	v_max_f32_e32 v136, v136, v136
	v_max_f32_e32 v137, v137, v137
	v_rcp_f32_e32 v92, v92
	v_rcp_f32_e32 v93, v93
	v_max_f32_e32 v136, 0x1e3ce508, v136
	v_max_f32_e32 v137, 0x1e3ce508, v137
	v_rcp_f32_e32 v136, v136
	v_rcp_f32_e32 v137, v137
	v_pk_mul_f32 v[150:151], v[150:151], v[154:155]
	s_waitcnt vmcnt(2)
	v_lshlrev_b32_e32 v158, 16, v146
	v_pk_mul_f32 v[90:91], v[94:95], v[150:151]
	v_lshlrev_b32_e32 v94, 16, v144
	v_and_b32_e32 v95, 0xffff0000, v144
	v_pk_mul_f32 v[92:93], v[92:93], v[94:95]
	v_lshlrev_b32_e32 v94, 16, v145
	v_and_b32_e32 v95, 0xffff0000, v145
	v_pk_mul_f32 v[94:95], v[136:137], v[94:95]
	v_lshlrev_b32_e32 v136, 16, v138
	v_max_f32_e32 v136, v136, v136
	v_max_f32_e32 v137, 0x1e3ce508, v136
	v_add_u32_e32 v136, 0xb0, v168
	v_lshlrev_b32_e32 v153, 11, v136
	v_add_u32_e32 v144, v153, v177
	global_load_dwordx4 v[148:151], v144, s[8:9]
	v_rcp_f32_e32 v144, v137
	v_and_b32_e32 v137, 0xffff0000, v138
	v_max_f32_e32 v137, v137, v137
	v_max_f32_e32 v137, 0x1e3ce508, v137
	v_rcp_f32_e32 v145, v137
	v_add_u32_e32 v137, 0xe7000, v175
	v_add_lshl_u32 v138, v137, v166, 1
	global_load_dwordx4 v[154:157], v138, s[18:19]
	v_pk_mul_f32 v[68:69], v[68:69], v[92:93]
	v_lshlrev_b32_e32 v138, 16, v139
	v_and_b32_e32 v139, 0xffff0000, v139
	v_max_f32_e32 v138, v138, v138
	v_max_f32_e32 v139, v139, v139
	v_max_f32_e32 v138, 0x1e3ce508, v138
	v_max_f32_e32 v139, 0x1e3ce508, v139
	v_rcp_f32_e32 v138, v138
	v_rcp_f32_e32 v139, v139
	v_pk_mul_f32 v[70:71], v[70:71], v[94:95]
	v_and_b32_e32 v159, 0xffff0000, v146
	v_pk_mul_f32 v[144:145], v[144:145], v[158:159]
	v_lshlrev_b32_e32 v146, 16, v147
	v_and_b32_e32 v147, 0xffff0000, v147
	v_pk_mul_f32 v[138:139], v[138:139], v[146:147]
	s_waitcnt vmcnt(3)
	v_lshlrev_b32_e32 v92, 16, v132
	v_and_b32_e32 v93, 0xffff0000, v132
	v_max_f32_e32 v92, v92, v92
	v_max_f32_e32 v93, v93, v93
	v_max_f32_e32 v92, 0x1e3ce508, v92
	v_max_f32_e32 v93, 0x1e3ce508, v93
	v_rcp_f32_e32 v92, v92
	v_rcp_f32_e32 v93, v93
	s_waitcnt vmcnt(2)
	v_lshlrev_b32_e32 v94, 16, v140
	v_and_b32_e32 v95, 0xffff0000, v140
	v_add_u32_e32 v132, v153, v173
	v_pk_mul_f32 v[92:93], v[92:93], v[94:95]
	v_lshlrev_b32_e32 v94, 16, v133
	v_and_b32_e32 v95, 0xffff0000, v133
	v_max_f32_e32 v94, v94, v94
	v_max_f32_e32 v95, v95, v95
	v_pk_mul_f32 v[64:65], v[64:65], v[144:145]
	v_max_f32_e32 v94, 0x1e3ce508, v94
	v_max_f32_e32 v95, 0x1e3ce508, v95
	global_load_dwordx4 v[144:147], v132, s[8:9]
	v_rcp_f32_e32 v94, v94
	v_rcp_f32_e32 v95, v95
	v_lshlrev_b32_e32 v132, 16, v141
	v_and_b32_e32 v133, 0xffff0000, v141
	v_pk_mul_f32 v[66:67], v[66:67], v[138:139]
	v_pk_mul_f32 v[94:95], v[94:95], v[132:133]
	v_add_lshl_u32 v133, v137, v171, 1
	global_load_dwordx4 v[138:141], v133, s[18:19]
	v_lshlrev_b32_e32 v132, 16, v134
	v_and_b32_e32 v133, 0xffff0000, v134
	v_max_f32_e32 v132, v132, v132
	v_max_f32_e32 v133, v133, v133
	v_max_f32_e32 v132, 0x1e3ce508, v132
	v_max_f32_e32 v133, 0x1e3ce508, v133
	v_rcp_f32_e32 v132, v132
	v_rcp_f32_e32 v133, v133
	v_lshlrev_b32_e32 v158, 16, v142
	v_and_b32_e32 v159, 0xffff0000, v142
	v_pk_mul_f32 v[92:93], v[40:41], v[92:93]
	v_pk_mul_f32 v[132:133], v[132:133], v[158:159]
	v_lshlrev_b32_e32 v134, 16, v135
	v_pk_mul_f32 v[44:45], v[44:45], v[132:133]
	v_and_b32_e32 v135, 0xffff0000, v135
	v_pk_mul_f32 v[94:95], v[42:43], v[94:95]
	v_max_f32_e32 v134, v134, v134
	v_max_f32_e32 v135, v135, v135
	v_max_f32_e32 v134, 0x1e3ce508, v134
	v_max_f32_e32 v135, 0x1e3ce508, v135
	v_rcp_f32_e32 v134, v134
	v_rcp_f32_e32 v135, v135
	v_lshlrev_b32_e32 v142, 16, v143
	v_and_b32_e32 v143, 0xffff0000, v143
	v_pk_mul_f32 v[134:135], v[134:135], v[142:143]
	s_waitcnt vmcnt(3)
	v_lshlrev_b32_e32 v40, 16, v148
	v_and_b32_e32 v41, 0xffff0000, v148
	v_max_f32_e32 v40, v40, v40
	v_max_f32_e32 v41, v41, v41
	v_lshlrev_b32_e32 v132, 16, v149
	v_and_b32_e32 v133, 0xffff0000, v149
	v_max_f32_e32 v40, 0x1e3ce508, v40
	v_max_f32_e32 v41, 0x1e3ce508, v41
	v_max_f32_e32 v132, v132, v132
	v_max_f32_e32 v133, v133, v133
	v_rcp_f32_e32 v40, v40
	v_rcp_f32_e32 v41, v41
	v_max_f32_e32 v132, 0x1e3ce508, v132
	v_max_f32_e32 v133, 0x1e3ce508, v133
	v_rcp_f32_e32 v132, v132
	v_rcp_f32_e32 v133, v133
	s_waitcnt vmcnt(2)
	v_lshlrev_b32_e32 v42, 16, v154
	v_and_b32_e32 v43, 0xffff0000, v154
	v_pk_mul_f32 v[40:41], v[40:41], v[42:43]
	v_lshlrev_b32_e32 v42, 16, v155
	v_and_b32_e32 v43, 0xffff0000, v155
	v_pk_mul_f32 v[42:43], v[132:133], v[42:43]
	v_lshlrev_b32_e32 v132, 16, v150
	v_and_b32_e32 v133, 0xffff0000, v150
	v_max_f32_e32 v132, v132, v132
	v_max_f32_e32 v133, v133, v133
	v_max_f32_e32 v132, 0x1e3ce508, v132
	v_max_f32_e32 v133, 0x1e3ce508, v133
	v_rcp_f32_e32 v132, v132
	v_rcp_f32_e32 v133, v133
	v_lshlrev_b32_e32 v137, 16, v151
	v_max_f32_e32 v137, v137, v137
	v_max_f32_e32 v137, 0x1e3ce508, v137
	v_pk_mul_f32 v[46:47], v[46:47], v[134:135]
	v_lshlrev_b32_e32 v134, 16, v156
	v_and_b32_e32 v135, 0xffff0000, v156
	v_rcp_f32_e32 v142, v137
	v_and_b32_e32 v137, 0xffff0000, v151
	v_max_f32_e32 v137, v137, v137
	v_pk_mul_f32 v[132:133], v[132:133], v[134:135]
	v_max_f32_e32 v137, 0x1e3ce508, v137
	v_pk_mul_f32 v[40:41], v[32:33], v[40:41]
	v_pk_mul_f32 v[32:33], v[36:37], v[132:133]
	v_rcp_f32_e32 v143, v137
	s_waitcnt vmcnt(1)
; __device__ __forceinline__ float lo16(unsigned w) { return __uint_as_float(w << 16); }
; __device__ __forceinline__ float hi16(unsigned w) { return __uint_as_float(w & 0xffff0000u); }
;     __device__ __forceinline__ void mid(f32x4 (&acc)[2][2][4][2], const pg8::Unit& u, int wr, int wc, int fr, int fq) const {
;     ...
;                     const u32x4 aw = *(const u32x4*)((const char*)gA + (unsigned)(row * DM + col) * 2u), bw = *(const u32x4*)((const char*)gB + (unsigned)(row * NMAIN + col) * 2u);
;                     f32x4 r0, r1;
;                     r0[0] = lo16(bw.x) * __builtin_amdgcn_rcpf(fmaxf(lo16(aw.x), 1e-20f)); r0[1] = hi16(bw.x) * __builtin_amdgcn_rcpf(fmaxf(hi16(aw.x), 1e-20f));
;                     r0[2] = lo16(bw.y) * __builtin_amdgcn_rcpf(fmaxf(lo16(aw.y), 1e-20f)); r0[3] = hi16(bw.y) * __builtin_amdgcn_rcpf(fmaxf(hi16(aw.y), 1e-20f));
;                     r1[0] = lo16(bw.z) * __builtin_amdgcn_rcpf(fmaxf(lo16(aw.z), 1e-20f)); r1[1] = hi16(bw.z) * __builtin_amdgcn_rcpf(fmaxf(hi16(aw.z), 1e-20f));
;                     r1[2] = lo16(bw.w) * __builtin_amdgcn_rcpf(fmaxf(lo16(aw.w), 1e-20f)); r1[3] = hi16(bw.w) * __builtin_amdgcn_rcpf(fmaxf(hi16(aw.w), 1e-20f));
;                     acc[ai][bj][m][0] *= r0; acc[ai][bj][m][1] *= r1;
	v_lshlrev_b32_e32 v36, 16, v144
	v_and_b32_e32 v37, 0xffff0000, v144
	v_max_f32_e32 v36, v36, v36
	v_max_f32_e32 v37, v37, v37
	v_lshlrev_b32_e32 v132, 16, v145
	v_and_b32_e32 v133, 0xffff0000, v145
	v_max_f32_e32 v36, 0x1e3ce508, v36
	v_max_f32_e32 v37, 0x1e3ce508, v37
	v_max_f32_e32 v132, v132, v132
	v_max_f32_e32 v133, v133, v133
	v_rcp_f32_e32 v36, v36
	v_rcp_f32_e32 v37, v37
	v_max_f32_e32 v132, 0x1e3ce508, v132
	v_max_f32_e32 v133, 0x1e3ce508, v133
	v_lshlrev_b32_e32 v134, 16, v157
	v_and_b32_e32 v135, 0xffff0000, v157
	v_rcp_f32_e32 v132, v132
	v_rcp_f32_e32 v133, v133
	v_pk_mul_f32 v[134:135], v[142:143], v[134:135]
	v_pk_mul_f32 v[42:43], v[34:35], v[42:43]
	v_pk_mul_f32 v[34:35], v[38:39], v[134:135]
	s_waitcnt vmcnt(0)
	v_lshlrev_b32_e32 v38, 16, v138
	v_and_b32_e32 v39, 0xffff0000, v138
	v_lshlrev_b32_e32 v137, 16, v147
	v_pk_mul_f32 v[36:37], v[36:37], v[38:39]
	v_lshlrev_b32_e32 v38, 16, v139
	v_and_b32_e32 v39, 0xffff0000, v139
	v_max_f32_e32 v137, v137, v137
	v_pk_mul_f32 v[38:39], v[132:133], v[38:39]
	v_lshlrev_b32_e32 v132, 16, v146
	v_and_b32_e32 v133, 0xffff0000, v146
	v_max_f32_e32 v137, 0x1e3ce508, v137
	v_max_f32_e32 v132, v132, v132
	v_max_f32_e32 v133, v133, v133
	v_rcp_f32_e32 v138, v137
	v_and_b32_e32 v137, 0xffff0000, v147
	v_max_f32_e32 v132, 0x1e3ce508, v132
	v_max_f32_e32 v133, 0x1e3ce508, v133
	v_max_f32_e32 v137, v137, v137
	v_rcp_f32_e32 v132, v132
	v_rcp_f32_e32 v133, v133
	v_max_f32_e32 v137, 0x1e3ce508, v137
	v_rcp_f32_e32 v139, v137
	v_lshlrev_b32_e32 v134, 16, v140
	v_and_b32_e32 v135, 0xffff0000, v140
	v_pk_mul_f32 v[132:133], v[132:133], v[134:135]
	v_lshlrev_b32_e32 v134, 16, v141
	v_and_b32_e32 v135, 0xffff0000, v141
	v_pk_mul_f32 v[134:135], v[138:139], v[134:135]
	v_pk_mul_f32 v[22:23], v[22:23], v[38:39]
	v_pk_mul_f32 v[20:21], v[20:21], v[36:37]
	v_pk_mul_f32 v[18:19], v[18:19], v[134:135]
	v_pk_mul_f32 v[16:17], v[16:17], v[132:133]
.LBB0_599:
	ds_read_b128 v[36:39], v195
	ds_read_b128 v[132:135], v195 offset:1024
	ds_read_b128 v[138:141], v195 offset:2048
	ds_read_b128 v[142:145], v195 offset:3072
	ds_read_b128 v[146:149], v196
	ds_read_b128 v[154:157], v196 offset:1024
	ds_read_b128 v[158:161], v196 offset:2048
	ds_read_b128 v[198:201], v196 offset:3072
	s_add_i32 s52, s44, 0xffeb0080
	s_cmp_eq_u32 s51, 16
	s_cselect_b32 s54, s50, s52
	s_cselect_b32 s53, s49, s43
	s_or_b32 s52, s54, 0x80
	v_add_u32_e32 v137, s44, v194
	s_mov_b32 m0, s0
	ds_read_b128 v[202:205], v191
	ds_read_b128 v[206:209], v191 offset:1024
	ds_read_b128 v[210:213], v191 offset:2048
	ds_read_b128 v[214:217], v191 offset:3072
	ds_read_b128 v[218:221], v191 offset:4096
	ds_read_b128 v[222:225], v191 offset:5120
	ds_read_b128 v[226:229], v191 offset:6144
	ds_read_b128 v[230:233], v191 offset:7168
	s_nop 0
	global_load_lds_dwordx4 v137, s[12:13]
	v_add_u32_e32 v137, s44, v193
	s_mov_b32 m0, s1
	s_nop 0
	global_load_lds_dwordx4 v137, s[12:13]
	s_waitcnt vmcnt(8)
	s_waitcnt lgkmcnt(0)
	s_barrier
	s_waitcnt lgkmcnt(0)
	v_mfma_f32_16x16x32_bf16 v[4:7], v[36:39], v[202:205], v[4:7]
	v_mfma_f32_16x16x32_bf16 v[0:3], v[138:141], v[202:205], v[0:3]
	v_mfma_f32_16x16x32_bf16 v[28:31], v[36:39], v[210:213], v[28:31]
	v_mfma_f32_16x16x32_bf16 v[24:27], v[138:141], v[210:213], v[24:27]
	v_mfma_f32_16x16x32_bf16 v[60:63], v[36:39], v[218:221], v[60:63]
	v_mfma_f32_16x16x32_bf16 v[56:59], v[138:141], v[218:221], v[56:59]
	v_mfma_f32_16x16x32_bf16 v[84:87], v[36:39], v[226:229], v[84:87]
	v_mfma_f32_16x16x32_bf16 v[80:83], v[138:141], v[226:229], v[80:83]
	v_mfma_f32_16x16x32_bf16 v[4:7], v[132:135], v[206:209], v[4:7]
	v_mfma_f32_16x16x32_bf16 v[0:3], v[142:145], v[206:209], v[0:3]
	v_mfma_f32_16x16x32_bf16 v[28:31], v[132:135], v[214:217], v[28:31]
	v_mfma_f32_16x16x32_bf16 v[24:27], v[142:145], v[214:217], v[24:27]
	v_mfma_f32_16x16x32_bf16 v[60:63], v[132:135], v[222:225], v[60:63]
	v_mfma_f32_16x16x32_bf16 v[56:59], v[142:145], v[222:225], v[56:59]
	v_mfma_f32_16x16x32_bf16 v[84:87], v[132:135], v[230:233], v[84:87]
	v_mfma_f32_16x16x32_bf16 v[80:83], v[142:145], v[230:233], v[80:83]
	v_mfma_f32_16x16x32_bf16 v[12:15], v[146:149], v[202:205], v[12:15]
	v_mfma_f32_16x16x32_bf16 v[8:11], v[158:161], v[202:205], v[8:11]
	v_mfma_f32_16x16x32_bf16 v[52:55], v[146:149], v[210:213], v[52:55]
	v_mfma_f32_16x16x32_bf16 v[48:51], v[158:161], v[210:213], v[48:51]
	v_mfma_f32_16x16x32_bf16 v[76:79], v[146:149], v[218:221], v[76:79]
	v_mfma_f32_16x16x32_bf16 v[72:75], v[158:161], v[218:221], v[72:75]
	v_mfma_f32_16x16x32_bf16 v[100:103], v[146:149], v[226:229], v[100:103]
	v_mfma_f32_16x16x32_bf16 v[96:99], v[158:161], v[226:229], v[96:99]
	v_mfma_f32_16x16x32_bf16 v[12:15], v[154:157], v[206:209], v[12:15]
	v_mfma_f32_16x16x32_bf16 v[8:11], v[198:201], v[206:209], v[8:11]
	v_mfma_f32_16x16x32_bf16 v[52:55], v[154:157], v[214:217], v[52:55]
	v_mfma_f32_16x16x32_bf16 v[48:51], v[198:201], v[214:217], v[48:51]
	v_mfma_f32_16x16x32_bf16 v[76:79], v[154:157], v[222:225], v[76:79]
	v_mfma_f32_16x16x32_bf16 v[72:75], v[198:201], v[222:225], v[72:75]
	v_mfma_f32_16x16x32_bf16 v[100:103], v[154:157], v[230:233], v[100:103]
	v_mfma_f32_16x16x32_bf16 v[96:99], v[198:201], v[230:233], v[96:99]
	s_barrier
	s_mov_b32 m0, s39
	ds_read_b128 v[202:205], v191 offset:16384
	ds_read_b128 v[206:209], v191 offset:17408
	ds_read_b128 v[210:213], v191 offset:18432
	ds_read_b128 v[214:217], v191 offset:19456
	ds_read_b128 v[218:221], v191 offset:20480
	ds_read_b128 v[222:225], v191 offset:21504
	ds_read_b128 v[226:229], v191 offset:22528
	ds_read_b128 v[230:233], v191 offset:23552
	v_add_u32_e32 v137, s53, v181
	s_add_i32 s55, s53, 0x50000
	global_load_lds_dwordx4 v137, s[14:15]
	v_add_u32_e32 v137, s53, v183
	s_mov_b32 m0, s40
	s_nop 0
	global_load_lds_dwordx4 v137, s[14:15]
	v_add_u32_e32 v137, s55, v181
	s_mov_b32 m0, s41
	s_nop 0
	global_load_lds_dwordx4 v137, s[14:15]
	v_add_u32_e32 v137, s55, v183
	s_mov_b32 m0, s42
	s_nop 0
	global_load_lds_dwordx4 v137, s[14:15]
	v_add_u32_e32 v137, s54, v180
	s_mov_b32 m0, s23
	s_nop 0
	global_load_lds_dwordx4 v137, s[12:13]
	v_add_u32_e32 v137, s54, v182
	s_mov_b32 m0, s24
	s_nop 0
	global_load_lds_dwordx4 v137, s[12:13]
	s_waitcnt vmcnt(8)
	s_waitcnt lgkmcnt(0)
	s_barrier
	s_waitcnt lgkmcnt(0)
	v_mfma_f32_16x16x32_bf16 v[116:119], v[36:39], v[202:205], v[116:119]
	v_mfma_f32_16x16x32_bf16 v[112:115], v[138:141], v[202:205], v[112:115]
	v_mfma_f32_16x16x32_bf16 v[128:131], v[36:39], v[210:213], v[128:131]
	v_mfma_f32_16x16x32_bf16 v[104:107], v[138:141], v[210:213], v[104:107]
	v_mfma_f32_16x16x32_bf16 v[68:71], v[36:39], v[218:221], v[68:71]
	v_mfma_f32_16x16x32_bf16 v[64:67], v[138:141], v[218:221], v[64:67]
	v_mfma_f32_16x16x32_bf16 v[32:35], v[138:141], v[226:229], v[32:35]
	v_mfma_f32_16x16x32_bf16 v[116:119], v[132:135], v[206:209], v[116:119]
	v_mfma_f32_16x16x32_bf16 v[112:115], v[142:145], v[206:209], v[112:115]
	v_mfma_f32_16x16x32_bf16 v[128:131], v[132:135], v[214:217], v[128:131]
	v_mfma_f32_16x16x32_bf16 v[104:107], v[142:145], v[214:217], v[104:107]
	v_mfma_f32_16x16x32_bf16 v[68:71], v[132:135], v[222:225], v[68:71]
	v_mfma_f32_16x16x32_bf16 v[64:67], v[142:145], v[222:225], v[64:67]
	v_mfma_f32_16x16x32_bf16 v[36:39], v[36:39], v[226:229], v[40:43]
	v_mfma_f32_16x16x32_bf16 v[32:35], v[142:145], v[230:233], v[32:35]
	v_mfma_f32_16x16x32_bf16 v[36:39], v[132:135], v[230:233], v[36:39]
	v_mfma_f32_16x16x32_bf16 v[40:43], v[146:149], v[202:205], v[124:127]
	v_mfma_f32_16x16x32_bf16 v[124:127], v[154:157], v[206:209], v[40:43]
	v_mfma_f32_16x16x32_bf16 v[40:43], v[158:161], v[202:205], v[120:123]
	v_mfma_f32_16x16x32_bf16 v[120:123], v[198:201], v[206:209], v[40:43]
	v_mfma_f32_16x16x32_bf16 v[40:43], v[146:149], v[210:213], v[108:111]
	v_mfma_f32_16x16x32_bf16 v[108:111], v[154:157], v[214:217], v[40:43]
	v_mfma_f32_16x16x32_bf16 v[40:43], v[158:161], v[210:213], v[88:91]
	v_mfma_f32_16x16x32_bf16 v[88:91], v[198:201], v[214:217], v[40:43]
	v_mfma_f32_16x16x32_bf16 v[40:43], v[146:149], v[218:221], v[92:95]
	v_mfma_f32_16x16x32_bf16 v[92:95], v[154:157], v[222:225], v[40:43]
	v_mfma_f32_16x16x32_bf16 v[40:43], v[158:161], v[218:221], v[44:47]
	v_mfma_f32_16x16x32_bf16 v[20:23], v[146:149], v[226:229], v[20:23]
	v_mfma_f32_16x16x32_bf16 v[16:19], v[158:161], v[226:229], v[16:19]
	v_mfma_f32_16x16x32_bf16 v[44:47], v[198:201], v[222:225], v[40:43]
	v_mfma_f32_16x16x32_bf16 v[20:23], v[154:157], v[230:233], v[20:23]
	v_mfma_f32_16x16x32_bf16 v[16:19], v[198:201], v[230:233], v[16:19]
	s_barrier
	s_nop 0
	ds_read_b128 v[40:43], v167
	ds_read_b128 v[132:135], v167 offset:1024
	ds_read_b128 v[138:141], v167 offset:2048
	ds_read_b128 v[142:145], v167 offset:3072
	ds_read_b128 v[146:149], v169
	ds_read_b128 v[154:157], v169 offset:1024
	ds_read_b128 v[158:161], v169 offset:2048
	ds_read_b128 v[198:201], v169 offset:3072
	s_add_i32 s54, s54, 0x150000
	v_add_u32_e32 v137, s54, v180
	s_mov_b32 m0, s25
	ds_read_b128 v[202:205], v191 offset:32768
	ds_read_b128 v[206:209], v191 offset:33792
	ds_read_b128 v[210:213], v191 offset:34816
	ds_read_b128 v[214:217], v191 offset:35840
	ds_read_b128 v[218:221], v191 offset:36864
	ds_read_b128 v[222:225], v191 offset:37888
	ds_read_b128 v[226:229], v191 offset:38912
	ds_read_b128 v[230:233], v191 offset:39936
	s_nop 0
	global_load_lds_dwordx4 v137, s[12:13]
	v_add_u32_e32 v137, s54, v182
	s_mov_b32 m0, s26
	s_nop 0
	global_load_lds_dwordx4 v137, s[12:13]
	s_waitcnt vmcnt(8)
	s_waitcnt lgkmcnt(0)
	s_barrier
; #define PG8_BAR __builtin_amdgcn_s_barrier()
;     ...
;         if constexpr (Epi::MIDHOOK) {
;             for (int t = 0; t < 4; t += 2) PG8_ITER(t);
;             E.mid(acc, cur, wr, wc, fr, fq);
;             for (int t = 4; t < nt; t += 2) PG8_ITER(t);
;         } else {
;             for (int t = 0; t < nt; t += 2) PG8_ITER(t);
;         }
;     ...
;         if constexpr (ALIGN_EPI) { if (wr == 0) PG8_BAR; }
	s_waitcnt lgkmcnt(0)
	v_mfma_f32_16x16x32_bf16 v[4:7], v[40:43], v[202:205], v[4:7]
	v_mfma_f32_16x16x32_bf16 v[0:3], v[138:141], v[202:205], v[0:3]
	v_mfma_f32_16x16x32_bf16 v[28:31], v[40:43], v[210:213], v[28:31]
	v_mfma_f32_16x16x32_bf16 v[24:27], v[138:141], v[210:213], v[24:27]
	v_mfma_f32_16x16x32_bf16 v[60:63], v[40:43], v[218:221], v[60:63]
	v_mfma_f32_16x16x32_bf16 v[56:59], v[138:141], v[218:221], v[56:59]
	v_mfma_f32_16x16x32_bf16 v[84:87], v[40:43], v[226:229], v[84:87]
	v_mfma_f32_16x16x32_bf16 v[80:83], v[138:141], v[226:229], v[80:83]
	v_mfma_f32_16x16x32_bf16 v[4:7], v[132:135], v[206:209], v[4:7]
	v_mfma_f32_16x16x32_bf16 v[0:3], v[142:145], v[206:209], v[0:3]
	v_mfma_f32_16x16x32_bf16 v[28:31], v[132:135], v[214:217], v[28:31]
	v_mfma_f32_16x16x32_bf16 v[24:27], v[142:145], v[214:217], v[24:27]
	v_mfma_f32_16x16x32_bf16 v[60:63], v[132:135], v[222:225], v[60:63]
	v_mfma_f32_16x16x32_bf16 v[56:59], v[142:145], v[222:225], v[56:59]
	v_mfma_f32_16x16x32_bf16 v[84:87], v[132:135], v[230:233], v[84:87]
	v_mfma_f32_16x16x32_bf16 v[80:83], v[142:145], v[230:233], v[80:83]
	v_mfma_f32_16x16x32_bf16 v[12:15], v[146:149], v[202:205], v[12:15]
	v_mfma_f32_16x16x32_bf16 v[8:11], v[158:161], v[202:205], v[8:11]
	v_mfma_f32_16x16x32_bf16 v[52:55], v[146:149], v[210:213], v[52:55]
	v_mfma_f32_16x16x32_bf16 v[48:51], v[158:161], v[210:213], v[48:51]
	v_mfma_f32_16x16x32_bf16 v[76:79], v[146:149], v[218:221], v[76:79]
	v_mfma_f32_16x16x32_bf16 v[72:75], v[158:161], v[218:221], v[72:75]
	v_mfma_f32_16x16x32_bf16 v[100:103], v[146:149], v[226:229], v[100:103]
	v_mfma_f32_16x16x32_bf16 v[96:99], v[158:161], v[226:229], v[96:99]
	v_mfma_f32_16x16x32_bf16 v[12:15], v[154:157], v[206:209], v[12:15]
	v_mfma_f32_16x16x32_bf16 v[8:11], v[198:201], v[206:209], v[8:11]
	v_mfma_f32_16x16x32_bf16 v[52:55], v[154:157], v[214:217], v[52:55]
	v_mfma_f32_16x16x32_bf16 v[48:51], v[198:201], v[214:217], v[48:51]
	v_mfma_f32_16x16x32_bf16 v[76:79], v[154:157], v[222:225], v[76:79]
	v_mfma_f32_16x16x32_bf16 v[72:75], v[198:201], v[222:225], v[72:75]
	v_mfma_f32_16x16x32_bf16 v[100:103], v[154:157], v[230:233], v[100:103]
	v_mfma_f32_16x16x32_bf16 v[96:99], v[198:201], v[230:233], v[96:99]
	s_barrier
	s_or_b32 s54, s53, 0x80
	v_add_u32_e32 v137, s54, v181
	s_mov_b32 m0, s45
	ds_read_b128 v[202:205], v191 offset:49152
	ds_read_b128 v[206:209], v191 offset:50176
	ds_read_b128 v[210:213], v191 offset:51200
	ds_read_b128 v[214:217], v191 offset:52224
	ds_read_b128 v[218:221], v191 offset:53248
	ds_read_b128 v[222:225], v191 offset:54272
	ds_read_b128 v[226:229], v191 offset:55296
	ds_read_b128 v[230:233], v191 offset:56320
	s_add_i32 s53, s53, 0x50080
	global_load_lds_dwordx4 v137, s[14:15]
	v_add_u32_e32 v137, s54, v183
	s_mov_b32 m0, s46
	s_nop 0
	global_load_lds_dwordx4 v137, s[14:15]
	v_add_u32_e32 v137, s53, v181
	s_mov_b32 m0, s47
	s_nop 0
	global_load_lds_dwordx4 v137, s[14:15]
	v_add_u32_e32 v137, s53, v183
	s_mov_b32 m0, s48
	s_nop 0
	global_load_lds_dwordx4 v137, s[14:15]
	v_add_u32_e32 v137, s52, v180
	s_mov_b32 m0, s28
	s_nop 0
	global_load_lds_dwordx4 v137, s[12:13]
	v_add_u32_e32 v137, s52, v182
	s_mov_b32 m0, s29
	s_nop 0
	global_load_lds_dwordx4 v137, s[12:13]
	s_waitcnt vmcnt(8)
	s_waitcnt lgkmcnt(0)
	s_barrier
	s_waitcnt lgkmcnt(0)
	v_mfma_f32_16x16x32_bf16 v[116:119], v[40:43], v[202:205], v[116:119]
	v_mfma_f32_16x16x32_bf16 v[112:115], v[138:141], v[202:205], v[112:115]
	v_mfma_f32_16x16x32_bf16 v[128:131], v[40:43], v[210:213], v[128:131]
	v_mfma_f32_16x16x32_bf16 v[104:107], v[138:141], v[210:213], v[104:107]
	v_mfma_f32_16x16x32_bf16 v[68:71], v[40:43], v[218:221], v[68:71]
	v_mfma_f32_16x16x32_bf16 v[64:67], v[138:141], v[218:221], v[64:67]
	v_mfma_f32_16x16x32_bf16 v[36:39], v[40:43], v[226:229], v[36:39]
	v_mfma_f32_16x16x32_bf16 v[32:35], v[138:141], v[226:229], v[32:35]
	v_mfma_f32_16x16x32_bf16 v[116:119], v[132:135], v[206:209], v[116:119]
	v_mfma_f32_16x16x32_bf16 v[112:115], v[142:145], v[206:209], v[112:115]
	v_mfma_f32_16x16x32_bf16 v[128:131], v[132:135], v[214:217], v[128:131]
	v_mfma_f32_16x16x32_bf16 v[104:107], v[142:145], v[214:217], v[104:107]
	v_mfma_f32_16x16x32_bf16 v[68:71], v[132:135], v[222:225], v[68:71]
	v_mfma_f32_16x16x32_bf16 v[64:67], v[142:145], v[222:225], v[64:67]
	v_mfma_f32_16x16x32_bf16 v[40:43], v[132:135], v[230:233], v[36:39]
	v_mfma_f32_16x16x32_bf16 v[32:35], v[142:145], v[230:233], v[32:35]
	v_mfma_f32_16x16x32_bf16 v[36:39], v[146:149], v[202:205], v[124:127]
	v_mfma_f32_16x16x32_bf16 v[124:127], v[154:157], v[206:209], v[36:39]
	v_mfma_f32_16x16x32_bf16 v[36:39], v[158:161], v[202:205], v[120:123]
	v_mfma_f32_16x16x32_bf16 v[120:123], v[198:201], v[206:209], v[36:39]
	v_mfma_f32_16x16x32_bf16 v[36:39], v[146:149], v[210:213], v[108:111]
	v_mfma_f32_16x16x32_bf16 v[108:111], v[154:157], v[214:217], v[36:39]
	v_mfma_f32_16x16x32_bf16 v[36:39], v[158:161], v[210:213], v[88:91]
	v_mfma_f32_16x16x32_bf16 v[88:91], v[198:201], v[214:217], v[36:39]
	v_mfma_f32_16x16x32_bf16 v[36:39], v[146:149], v[218:221], v[92:95]
	v_mfma_f32_16x16x32_bf16 v[92:95], v[154:157], v[222:225], v[36:39]
	v_mfma_f32_16x16x32_bf16 v[36:39], v[158:161], v[218:221], v[44:47]
	v_mfma_f32_16x16x32_bf16 v[20:23], v[146:149], v[226:229], v[20:23]
	v_mfma_f32_16x16x32_bf16 v[16:19], v[158:161], v[226:229], v[16:19]
	v_mfma_f32_16x16x32_bf16 v[44:47], v[198:201], v[222:225], v[36:39]
	v_mfma_f32_16x16x32_bf16 v[20:23], v[154:157], v[230:233], v[20:23]
	v_mfma_f32_16x16x32_bf16 v[16:19], v[198:201], v[230:233], v[16:19]
	s_barrier
	s_add_i32 s51, s51, 2
	s_addk_i32 s44, 0x100
	s_addk_i32 s43, 0x100
	s_cmp_gt_u32 s51, 17
	s_cbranch_scc0 .LBB0_599
	s_and_b64 vcc, exec, s[20:21]
	s_cbranch_vccz .LBB0_602
	s_barrier

.LBB0_674:
	v_add_u32_e32 v154, s36, v136
	v_add_u32_e32 v170, s37, v136
	ds_read_b128 v[142:145], v154
	ds_read_b128 v[146:149], v154 offset:1024
	ds_read_b128 v[150:153], v154 offset:2048
	ds_read_b128 v[154:157], v154 offset:3072
	ds_read_b128 v[158:161], v170
	ds_read_b128 v[162:165], v170 offset:1024
	ds_read_b128 v[166:169], v170 offset:2048
	ds_read_b128 v[170:173], v170 offset:3072
	s_add_i32 s45, s28, s44
	s_add_i32 s46, s27, s44
	s_cmp_eq_u32 s43, 12
	s_cselect_b32 s47, s41, s45
	s_cselect_b32 s46, s42, s46
	s_or_b32 s45, s47, 0x80
	v_add_u32_e32 v185, s44, v141
	v_add_u32_e32 v185, 0x3ff80, v185
	ds_read_b128 v[174:177], v139
	ds_read_b128 v[178:181], v139 offset:1024
	ds_read_b128 v[192:195], v139 offset:2048
	ds_read_b128 v[196:199], v139 offset:3072
	ds_read_b128 v[200:203], v139 offset:4096
	ds_read_b128 v[204:207], v139 offset:5120
	ds_read_b128 v[208:211], v139 offset:6144
	ds_read_b128 v[212:215], v139 offset:7168
	s_add_i32 m0, s26, 0xc000
	s_nop 0
	global_load_lds_dwordx4 v185, s[10:11]
	v_add_u32_e32 v185, s44, v140
	v_add_u32_e32 v185, 0x3ff80, v185
	s_add_i32 m0, s26, 0xe000
	s_nop 0
	global_load_lds_dwordx4 v185, s[10:11]
	s_waitcnt vmcnt(8)
	s_waitcnt lgkmcnt(0)
	s_barrier
	s_waitcnt lgkmcnt(0)
	v_mfma_f32_16x16x32_bf16 v[124:127], v[142:145], v[174:177], v[124:127]
	v_mfma_f32_16x16x32_bf16 v[120:123], v[150:153], v[174:177], v[120:123]
	v_mfma_f32_16x16x32_bf16 v[108:111], v[142:145], v[192:195], v[108:111]
	v_mfma_f32_16x16x32_bf16 v[104:107], v[150:153], v[192:195], v[104:107]
	v_mfma_f32_16x16x32_bf16 v[92:95], v[142:145], v[200:203], v[92:95]
	v_mfma_f32_16x16x32_bf16 v[88:91], v[150:153], v[200:203], v[88:91]
	v_mfma_f32_16x16x32_bf16 v[76:79], v[142:145], v[208:211], v[76:79]
	v_mfma_f32_16x16x32_bf16 v[72:75], v[150:153], v[208:211], v[72:75]
	v_mfma_f32_16x16x32_bf16 v[124:127], v[146:149], v[178:181], v[124:127]
	v_mfma_f32_16x16x32_bf16 v[120:123], v[154:157], v[178:181], v[120:123]
	v_mfma_f32_16x16x32_bf16 v[108:111], v[146:149], v[196:199], v[108:111]
	v_mfma_f32_16x16x32_bf16 v[104:107], v[154:157], v[196:199], v[104:107]
	v_mfma_f32_16x16x32_bf16 v[92:95], v[146:149], v[204:207], v[92:95]
	v_mfma_f32_16x16x32_bf16 v[88:91], v[154:157], v[204:207], v[88:91]
	v_mfma_f32_16x16x32_bf16 v[76:79], v[146:149], v[212:215], v[76:79]
	v_mfma_f32_16x16x32_bf16 v[72:75], v[154:157], v[212:215], v[72:75]
	v_mfma_f32_16x16x32_bf16 v[116:119], v[158:161], v[174:177], v[116:119]
	v_mfma_f32_16x16x32_bf16 v[112:115], v[166:169], v[174:177], v[112:115]
	v_mfma_f32_16x16x32_bf16 v[100:103], v[158:161], v[192:195], v[100:103]
	v_mfma_f32_16x16x32_bf16 v[96:99], v[166:169], v[192:195], v[96:99]
	v_mfma_f32_16x16x32_bf16 v[84:87], v[158:161], v[200:203], v[84:87]
	v_mfma_f32_16x16x32_bf16 v[80:83], v[166:169], v[200:203], v[80:83]
	v_mfma_f32_16x16x32_bf16 v[68:71], v[158:161], v[208:211], v[68:71]
	v_mfma_f32_16x16x32_bf16 v[64:67], v[166:169], v[208:211], v[64:67]
	v_mfma_f32_16x16x32_bf16 v[116:119], v[162:165], v[178:181], v[116:119]
	v_mfma_f32_16x16x32_bf16 v[112:115], v[170:173], v[178:181], v[112:115]
	v_mfma_f32_16x16x32_bf16 v[100:103], v[162:165], v[196:199], v[100:103]
	v_mfma_f32_16x16x32_bf16 v[96:99], v[170:173], v[196:199], v[96:99]
	v_mfma_f32_16x16x32_bf16 v[84:87], v[162:165], v[204:207], v[84:87]
	v_mfma_f32_16x16x32_bf16 v[80:83], v[170:173], v[204:207], v[80:83]
	v_mfma_f32_16x16x32_bf16 v[68:71], v[162:165], v[212:215], v[68:71]
	v_mfma_f32_16x16x32_bf16 v[64:67], v[170:173], v[212:215], v[64:67]
	s_barrier
	s_add_i32 s48, s36, s25
	ds_read_b128 v[174:177], v139 offset:16384
	ds_read_b128 v[178:181], v139 offset:17408
	ds_read_b128 v[192:195], v139 offset:18432
	ds_read_b128 v[196:199], v139 offset:19456
	ds_read_b128 v[200:203], v139 offset:20480
	ds_read_b128 v[204:207], v139 offset:21504
	ds_read_b128 v[208:211], v139 offset:22528
	ds_read_b128 v[212:215], v139 offset:23552
	v_add_u32_e32 v185, s46, v133
	s_mov_b32 m0, s48
	s_add_i32 s49, s37, s25
	global_load_lds_dwordx4 v185, s[0:1]
	v_add_u32_e32 v185, s46, v135
	s_add_i32 m0, s48, 0x2000
	s_add_i32 s48, s46, 0x40000
	global_load_lds_dwordx4 v185, s[0:1]
	v_add_u32_e32 v185, s48, v133
	s_mov_b32 m0, s49
	s_nop 0
	global_load_lds_dwordx4 v185, s[0:1]
	v_add_u32_e32 v185, s48, v135
	s_add_i32 m0, s49, 0x2000
	s_nop 0
	global_load_lds_dwordx4 v185, s[0:1]
	v_add_u32_e32 v185, s47, v132
	s_mov_b32 m0, s26
	s_nop 0
	global_load_lds_dwordx4 v185, s[10:11]
	v_add_u32_e32 v185, s47, v134
	s_mov_b32 m0, s29
	s_nop 0
	global_load_lds_dwordx4 v185, s[10:11]
	s_waitcnt vmcnt(8)
	s_waitcnt lgkmcnt(0)
	s_barrier
	s_waitcnt lgkmcnt(0)
	v_mfma_f32_16x16x32_bf16 v[60:63], v[142:145], v[174:177], v[60:63]
	v_mfma_f32_16x16x32_bf16 v[56:59], v[150:153], v[174:177], v[56:59]
	v_mfma_f32_16x16x32_bf16 v[44:47], v[142:145], v[192:195], v[44:47]
	v_mfma_f32_16x16x32_bf16 v[40:43], v[150:153], v[192:195], v[40:43]
	v_mfma_f32_16x16x32_bf16 v[28:31], v[142:145], v[200:203], v[28:31]
	v_mfma_f32_16x16x32_bf16 v[24:27], v[150:153], v[200:203], v[24:27]
	v_mfma_f32_16x16x32_bf16 v[12:15], v[142:145], v[208:211], v[12:15]
	v_mfma_f32_16x16x32_bf16 v[8:11], v[150:153], v[208:211], v[8:11]
	v_mfma_f32_16x16x32_bf16 v[60:63], v[146:149], v[178:181], v[60:63]
	v_mfma_f32_16x16x32_bf16 v[56:59], v[154:157], v[178:181], v[56:59]
	v_mfma_f32_16x16x32_bf16 v[44:47], v[146:149], v[196:199], v[44:47]
	v_mfma_f32_16x16x32_bf16 v[40:43], v[154:157], v[196:199], v[40:43]
	v_mfma_f32_16x16x32_bf16 v[28:31], v[146:149], v[204:207], v[28:31]
	v_mfma_f32_16x16x32_bf16 v[24:27], v[154:157], v[204:207], v[24:27]
	v_mfma_f32_16x16x32_bf16 v[12:15], v[146:149], v[212:215], v[12:15]
	v_mfma_f32_16x16x32_bf16 v[8:11], v[154:157], v[212:215], v[8:11]
	v_mfma_f32_16x16x32_bf16 v[52:55], v[158:161], v[174:177], v[52:55]
	v_mfma_f32_16x16x32_bf16 v[48:51], v[166:169], v[174:177], v[48:51]
	v_mfma_f32_16x16x32_bf16 v[36:39], v[158:161], v[192:195], v[36:39]
	v_mfma_f32_16x16x32_bf16 v[32:35], v[166:169], v[192:195], v[32:35]
	v_mfma_f32_16x16x32_bf16 v[20:23], v[158:161], v[200:203], v[20:23]
	v_mfma_f32_16x16x32_bf16 v[16:19], v[166:169], v[200:203], v[16:19]
	v_mfma_f32_16x16x32_bf16 v[4:7], v[158:161], v[208:211], v[4:7]
	v_mfma_f32_16x16x32_bf16 v[0:3], v[166:169], v[208:211], v[0:3]
	v_mfma_f32_16x16x32_bf16 v[52:55], v[162:165], v[178:181], v[52:55]
	v_mfma_f32_16x16x32_bf16 v[48:51], v[170:173], v[178:181], v[48:51]
	v_mfma_f32_16x16x32_bf16 v[36:39], v[162:165], v[196:199], v[36:39]
	v_mfma_f32_16x16x32_bf16 v[32:35], v[170:173], v[196:199], v[32:35]
	v_mfma_f32_16x16x32_bf16 v[20:23], v[162:165], v[204:207], v[20:23]
	v_mfma_f32_16x16x32_bf16 v[16:19], v[170:173], v[204:207], v[16:19]
	v_mfma_f32_16x16x32_bf16 v[4:7], v[162:165], v[212:215], v[4:7]
	v_mfma_f32_16x16x32_bf16 v[0:3], v[170:173], v[212:215], v[0:3]
	s_barrier
	s_add_i32 s48, 0, 0x18000
	s_add_i32 s49, 0, 0x1c000
	v_add_u32_e32 v154, s48, v136
	v_add_u32_e32 v170, s49, v136
	ds_read_b128 v[142:145], v154
	ds_read_b128 v[146:149], v154 offset:1024
	ds_read_b128 v[150:153], v154 offset:2048
	ds_read_b128 v[154:157], v154 offset:3072
	ds_read_b128 v[158:161], v170
	ds_read_b128 v[162:165], v170 offset:1024
	ds_read_b128 v[166:169], v170 offset:2048
	ds_read_b128 v[170:173], v170 offset:3072
	s_add_i32 s47, s47, 0x40000
	v_add_u32_e32 v185, s47, v132
	s_mov_b32 m0, s30
	ds_read_b128 v[174:177], v139 offset:32768
	ds_read_b128 v[178:181], v139 offset:33792
	ds_read_b128 v[192:195], v139 offset:34816
	ds_read_b128 v[196:199], v139 offset:35840
	ds_read_b128 v[200:203], v139 offset:36864
	ds_read_b128 v[204:207], v139 offset:37888
	ds_read_b128 v[208:211], v139 offset:38912
	ds_read_b128 v[212:215], v139 offset:39936
	s_nop 0
	global_load_lds_dwordx4 v185, s[10:11]
	v_add_u32_e32 v185, s47, v134
	s_mov_b32 m0, s31
	s_nop 0
	global_load_lds_dwordx4 v185, s[10:11]
	s_waitcnt vmcnt(8)
	s_waitcnt lgkmcnt(0)
	s_barrier
	s_waitcnt lgkmcnt(0)
	v_mfma_f32_16x16x32_bf16 v[124:127], v[142:145], v[174:177], v[124:127]
	v_mfma_f32_16x16x32_bf16 v[120:123], v[150:153], v[174:177], v[120:123]
	v_mfma_f32_16x16x32_bf16 v[108:111], v[142:145], v[192:195], v[108:111]
	v_mfma_f32_16x16x32_bf16 v[104:107], v[150:153], v[192:195], v[104:107]
	v_mfma_f32_16x16x32_bf16 v[92:95], v[142:145], v[200:203], v[92:95]
	v_mfma_f32_16x16x32_bf16 v[88:91], v[150:153], v[200:203], v[88:91]
	v_mfma_f32_16x16x32_bf16 v[76:79], v[142:145], v[208:211], v[76:79]
	v_mfma_f32_16x16x32_bf16 v[72:75], v[150:153], v[208:211], v[72:75]
	v_mfma_f32_16x16x32_bf16 v[124:127], v[146:149], v[178:181], v[124:127]
	v_mfma_f32_16x16x32_bf16 v[120:123], v[154:157], v[178:181], v[120:123]
	v_mfma_f32_16x16x32_bf16 v[108:111], v[146:149], v[196:199], v[108:111]
	v_mfma_f32_16x16x32_bf16 v[104:107], v[154:157], v[196:199], v[104:107]
	v_mfma_f32_16x16x32_bf16 v[92:95], v[146:149], v[204:207], v[92:95]
	v_mfma_f32_16x16x32_bf16 v[88:91], v[154:157], v[204:207], v[88:91]
	v_mfma_f32_16x16x32_bf16 v[76:79], v[146:149], v[212:215], v[76:79]
	v_mfma_f32_16x16x32_bf16 v[72:75], v[154:157], v[212:215], v[72:75]
	v_mfma_f32_16x16x32_bf16 v[116:119], v[158:161], v[174:177], v[116:119]
	v_mfma_f32_16x16x32_bf16 v[112:115], v[166:169], v[174:177], v[112:115]
	v_mfma_f32_16x16x32_bf16 v[100:103], v[158:161], v[192:195], v[100:103]
	v_mfma_f32_16x16x32_bf16 v[96:99], v[166:169], v[192:195], v[96:99]
	v_mfma_f32_16x16x32_bf16 v[84:87], v[158:161], v[200:203], v[84:87]
	v_mfma_f32_16x16x32_bf16 v[80:83], v[166:169], v[200:203], v[80:83]
	v_mfma_f32_16x16x32_bf16 v[68:71], v[158:161], v[208:211], v[68:71]
	v_mfma_f32_16x16x32_bf16 v[64:67], v[166:169], v[208:211], v[64:67]
	v_mfma_f32_16x16x32_bf16 v[116:119], v[162:165], v[178:181], v[116:119]
	v_mfma_f32_16x16x32_bf16 v[112:115], v[170:173], v[178:181], v[112:115]
	v_mfma_f32_16x16x32_bf16 v[100:103], v[162:165], v[196:199], v[100:103]
	v_mfma_f32_16x16x32_bf16 v[96:99], v[170:173], v[196:199], v[96:99]
	v_mfma_f32_16x16x32_bf16 v[84:87], v[162:165], v[204:207], v[84:87]
	v_mfma_f32_16x16x32_bf16 v[80:83], v[170:173], v[204:207], v[80:83]
	v_mfma_f32_16x16x32_bf16 v[68:71], v[162:165], v[212:215], v[68:71]
	v_mfma_f32_16x16x32_bf16 v[64:67], v[170:173], v[212:215], v[64:67]
	s_barrier
; #define PG8_BAR __builtin_amdgcn_s_barrier()
;     ...
;         if constexpr (Epi::MIDHOOK) {
;             for (int t = 0; t < 4; t += 2) PG8_ITER(t);
;             E.mid(acc, cur, wr, wc, fr, fq);
;             for (int t = 4; t < nt; t += 2) PG8_ITER(t);
;         } else {
;             for (int t = 0; t < nt; t += 2) PG8_ITER(t);
;         }
;     ...
;         if constexpr (ALIGN_EPI) { if (wr == 0) PG8_BAR; }
;         if constexpr (!Epi::AFTER_DRAIN) { E(acc, cur, wr, wc, fr, fq); }
;         if (!has_next) break;
; #pragma unroll
;         for (int a = 0; a < 2; ++a)
; #pragma unroll
;             for (int b = 0; b < 2; ++b)
; #pragma unroll
;                 for (int m = 0; m < 4; ++m)
; #pragma unroll
;                     for (int n = 0; n < 2; ++n) acc[a][b][m][n] = (f32x4){0.f, 0.f, 0.f, 0.f};
;         cur = nxt; cA = nA; cB = nB; ++ui;
	s_or_b32 s47, s46, 0x80
	v_add_u32_e32 v185, s47, v133
	s_add_i32 s48, s48, s25
	ds_read_b128 v[174:177], v139 offset:49152
	ds_read_b128 v[178:181], v139 offset:50176
	ds_read_b128 v[192:195], v139 offset:51200
	ds_read_b128 v[196:199], v139 offset:52224
	ds_read_b128 v[200:203], v139 offset:53248
	ds_read_b128 v[204:207], v139 offset:54272
	ds_read_b128 v[208:211], v139 offset:55296
	ds_read_b128 v[212:215], v139 offset:56320
	s_mov_b32 m0, s48
	s_add_i32 s46, s46, 0x40080
	global_load_lds_dwordx4 v185, s[0:1]
	v_add_u32_e32 v185, s47, v135
	s_add_i32 m0, s48, 0x2000
	s_add_i32 s47, s49, s25
	global_load_lds_dwordx4 v185, s[0:1]
	v_add_u32_e32 v185, s46, v133
	s_mov_b32 m0, s47
	s_nop 0
	global_load_lds_dwordx4 v185, s[0:1]
	v_add_u32_e32 v185, s46, v135
	s_add_i32 m0, s47, 0x2000
	s_nop 0
	global_load_lds_dwordx4 v185, s[0:1]
	v_add_u32_e32 v185, s45, v132
	s_mov_b32 m0, s33
	s_nop 0
	global_load_lds_dwordx4 v185, s[10:11]
	v_add_u32_e32 v185, s45, v134
	s_mov_b32 m0, s34
	s_nop 0
	global_load_lds_dwordx4 v185, s[10:11]
	s_waitcnt vmcnt(8)
	s_waitcnt lgkmcnt(0)
	s_barrier
	s_waitcnt lgkmcnt(0)
	v_mfma_f32_16x16x32_bf16 v[60:63], v[142:145], v[174:177], v[60:63]
	v_mfma_f32_16x16x32_bf16 v[56:59], v[150:153], v[174:177], v[56:59]
	v_mfma_f32_16x16x32_bf16 v[44:47], v[142:145], v[192:195], v[44:47]
	v_mfma_f32_16x16x32_bf16 v[40:43], v[150:153], v[192:195], v[40:43]
	v_mfma_f32_16x16x32_bf16 v[28:31], v[142:145], v[200:203], v[28:31]
	v_mfma_f32_16x16x32_bf16 v[24:27], v[150:153], v[200:203], v[24:27]
	v_mfma_f32_16x16x32_bf16 v[12:15], v[142:145], v[208:211], v[12:15]
	v_mfma_f32_16x16x32_bf16 v[8:11], v[150:153], v[208:211], v[8:11]
	v_mfma_f32_16x16x32_bf16 v[60:63], v[146:149], v[178:181], v[60:63]
	v_mfma_f32_16x16x32_bf16 v[56:59], v[154:157], v[178:181], v[56:59]
	v_mfma_f32_16x16x32_bf16 v[44:47], v[146:149], v[196:199], v[44:47]
	v_mfma_f32_16x16x32_bf16 v[40:43], v[154:157], v[196:199], v[40:43]
	v_mfma_f32_16x16x32_bf16 v[28:31], v[146:149], v[204:207], v[28:31]
	v_mfma_f32_16x16x32_bf16 v[24:27], v[154:157], v[204:207], v[24:27]
	v_mfma_f32_16x16x32_bf16 v[12:15], v[146:149], v[212:215], v[12:15]
	v_mfma_f32_16x16x32_bf16 v[8:11], v[154:157], v[212:215], v[8:11]
	v_mfma_f32_16x16x32_bf16 v[52:55], v[158:161], v[174:177], v[52:55]
	v_mfma_f32_16x16x32_bf16 v[48:51], v[166:169], v[174:177], v[48:51]
	v_mfma_f32_16x16x32_bf16 v[36:39], v[158:161], v[192:195], v[36:39]
	v_mfma_f32_16x16x32_bf16 v[32:35], v[166:169], v[192:195], v[32:35]
	v_mfma_f32_16x16x32_bf16 v[20:23], v[158:161], v[200:203], v[20:23]
	v_mfma_f32_16x16x32_bf16 v[16:19], v[166:169], v[200:203], v[16:19]
	v_mfma_f32_16x16x32_bf16 v[4:7], v[158:161], v[208:211], v[4:7]
	v_mfma_f32_16x16x32_bf16 v[0:3], v[166:169], v[208:211], v[0:3]
	v_mfma_f32_16x16x32_bf16 v[52:55], v[162:165], v[178:181], v[52:55]
	v_mfma_f32_16x16x32_bf16 v[48:51], v[170:173], v[178:181], v[48:51]
	v_mfma_f32_16x16x32_bf16 v[36:39], v[162:165], v[196:199], v[36:39]
	v_mfma_f32_16x16x32_bf16 v[32:35], v[170:173], v[196:199], v[32:35]
	v_mfma_f32_16x16x32_bf16 v[20:23], v[162:165], v[204:207], v[20:23]
	v_mfma_f32_16x16x32_bf16 v[16:19], v[170:173], v[204:207], v[16:19]
	v_mfma_f32_16x16x32_bf16 v[4:7], v[162:165], v[212:215], v[4:7]
	v_mfma_f32_16x16x32_bf16 v[0:3], v[170:173], v[212:215], v[0:3]
	s_barrier
	s_add_i32 s43, s43, 2
	s_addk_i32 s44, 0x100
	s_cmp_gt_u32 s43, 13
	s_cbranch_scc0 .LBB0_674
	s_andn2_b64 vcc, exec, s[8:9]
	s_cbranch_vccnz .LBB0_666
	v_mov_b32_e32 v0, 0
	s_mov_b32 s16, s38
	s_mov_b32 s21, s39
	s_mov_b32 s27, s3
	s_mov_b32 s28, s2
	s_mov_b32 s35, s40
	v_mov_b32_e32 v1, v0
	v_mov_b32_e32 v2, v0
	v_mov_b32_e32 v3, v0
	v_mov_b32_e32 v4, v0
	v_mov_b32_e32 v5, v0
	v_mov_b32_e32 v6, v0
	v_mov_b32_e32 v7, v0
	v_mov_b32_e32 v16, v0
	v_mov_b32_e32 v17, v0
	v_mov_b32_e32 v18, v0
	v_mov_b32_e32 v19, v0
	v_mov_b32_e32 v20, v0
	v_mov_b32_e32 v21, v0
	v_mov_b32_e32 v22, v0
	v_mov_b32_e32 v23, v0
	v_mov_b32_e32 v32, v0
	v_mov_b32_e32 v33, v0
	v_mov_b32_e32 v34, v0
	v_mov_b32_e32 v35, v0
	v_mov_b32_e32 v36, v0
	v_mov_b32_e32 v37, v0
	v_mov_b32_e32 v38, v0
	v_mov_b32_e32 v39, v0
	v_mov_b32_e32 v48, v0
	v_mov_b32_e32 v49, v0
	v_mov_b32_e32 v50, v0
	v_mov_b32_e32 v51, v0
	v_mov_b32_e32 v52, v0
	v_mov_b32_e32 v53, v0
	v_mov_b32_e32 v54, v0
	v_mov_b32_e32 v55, v0
	v_mov_b32_e32 v8, v0
	v_mov_b32_e32 v9, v0
	v_mov_b32_e32 v10, v0
	v_mov_b32_e32 v11, v0
	v_mov_b32_e32 v12, v0
	v_mov_b32_e32 v13, v0
	v_mov_b32_e32 v14, v0
	v_mov_b32_e32 v15, v0
	v_mov_b32_e32 v24, v0
	v_mov_b32_e32 v25, v0
	v_mov_b32_e32 v26, v0
	v_mov_b32_e32 v27, v0
	v_mov_b32_e32 v28, v0
	v_mov_b32_e32 v29, v0
	v_mov_b32_e32 v30, v0
	v_mov_b32_e32 v31, v0
	v_mov_b32_e32 v40, v0
	v_mov_b32_e32 v41, v0
	v_mov_b32_e32 v42, v0
	v_mov_b32_e32 v43, v0
	v_mov_b32_e32 v44, v0
	v_mov_b32_e32 v45, v0
	v_mov_b32_e32 v46, v0
	v_mov_b32_e32 v47, v0
	v_mov_b32_e32 v56, v0
	v_mov_b32_e32 v57, v0
	v_mov_b32_e32 v58, v0
	v_mov_b32_e32 v59, v0
	v_mov_b32_e32 v60, v0
	v_mov_b32_e32 v61, v0
	v_mov_b32_e32 v62, v0
	v_mov_b32_e32 v63, v0
	v_mov_b32_e32 v64, v0
	v_mov_b32_e32 v65, v0
	v_mov_b32_e32 v66, v0
	v_mov_b32_e32 v67, v0
	v_mov_b32_e32 v68, v0
	v_mov_b32_e32 v69, v0
	v_mov_b32_e32 v70, v0
	v_mov_b32_e32 v71, v0
	v_mov_b32_e32 v80, v0
	v_mov_b32_e32 v81, v0
	v_mov_b32_e32 v82, v0
	v_mov_b32_e32 v83, v0
	v_mov_b32_e32 v84, v0
	v_mov_b32_e32 v85, v0
	v_mov_b32_e32 v86, v0
	v_mov_b32_e32 v87, v0
	v_mov_b32_e32 v96, v0
	v_mov_b32_e32 v97, v0
	v_mov_b32_e32 v98, v0
	v_mov_b32_e32 v99, v0
	v_mov_b32_e32 v100, v0
	v_mov_b32_e32 v101, v0
	v_mov_b32_e32 v102, v0
	v_mov_b32_e32 v103, v0
	v_mov_b32_e32 v112, v0
	v_mov_b32_e32 v113, v0
	v_mov_b32_e32 v114, v0
	v_mov_b32_e32 v115, v0
	v_mov_b32_e32 v116, v0
	v_mov_b32_e32 v117, v0
	v_mov_b32_e32 v118, v0
	v_mov_b32_e32 v119, v0
	v_mov_b32_e32 v72, v0
	v_mov_b32_e32 v73, v0
	v_mov_b32_e32 v74, v0
	v_mov_b32_e32 v75, v0
	v_mov_b32_e32 v76, v0
	v_mov_b32_e32 v77, v0
	v_mov_b32_e32 v78, v0
	v_mov_b32_e32 v79, v0
	v_mov_b32_e32 v88, v0
	v_mov_b32_e32 v89, v0
	v_mov_b32_e32 v90, v0
	v_mov_b32_e32 v91, v0
	v_mov_b32_e32 v92, v0
	v_mov_b32_e32 v93, v0
	v_mov_b32_e32 v94, v0
	v_mov_b32_e32 v95, v0
	v_mov_b32_e32 v104, v0
	v_mov_b32_e32 v105, v0
	v_mov_b32_e32 v106, v0
	v_mov_b32_e32 v107, v0
	v_mov_b32_e32 v108, v0
	v_mov_b32_e32 v109, v0
	v_mov_b32_e32 v110, v0
	v_mov_b32_e32 v111, v0
	v_mov_b32_e32 v120, v0
	v_mov_b32_e32 v121, v0
	v_mov_b32_e32 v122, v0
	v_mov_b32_e32 v123, v0
	v_mov_b32_e32 v124, v0
	v_mov_b32_e32 v125, v0
	v_mov_b32_e32 v126, v0
	v_mov_b32_e32 v127, v0
	s_branch .LBB0_666

.LBB0_780:
	ds_read_b128 v[128:131], v207
	ds_read_b128 v[132:135], v207 offset:1024
	ds_read_b128 v[136:139], v207 offset:2048
	ds_read_b128 v[140:143], v207 offset:3072
	ds_read_b128 v[144:147], v208
	ds_read_b128 v[148:151], v208 offset:1024
	ds_read_b128 v[152:155], v208 offset:2048
	ds_read_b128 v[156:159], v208 offset:3072
	s_add_i32 s12, s2, 0xffffe080
	s_cmp_eq_u32 s11, 12
	s_cselect_b32 s14, s0, s12
	s_cselect_b32 s13, s1, s3
	s_or_b32 s12, s14, 0x80
	v_add_u32_e32 v184, s2, v206
	ds_read_b128 v[164:167], v209
	ds_read_b128 v[168:171], v209 offset:1024
	ds_read_b128 v[172:175], v209 offset:2048
	ds_read_b128 v[176:179], v209 offset:3072
	ds_read_b128 v[180:183], v209 offset:4096
	ds_read_b128 v[210:213], v209 offset:5120
	ds_read_b128 v[214:217], v209 offset:6144
	ds_read_b128 v[218:221], v209 offset:7168
	s_add_i32 m0, s27, 0xc000
	s_nop 0
	global_load_lds_dwordx4 v184, s[22:23]
	v_add_u32_e32 v184, s2, v205
	s_add_i32 m0, s27, 0xe000
	s_nop 0
	global_load_lds_dwordx4 v184, s[22:23]
	s_waitcnt vmcnt(8)
	s_waitcnt lgkmcnt(0)
	s_barrier
	s_waitcnt lgkmcnt(0)
	v_mfma_f32_16x16x32_bf16 v[120:123], v[128:131], v[164:167], v[120:123]
	v_mfma_f32_16x16x32_bf16 v[56:59], v[136:139], v[164:167], v[56:59]
	v_mfma_f32_16x16x32_bf16 v[112:115], v[128:131], v[172:175], v[112:115]
	v_mfma_f32_16x16x32_bf16 v[48:51], v[136:139], v[172:175], v[48:51]
	v_mfma_f32_16x16x32_bf16 v[104:107], v[128:131], v[180:183], v[104:107]
	v_mfma_f32_16x16x32_bf16 v[40:43], v[136:139], v[180:183], v[40:43]
	v_mfma_f32_16x16x32_bf16 v[96:99], v[128:131], v[214:217], v[96:99]
	v_mfma_f32_16x16x32_bf16 v[32:35], v[136:139], v[214:217], v[32:35]
	v_mfma_f32_16x16x32_bf16 v[120:123], v[132:135], v[168:171], v[120:123]
	v_mfma_f32_16x16x32_bf16 v[56:59], v[140:143], v[168:171], v[56:59]
	v_mfma_f32_16x16x32_bf16 v[112:115], v[132:135], v[176:179], v[112:115]
	v_mfma_f32_16x16x32_bf16 v[48:51], v[140:143], v[176:179], v[48:51]
	v_mfma_f32_16x16x32_bf16 v[104:107], v[132:135], v[210:213], v[104:107]
	v_mfma_f32_16x16x32_bf16 v[40:43], v[140:143], v[210:213], v[40:43]
	v_mfma_f32_16x16x32_bf16 v[96:99], v[132:135], v[218:221], v[96:99]
	v_mfma_f32_16x16x32_bf16 v[32:35], v[140:143], v[218:221], v[32:35]
	v_mfma_f32_16x16x32_bf16 v[124:127], v[144:147], v[164:167], v[124:127]
	v_mfma_f32_16x16x32_bf16 v[60:63], v[152:155], v[164:167], v[60:63]
	v_mfma_f32_16x16x32_bf16 v[116:119], v[144:147], v[172:175], v[116:119]
	v_mfma_f32_16x16x32_bf16 v[52:55], v[152:155], v[172:175], v[52:55]
	v_mfma_f32_16x16x32_bf16 v[108:111], v[144:147], v[180:183], v[108:111]
	v_mfma_f32_16x16x32_bf16 v[44:47], v[152:155], v[180:183], v[44:47]
	v_mfma_f32_16x16x32_bf16 v[100:103], v[144:147], v[214:217], v[100:103]
	v_mfma_f32_16x16x32_bf16 v[36:39], v[152:155], v[214:217], v[36:39]
	v_mfma_f32_16x16x32_bf16 v[124:127], v[148:151], v[168:171], v[124:127]
	v_mfma_f32_16x16x32_bf16 v[60:63], v[156:159], v[168:171], v[60:63]
	v_mfma_f32_16x16x32_bf16 v[116:119], v[148:151], v[176:179], v[116:119]
	v_mfma_f32_16x16x32_bf16 v[52:55], v[156:159], v[176:179], v[52:55]
	v_mfma_f32_16x16x32_bf16 v[108:111], v[148:151], v[210:213], v[108:111]
	v_mfma_f32_16x16x32_bf16 v[44:47], v[156:159], v[210:213], v[44:47]
	v_mfma_f32_16x16x32_bf16 v[100:103], v[148:151], v[218:221], v[100:103]
	v_mfma_f32_16x16x32_bf16 v[36:39], v[156:159], v[218:221], v[36:39]
	s_barrier
	s_add_i32 s15, s71, s26
	ds_read_b128 v[164:167], v209 offset:16384
	ds_read_b128 v[168:171], v209 offset:17408
	ds_read_b128 v[172:175], v209 offset:18432
	ds_read_b128 v[176:179], v209 offset:19456
	ds_read_b128 v[180:183], v209 offset:20480
	ds_read_b128 v[210:213], v209 offset:21504
	ds_read_b128 v[214:217], v209 offset:22528
	ds_read_b128 v[218:221], v209 offset:23552
	v_add_u32_e32 v184, s13, v192
	s_mov_b32 m0, s15
	s_add_i32 s16, s72, s26
	global_load_lds_dwordx4 v184, s[36:37]
	v_add_u32_e32 v184, s13, v194
	s_add_i32 m0, s15, 0x2000
	s_add_i32 s15, s13, 0x40000
	global_load_lds_dwordx4 v184, s[36:37]
	v_add_u32_e32 v184, s15, v192
	s_mov_b32 m0, s16
	s_nop 0
	global_load_lds_dwordx4 v184, s[36:37]
	v_add_u32_e32 v184, s15, v194
	s_add_i32 m0, s16, 0x2000
	s_nop 0
	global_load_lds_dwordx4 v184, s[36:37]
	v_add_u32_e32 v184, s14, v191
	s_mov_b32 m0, s27
	s_nop 0
	global_load_lds_dwordx4 v184, s[22:23]
	v_add_u32_e32 v184, s14, v193
	s_mov_b32 m0, s33
	s_nop 0
	global_load_lds_dwordx4 v184, s[22:23]
	s_waitcnt vmcnt(8)
	s_waitcnt lgkmcnt(0)
	s_barrier
	s_waitcnt lgkmcnt(0)
	v_mfma_f32_16x16x32_bf16 v[88:91], v[128:131], v[164:167], v[88:91]
	v_mfma_f32_16x16x32_bf16 v[24:27], v[136:139], v[164:167], v[24:27]
	v_mfma_f32_16x16x32_bf16 v[72:75], v[128:131], v[172:175], v[72:75]
	v_mfma_f32_16x16x32_bf16 v[8:11], v[136:139], v[172:175], v[8:11]
	v_mfma_f32_16x16x32_bf16 v[68:71], v[128:131], v[180:183], v[68:71]
	v_mfma_f32_16x16x32_bf16 v[4:7], v[136:139], v[180:183], v[4:7]
	v_mfma_f32_16x16x32_bf16 v[64:67], v[128:131], v[214:217], v[64:67]
	v_mfma_f32_16x16x32_bf16 v[0:3], v[136:139], v[214:217], v[0:3]
	v_mfma_f32_16x16x32_bf16 v[88:91], v[132:135], v[168:171], v[88:91]
	v_mfma_f32_16x16x32_bf16 v[24:27], v[140:143], v[168:171], v[24:27]
	v_mfma_f32_16x16x32_bf16 v[72:75], v[132:135], v[176:179], v[72:75]
	v_mfma_f32_16x16x32_bf16 v[8:11], v[140:143], v[176:179], v[8:11]
	v_mfma_f32_16x16x32_bf16 v[68:71], v[132:135], v[210:213], v[68:71]
	v_mfma_f32_16x16x32_bf16 v[4:7], v[140:143], v[210:213], v[4:7]
	v_mfma_f32_16x16x32_bf16 v[64:67], v[132:135], v[218:221], v[64:67]
	v_mfma_f32_16x16x32_bf16 v[0:3], v[140:143], v[218:221], v[0:3]
	v_mfma_f32_16x16x32_bf16 v[92:95], v[144:147], v[164:167], v[92:95]
	v_mfma_f32_16x16x32_bf16 v[28:31], v[152:155], v[164:167], v[28:31]
	v_mfma_f32_16x16x32_bf16 v[76:79], v[144:147], v[172:175], v[76:79]
	v_mfma_f32_16x16x32_bf16 v[16:19], v[152:155], v[172:175], v[16:19]
	v_mfma_f32_16x16x32_bf16 v[84:87], v[144:147], v[180:183], v[84:87]
	v_mfma_f32_16x16x32_bf16 v[20:23], v[152:155], v[180:183], v[20:23]
	v_mfma_f32_16x16x32_bf16 v[80:83], v[144:147], v[214:217], v[80:83]
	v_mfma_f32_16x16x32_bf16 v[12:15], v[152:155], v[214:217], v[12:15]
	v_mfma_f32_16x16x32_bf16 v[92:95], v[148:151], v[168:171], v[92:95]
	v_mfma_f32_16x16x32_bf16 v[28:31], v[156:159], v[168:171], v[28:31]
	v_mfma_f32_16x16x32_bf16 v[76:79], v[148:151], v[176:179], v[76:79]
	v_mfma_f32_16x16x32_bf16 v[16:19], v[156:159], v[176:179], v[16:19]
	v_mfma_f32_16x16x32_bf16 v[84:87], v[148:151], v[210:213], v[84:87]
	v_mfma_f32_16x16x32_bf16 v[20:23], v[156:159], v[210:213], v[20:23]
	v_mfma_f32_16x16x32_bf16 v[80:83], v[148:151], v[218:221], v[80:83]
	v_mfma_f32_16x16x32_bf16 v[12:15], v[156:159], v[218:221], v[12:15]
	s_barrier
; #define PG8_BAR __builtin_amdgcn_s_barrier()
;     ...
;         if constexpr (Epi::MIDHOOK) {
;             for (int t = 0; t < 4; t += 2) PG8_ITER(t);
;             E.mid(acc, cur, wr, wc, fr, fq);
;             for (int t = 4; t < nt; t += 2) PG8_ITER(t);
;         } else {
;             for (int t = 0; t < nt; t += 2) PG8_ITER(t);
;         }
;     ...
;         if constexpr (ALIGN_EPI) { if (wr == 0) PG8_BAR; }
	s_add_i32 s15, 0, 0x18000
	s_add_i32 s16, 0, 0x1c000
	v_add_u32_e32 v140, s15, v195
	v_add_u32_e32 v156, s16, v195
	ds_read_b128 v[128:131], v140
	ds_read_b128 v[132:135], v140 offset:1024
	ds_read_b128 v[136:139], v140 offset:2048
	ds_read_b128 v[140:143], v140 offset:3072
	ds_read_b128 v[144:147], v156
	ds_read_b128 v[148:151], v156 offset:1024
	ds_read_b128 v[152:155], v156 offset:2048
	ds_read_b128 v[156:159], v156 offset:3072
	s_addk_i32 s14, 0x2000
	v_add_u32_e32 v184, s14, v191
	s_mov_b32 m0, s34
	ds_read_b128 v[164:167], v209 offset:32768
	ds_read_b128 v[168:171], v209 offset:33792
	ds_read_b128 v[172:175], v209 offset:34816
	ds_read_b128 v[176:179], v209 offset:35840
	ds_read_b128 v[180:183], v209 offset:36864
	ds_read_b128 v[210:213], v209 offset:37888
	ds_read_b128 v[214:217], v209 offset:38912
	ds_read_b128 v[218:221], v209 offset:39936
	s_nop 0
	global_load_lds_dwordx4 v184, s[22:23]
	v_add_u32_e32 v184, s14, v193
	s_mov_b32 m0, s35
	s_nop 0
	global_load_lds_dwordx4 v184, s[22:23]
	s_waitcnt vmcnt(8)
	s_waitcnt lgkmcnt(0)
	s_barrier
	s_waitcnt lgkmcnt(0)
	v_mfma_f32_16x16x32_bf16 v[120:123], v[128:131], v[164:167], v[120:123]
	v_mfma_f32_16x16x32_bf16 v[56:59], v[136:139], v[164:167], v[56:59]
	v_mfma_f32_16x16x32_bf16 v[112:115], v[128:131], v[172:175], v[112:115]
	v_mfma_f32_16x16x32_bf16 v[48:51], v[136:139], v[172:175], v[48:51]
	v_mfma_f32_16x16x32_bf16 v[104:107], v[128:131], v[180:183], v[104:107]
	v_mfma_f32_16x16x32_bf16 v[40:43], v[136:139], v[180:183], v[40:43]
	v_mfma_f32_16x16x32_bf16 v[96:99], v[128:131], v[214:217], v[96:99]
	v_mfma_f32_16x16x32_bf16 v[32:35], v[136:139], v[214:217], v[32:35]
	v_mfma_f32_16x16x32_bf16 v[120:123], v[132:135], v[168:171], v[120:123]
	v_mfma_f32_16x16x32_bf16 v[56:59], v[140:143], v[168:171], v[56:59]
	v_mfma_f32_16x16x32_bf16 v[112:115], v[132:135], v[176:179], v[112:115]
	v_mfma_f32_16x16x32_bf16 v[48:51], v[140:143], v[176:179], v[48:51]
	v_mfma_f32_16x16x32_bf16 v[104:107], v[132:135], v[210:213], v[104:107]
	v_mfma_f32_16x16x32_bf16 v[40:43], v[140:143], v[210:213], v[40:43]
	v_mfma_f32_16x16x32_bf16 v[96:99], v[132:135], v[218:221], v[96:99]
	v_mfma_f32_16x16x32_bf16 v[32:35], v[140:143], v[218:221], v[32:35]
	v_mfma_f32_16x16x32_bf16 v[124:127], v[144:147], v[164:167], v[124:127]
	v_mfma_f32_16x16x32_bf16 v[60:63], v[152:155], v[164:167], v[60:63]
	v_mfma_f32_16x16x32_bf16 v[116:119], v[144:147], v[172:175], v[116:119]
	v_mfma_f32_16x16x32_bf16 v[52:55], v[152:155], v[172:175], v[52:55]
	v_mfma_f32_16x16x32_bf16 v[108:111], v[144:147], v[180:183], v[108:111]
	v_mfma_f32_16x16x32_bf16 v[44:47], v[152:155], v[180:183], v[44:47]
	v_mfma_f32_16x16x32_bf16 v[100:103], v[144:147], v[214:217], v[100:103]
	v_mfma_f32_16x16x32_bf16 v[36:39], v[152:155], v[214:217], v[36:39]
	v_mfma_f32_16x16x32_bf16 v[124:127], v[148:151], v[168:171], v[124:127]
	v_mfma_f32_16x16x32_bf16 v[60:63], v[156:159], v[168:171], v[60:63]
	v_mfma_f32_16x16x32_bf16 v[116:119], v[148:151], v[176:179], v[116:119]
	v_mfma_f32_16x16x32_bf16 v[52:55], v[156:159], v[176:179], v[52:55]
	v_mfma_f32_16x16x32_bf16 v[108:111], v[148:151], v[210:213], v[108:111]
	v_mfma_f32_16x16x32_bf16 v[44:47], v[156:159], v[210:213], v[44:47]
	v_mfma_f32_16x16x32_bf16 v[100:103], v[148:151], v[218:221], v[100:103]
	v_mfma_f32_16x16x32_bf16 v[36:39], v[156:159], v[218:221], v[36:39]
	s_barrier
	s_or_b32 s14, s13, 0x80
	v_add_u32_e32 v184, s14, v192
	s_add_i32 s15, s15, s26
	ds_read_b128 v[164:167], v209 offset:49152
	ds_read_b128 v[168:171], v209 offset:50176
	ds_read_b128 v[172:175], v209 offset:51200
	ds_read_b128 v[176:179], v209 offset:52224
	ds_read_b128 v[180:183], v209 offset:53248
	ds_read_b128 v[210:213], v209 offset:54272
	ds_read_b128 v[214:217], v209 offset:55296
	ds_read_b128 v[218:221], v209 offset:56320
	s_mov_b32 m0, s15
	s_add_i32 s13, s13, 0x40080
	global_load_lds_dwordx4 v184, s[36:37]
	v_add_u32_e32 v184, s14, v194
	s_add_i32 m0, s15, 0x2000
	s_add_i32 s14, s16, s26
	global_load_lds_dwordx4 v184, s[36:37]
	v_add_u32_e32 v184, s13, v192
	s_mov_b32 m0, s14
	s_nop 0
	global_load_lds_dwordx4 v184, s[36:37]
	v_add_u32_e32 v184, s13, v194
	s_add_i32 m0, s14, 0x2000
	s_nop 0
	global_load_lds_dwordx4 v184, s[36:37]
	v_add_u32_e32 v184, s12, v191
	s_mov_b32 m0, s61
	s_nop 0
	global_load_lds_dwordx4 v184, s[22:23]
	v_add_u32_e32 v184, s12, v193
	s_mov_b32 m0, s63
	s_nop 0
	global_load_lds_dwordx4 v184, s[22:23]
	s_waitcnt vmcnt(8)
	s_waitcnt lgkmcnt(0)
	s_barrier
	s_waitcnt lgkmcnt(0)
	v_mfma_f32_16x16x32_bf16 v[88:91], v[128:131], v[164:167], v[88:91]
	v_mfma_f32_16x16x32_bf16 v[24:27], v[136:139], v[164:167], v[24:27]
	v_mfma_f32_16x16x32_bf16 v[72:75], v[128:131], v[172:175], v[72:75]
	v_mfma_f32_16x16x32_bf16 v[8:11], v[136:139], v[172:175], v[8:11]
	v_mfma_f32_16x16x32_bf16 v[68:71], v[128:131], v[180:183], v[68:71]
	v_mfma_f32_16x16x32_bf16 v[4:7], v[136:139], v[180:183], v[4:7]
	v_mfma_f32_16x16x32_bf16 v[64:67], v[128:131], v[214:217], v[64:67]
	v_mfma_f32_16x16x32_bf16 v[0:3], v[136:139], v[214:217], v[0:3]
	v_mfma_f32_16x16x32_bf16 v[88:91], v[132:135], v[168:171], v[88:91]
	v_mfma_f32_16x16x32_bf16 v[24:27], v[140:143], v[168:171], v[24:27]
	v_mfma_f32_16x16x32_bf16 v[72:75], v[132:135], v[176:179], v[72:75]
	v_mfma_f32_16x16x32_bf16 v[8:11], v[140:143], v[176:179], v[8:11]
	v_mfma_f32_16x16x32_bf16 v[68:71], v[132:135], v[210:213], v[68:71]
	v_mfma_f32_16x16x32_bf16 v[4:7], v[140:143], v[210:213], v[4:7]
	v_mfma_f32_16x16x32_bf16 v[64:67], v[132:135], v[218:221], v[64:67]
	v_mfma_f32_16x16x32_bf16 v[0:3], v[140:143], v[218:221], v[0:3]
	v_mfma_f32_16x16x32_bf16 v[92:95], v[144:147], v[164:167], v[92:95]
	v_mfma_f32_16x16x32_bf16 v[28:31], v[152:155], v[164:167], v[28:31]
	v_mfma_f32_16x16x32_bf16 v[76:79], v[144:147], v[172:175], v[76:79]
	v_mfma_f32_16x16x32_bf16 v[16:19], v[152:155], v[172:175], v[16:19]
	v_mfma_f32_16x16x32_bf16 v[84:87], v[144:147], v[180:183], v[84:87]
	v_mfma_f32_16x16x32_bf16 v[20:23], v[152:155], v[180:183], v[20:23]
	v_mfma_f32_16x16x32_bf16 v[80:83], v[144:147], v[214:217], v[80:83]
	v_mfma_f32_16x16x32_bf16 v[12:15], v[152:155], v[214:217], v[12:15]
	v_mfma_f32_16x16x32_bf16 v[92:95], v[148:151], v[168:171], v[92:95]
	v_mfma_f32_16x16x32_bf16 v[28:31], v[156:159], v[168:171], v[28:31]
	v_mfma_f32_16x16x32_bf16 v[76:79], v[148:151], v[176:179], v[76:79]
	v_mfma_f32_16x16x32_bf16 v[16:19], v[156:159], v[176:179], v[16:19]
	v_mfma_f32_16x16x32_bf16 v[84:87], v[148:151], v[210:213], v[84:87]
	v_mfma_f32_16x16x32_bf16 v[20:23], v[156:159], v[210:213], v[20:23]
	v_mfma_f32_16x16x32_bf16 v[80:83], v[148:151], v[218:221], v[80:83]
	v_mfma_f32_16x16x32_bf16 v[12:15], v[156:159], v[218:221], v[12:15]
	s_barrier
	s_add_i32 s11, s11, 2
	s_addk_i32 s2, 0x100
	s_addk_i32 s3, 0x100
	s_cmp_gt_u32 s11, 13
	s_cbranch_scc0 .LBB0_780
	s_and_b64 vcc, exec, s[42:43]
	s_cbranch_vccz .LBB0_783
	s_barrier

.LBB0_924:
	v_add_u32_e32 v154, s34, v136
	v_add_u32_e32 v162, s35, v136
	ds_read_b128 v[142:145], v154
	ds_read_b128 v[146:149], v154 offset:1024
	ds_read_b128 v[150:153], v154 offset:2048
	ds_read_b128 v[154:157], v154 offset:3072
	ds_read_b128 v[158:161], v162
	ds_read_b128 v[166:169], v162 offset:1024
	ds_read_b128 v[170:173], v162 offset:2048
	ds_read_b128 v[174:177], v162 offset:3072
	s_add_i32 s43, s46, 0x100
	s_add_i32 s44, s43, s26
	s_add_i32 s45, s39, s46
	s_cmpk_eq_i32 s46, 0x1500
	s_cselect_b32 s47, s40, s44
	s_cselect_b32 s45, s41, s45
	s_or_b32 s44, s47, 0x80
	v_add_u32_e32 v162, s46, v141
	ds_read_b128 v[178:181], v139
	ds_read_b128 v[182:185], v139 offset:1024
	ds_read_b128 v[192:195], v139 offset:2048
	ds_read_b128 v[196:199], v139 offset:3072
	ds_read_b128 v[200:203], v139 offset:4096
	ds_read_b128 v[204:207], v139 offset:5120
	ds_read_b128 v[208:211], v139 offset:6144
	ds_read_b128 v[212:215], v139 offset:7168
	s_add_i32 m0, s24, 0xc000
	s_nop 0
	global_load_lds_dwordx4 v162, s[2:3]
	v_add_u32_e32 v162, s46, v140
	s_add_i32 m0, s24, 0xe000
	s_nop 0
	global_load_lds_dwordx4 v162, s[2:3]
	s_waitcnt vmcnt(8)
	s_waitcnt lgkmcnt(0)
	s_barrier
	s_waitcnt lgkmcnt(0)
	v_mfma_f32_16x16x32_bf16 v[124:127], v[142:145], v[178:181], v[124:127]
	v_mfma_f32_16x16x32_bf16 v[120:123], v[150:153], v[178:181], v[120:123]
	v_mfma_f32_16x16x32_bf16 v[108:111], v[142:145], v[192:195], v[108:111]
	v_mfma_f32_16x16x32_bf16 v[104:107], v[150:153], v[192:195], v[104:107]
	v_mfma_f32_16x16x32_bf16 v[92:95], v[142:145], v[200:203], v[92:95]
	v_mfma_f32_16x16x32_bf16 v[88:91], v[150:153], v[200:203], v[88:91]
	v_mfma_f32_16x16x32_bf16 v[76:79], v[142:145], v[208:211], v[76:79]
	v_mfma_f32_16x16x32_bf16 v[72:75], v[150:153], v[208:211], v[72:75]
	v_mfma_f32_16x16x32_bf16 v[124:127], v[146:149], v[182:185], v[124:127]
	v_mfma_f32_16x16x32_bf16 v[120:123], v[154:157], v[182:185], v[120:123]
	v_mfma_f32_16x16x32_bf16 v[108:111], v[146:149], v[196:199], v[108:111]
	v_mfma_f32_16x16x32_bf16 v[104:107], v[154:157], v[196:199], v[104:107]
	v_mfma_f32_16x16x32_bf16 v[92:95], v[146:149], v[204:207], v[92:95]
	v_mfma_f32_16x16x32_bf16 v[88:91], v[154:157], v[204:207], v[88:91]
	v_mfma_f32_16x16x32_bf16 v[76:79], v[146:149], v[212:215], v[76:79]
	v_mfma_f32_16x16x32_bf16 v[72:75], v[154:157], v[212:215], v[72:75]
	v_mfma_f32_16x16x32_bf16 v[116:119], v[158:161], v[178:181], v[116:119]
	v_mfma_f32_16x16x32_bf16 v[112:115], v[170:173], v[178:181], v[112:115]
	v_mfma_f32_16x16x32_bf16 v[100:103], v[158:161], v[192:195], v[100:103]
	v_mfma_f32_16x16x32_bf16 v[96:99], v[170:173], v[192:195], v[96:99]
	v_mfma_f32_16x16x32_bf16 v[84:87], v[158:161], v[200:203], v[84:87]
	v_mfma_f32_16x16x32_bf16 v[80:83], v[170:173], v[200:203], v[80:83]
	v_mfma_f32_16x16x32_bf16 v[68:71], v[158:161], v[208:211], v[68:71]
	v_mfma_f32_16x16x32_bf16 v[64:67], v[170:173], v[208:211], v[64:67]
	v_mfma_f32_16x16x32_bf16 v[116:119], v[166:169], v[182:185], v[116:119]
	v_mfma_f32_16x16x32_bf16 v[112:115], v[174:177], v[182:185], v[112:115]
	v_mfma_f32_16x16x32_bf16 v[100:103], v[166:169], v[196:199], v[100:103]
	v_mfma_f32_16x16x32_bf16 v[96:99], v[174:177], v[196:199], v[96:99]
	v_mfma_f32_16x16x32_bf16 v[84:87], v[166:169], v[204:207], v[84:87]
	v_mfma_f32_16x16x32_bf16 v[80:83], v[174:177], v[204:207], v[80:83]
	v_mfma_f32_16x16x32_bf16 v[68:71], v[166:169], v[212:215], v[68:71]
	v_mfma_f32_16x16x32_bf16 v[64:67], v[174:177], v[212:215], v[64:67]
	s_barrier
	s_add_i32 s46, s34, s23
	ds_read_b128 v[178:181], v139 offset:16384
	ds_read_b128 v[182:185], v139 offset:17408
	ds_read_b128 v[192:195], v139 offset:18432
	ds_read_b128 v[196:199], v139 offset:19456
	ds_read_b128 v[200:203], v139 offset:20480
	ds_read_b128 v[204:207], v139 offset:21504
	ds_read_b128 v[208:211], v139 offset:22528
	ds_read_b128 v[212:215], v139 offset:23552
	v_add_u32_e32 v162, s45, v133
	s_mov_b32 m0, s46
	s_add_i32 s48, s35, s23
	global_load_lds_dwordx4 v162, s[14:15]
	v_add_u32_e32 v162, s45, v135
	s_add_i32 m0, s46, 0x2000
	s_add_i32 s46, s45, 0xb0000
	global_load_lds_dwordx4 v162, s[14:15]
	v_add_u32_e32 v162, s46, v133
	s_mov_b32 m0, s48
	s_nop 0
	global_load_lds_dwordx4 v162, s[14:15]
	v_add_u32_e32 v162, s46, v135
	s_add_i32 m0, s48, 0x2000
	s_nop 0
	global_load_lds_dwordx4 v162, s[14:15]
	v_add_u32_e32 v162, s47, v132
	s_mov_b32 m0, s24
	s_nop 0
	global_load_lds_dwordx4 v162, s[2:3]
	v_add_u32_e32 v162, s47, v134
	s_mov_b32 m0, s27
	s_nop 0
	global_load_lds_dwordx4 v162, s[2:3]
	s_waitcnt vmcnt(8)
	s_waitcnt lgkmcnt(0)
	s_barrier
	s_waitcnt lgkmcnt(0)
	v_mfma_f32_16x16x32_bf16 v[60:63], v[142:145], v[178:181], v[60:63]
	v_mfma_f32_16x16x32_bf16 v[56:59], v[150:153], v[178:181], v[56:59]
	v_mfma_f32_16x16x32_bf16 v[44:47], v[142:145], v[192:195], v[44:47]
	v_mfma_f32_16x16x32_bf16 v[40:43], v[150:153], v[192:195], v[40:43]
	v_mfma_f32_16x16x32_bf16 v[28:31], v[142:145], v[200:203], v[28:31]
	v_mfma_f32_16x16x32_bf16 v[24:27], v[150:153], v[200:203], v[24:27]
	v_mfma_f32_16x16x32_bf16 v[12:15], v[142:145], v[208:211], v[12:15]
	v_mfma_f32_16x16x32_bf16 v[8:11], v[150:153], v[208:211], v[8:11]
	v_mfma_f32_16x16x32_bf16 v[60:63], v[146:149], v[182:185], v[60:63]
	v_mfma_f32_16x16x32_bf16 v[56:59], v[154:157], v[182:185], v[56:59]
	v_mfma_f32_16x16x32_bf16 v[44:47], v[146:149], v[196:199], v[44:47]
	v_mfma_f32_16x16x32_bf16 v[40:43], v[154:157], v[196:199], v[40:43]
	v_mfma_f32_16x16x32_bf16 v[28:31], v[146:149], v[204:207], v[28:31]
	v_mfma_f32_16x16x32_bf16 v[24:27], v[154:157], v[204:207], v[24:27]
	v_mfma_f32_16x16x32_bf16 v[12:15], v[146:149], v[212:215], v[12:15]
	v_mfma_f32_16x16x32_bf16 v[8:11], v[154:157], v[212:215], v[8:11]
	v_mfma_f32_16x16x32_bf16 v[52:55], v[158:161], v[178:181], v[52:55]
	v_mfma_f32_16x16x32_bf16 v[48:51], v[170:173], v[178:181], v[48:51]
	v_mfma_f32_16x16x32_bf16 v[36:39], v[158:161], v[192:195], v[36:39]
	v_mfma_f32_16x16x32_bf16 v[32:35], v[170:173], v[192:195], v[32:35]
	v_mfma_f32_16x16x32_bf16 v[20:23], v[158:161], v[200:203], v[20:23]
	v_mfma_f32_16x16x32_bf16 v[16:19], v[170:173], v[200:203], v[16:19]
	v_mfma_f32_16x16x32_bf16 v[4:7], v[158:161], v[208:211], v[4:7]
	v_mfma_f32_16x16x32_bf16 v[0:3], v[170:173], v[208:211], v[0:3]
	v_mfma_f32_16x16x32_bf16 v[52:55], v[166:169], v[182:185], v[52:55]
	v_mfma_f32_16x16x32_bf16 v[48:51], v[174:177], v[182:185], v[48:51]
	v_mfma_f32_16x16x32_bf16 v[36:39], v[166:169], v[196:199], v[36:39]
	v_mfma_f32_16x16x32_bf16 v[32:35], v[174:177], v[196:199], v[32:35]
	v_mfma_f32_16x16x32_bf16 v[20:23], v[166:169], v[204:207], v[20:23]
	v_mfma_f32_16x16x32_bf16 v[16:19], v[174:177], v[204:207], v[16:19]
	v_mfma_f32_16x16x32_bf16 v[4:7], v[166:169], v[212:215], v[4:7]
	v_mfma_f32_16x16x32_bf16 v[0:3], v[174:177], v[212:215], v[0:3]
	s_barrier
	s_add_i32 s46, 0, 0x18000
	s_add_i32 s48, 0, 0x1c000
	v_add_u32_e32 v154, s46, v136
	v_add_u32_e32 v162, s48, v136
	ds_read_b128 v[142:145], v154
	ds_read_b128 v[146:149], v154 offset:1024
	ds_read_b128 v[150:153], v154 offset:2048
	ds_read_b128 v[154:157], v154 offset:3072
	ds_read_b128 v[158:161], v162
	ds_read_b128 v[166:169], v162 offset:1024
	ds_read_b128 v[170:173], v162 offset:2048
	ds_read_b128 v[174:177], v162 offset:3072
	s_add_i32 s47, s47, 0xb0000
	v_add_u32_e32 v162, s47, v132
	s_mov_b32 m0, s28
	ds_read_b128 v[178:181], v139 offset:32768
	ds_read_b128 v[182:185], v139 offset:33792
	ds_read_b128 v[192:195], v139 offset:34816
	ds_read_b128 v[196:199], v139 offset:35840
	ds_read_b128 v[200:203], v139 offset:36864
	ds_read_b128 v[204:207], v139 offset:37888
	ds_read_b128 v[208:211], v139 offset:38912
	ds_read_b128 v[212:215], v139 offset:39936
	s_nop 0
	global_load_lds_dwordx4 v162, s[2:3]
	v_add_u32_e32 v162, s47, v134
	s_mov_b32 m0, s29
	s_nop 0
	global_load_lds_dwordx4 v162, s[2:3]
	s_waitcnt vmcnt(8)
	s_waitcnt lgkmcnt(0)
	s_barrier
	s_waitcnt lgkmcnt(0)
	v_mfma_f32_16x16x32_bf16 v[124:127], v[142:145], v[178:181], v[124:127]
	v_mfma_f32_16x16x32_bf16 v[120:123], v[150:153], v[178:181], v[120:123]
	v_mfma_f32_16x16x32_bf16 v[108:111], v[142:145], v[192:195], v[108:111]
	v_mfma_f32_16x16x32_bf16 v[104:107], v[150:153], v[192:195], v[104:107]
	v_mfma_f32_16x16x32_bf16 v[92:95], v[142:145], v[200:203], v[92:95]
	v_mfma_f32_16x16x32_bf16 v[88:91], v[150:153], v[200:203], v[88:91]
	v_mfma_f32_16x16x32_bf16 v[76:79], v[142:145], v[208:211], v[76:79]
	v_mfma_f32_16x16x32_bf16 v[72:75], v[150:153], v[208:211], v[72:75]
	v_mfma_f32_16x16x32_bf16 v[124:127], v[146:149], v[182:185], v[124:127]
	v_mfma_f32_16x16x32_bf16 v[120:123], v[154:157], v[182:185], v[120:123]
	v_mfma_f32_16x16x32_bf16 v[108:111], v[146:149], v[196:199], v[108:111]
	v_mfma_f32_16x16x32_bf16 v[104:107], v[154:157], v[196:199], v[104:107]
	v_mfma_f32_16x16x32_bf16 v[92:95], v[146:149], v[204:207], v[92:95]
	v_mfma_f32_16x16x32_bf16 v[88:91], v[154:157], v[204:207], v[88:91]
	v_mfma_f32_16x16x32_bf16 v[76:79], v[146:149], v[212:215], v[76:79]
	v_mfma_f32_16x16x32_bf16 v[72:75], v[154:157], v[212:215], v[72:75]
	v_mfma_f32_16x16x32_bf16 v[116:119], v[158:161], v[178:181], v[116:119]
	v_mfma_f32_16x16x32_bf16 v[112:115], v[170:173], v[178:181], v[112:115]
	v_mfma_f32_16x16x32_bf16 v[100:103], v[158:161], v[192:195], v[100:103]
	v_mfma_f32_16x16x32_bf16 v[96:99], v[170:173], v[192:195], v[96:99]
	v_mfma_f32_16x16x32_bf16 v[84:87], v[158:161], v[200:203], v[84:87]
	v_mfma_f32_16x16x32_bf16 v[80:83], v[170:173], v[200:203], v[80:83]
	v_mfma_f32_16x16x32_bf16 v[68:71], v[158:161], v[208:211], v[68:71]
	v_mfma_f32_16x16x32_bf16 v[64:67], v[170:173], v[208:211], v[64:67]
	v_mfma_f32_16x16x32_bf16 v[116:119], v[166:169], v[182:185], v[116:119]
	v_mfma_f32_16x16x32_bf16 v[112:115], v[174:177], v[182:185], v[112:115]
	v_mfma_f32_16x16x32_bf16 v[100:103], v[166:169], v[196:199], v[100:103]
	v_mfma_f32_16x16x32_bf16 v[96:99], v[174:177], v[196:199], v[96:99]
	v_mfma_f32_16x16x32_bf16 v[84:87], v[166:169], v[204:207], v[84:87]
	v_mfma_f32_16x16x32_bf16 v[80:83], v[174:177], v[204:207], v[80:83]
	v_mfma_f32_16x16x32_bf16 v[68:71], v[166:169], v[212:215], v[68:71]
	v_mfma_f32_16x16x32_bf16 v[64:67], v[174:177], v[212:215], v[64:67]
	s_barrier
; #define PG8_BAR __builtin_amdgcn_s_barrier()
;     ...
;         if constexpr (Epi::MIDHOOK) {
;             for (int t = 0; t < 4; t += 2) PG8_ITER(t);
;             E.mid(acc, cur, wr, wc, fr, fq);
;             for (int t = 4; t < nt; t += 2) PG8_ITER(t);
;         } else {
;             for (int t = 0; t < nt; t += 2) PG8_ITER(t);
;         }
;     ...
;         if constexpr (ALIGN_EPI) { if (wr == 0) PG8_BAR; }
;         if constexpr (!Epi::AFTER_DRAIN) { E(acc, cur, wr, wc, fr, fq); }
;         if (!has_next) break;
; #pragma unroll
;         for (int a = 0; a < 2; ++a)
; #pragma unroll
;             for (int b = 0; b < 2; ++b)
; #pragma unroll
;                 for (int m = 0; m < 4; ++m)
; #pragma unroll
;                     for (int n = 0; n < 2; ++n) acc[a][b][m][n] = (f32x4){0.f, 0.f, 0.f, 0.f};
;         cur = nxt; cA = nA; cB = nB; ++ui;
	s_or_b32 s47, s45, 0x80
	v_add_u32_e32 v162, s47, v133
	s_add_i32 s46, s46, s23
	ds_read_b128 v[178:181], v139 offset:49152
	ds_read_b128 v[182:185], v139 offset:50176
	ds_read_b128 v[192:195], v139 offset:51200
	ds_read_b128 v[196:199], v139 offset:52224
	ds_read_b128 v[200:203], v139 offset:53248
	ds_read_b128 v[204:207], v139 offset:54272
	ds_read_b128 v[208:211], v139 offset:55296
	ds_read_b128 v[212:215], v139 offset:56320
	s_mov_b32 m0, s46
	s_add_i32 s45, s45, 0xb0080
	global_load_lds_dwordx4 v162, s[14:15]
	v_add_u32_e32 v162, s47, v135
	s_add_i32 m0, s46, 0x2000
	s_add_i32 s46, s48, s23
	global_load_lds_dwordx4 v162, s[14:15]
	v_add_u32_e32 v162, s45, v133
	s_mov_b32 m0, s46
	s_nop 0
	global_load_lds_dwordx4 v162, s[14:15]
	v_add_u32_e32 v162, s45, v135
	s_add_i32 m0, s46, 0x2000
	s_nop 0
	global_load_lds_dwordx4 v162, s[14:15]
	v_add_u32_e32 v162, s44, v132
	s_mov_b32 m0, s30
	s_nop 0
	global_load_lds_dwordx4 v162, s[2:3]
	v_add_u32_e32 v162, s44, v134
	s_mov_b32 m0, s31
	s_nop 0
	global_load_lds_dwordx4 v162, s[2:3]
	s_waitcnt vmcnt(8)
	s_waitcnt lgkmcnt(0)
	s_barrier
	s_waitcnt lgkmcnt(0)
	v_mfma_f32_16x16x32_bf16 v[60:63], v[142:145], v[178:181], v[60:63]
	v_mfma_f32_16x16x32_bf16 v[56:59], v[150:153], v[178:181], v[56:59]
	v_mfma_f32_16x16x32_bf16 v[44:47], v[142:145], v[192:195], v[44:47]
	v_mfma_f32_16x16x32_bf16 v[40:43], v[150:153], v[192:195], v[40:43]
	v_mfma_f32_16x16x32_bf16 v[28:31], v[142:145], v[200:203], v[28:31]
	v_mfma_f32_16x16x32_bf16 v[24:27], v[150:153], v[200:203], v[24:27]
	v_mfma_f32_16x16x32_bf16 v[12:15], v[142:145], v[208:211], v[12:15]
	v_mfma_f32_16x16x32_bf16 v[8:11], v[150:153], v[208:211], v[8:11]
	v_mfma_f32_16x16x32_bf16 v[60:63], v[146:149], v[182:185], v[60:63]
	v_mfma_f32_16x16x32_bf16 v[56:59], v[154:157], v[182:185], v[56:59]
	v_mfma_f32_16x16x32_bf16 v[44:47], v[146:149], v[196:199], v[44:47]
	v_mfma_f32_16x16x32_bf16 v[40:43], v[154:157], v[196:199], v[40:43]
	v_mfma_f32_16x16x32_bf16 v[28:31], v[146:149], v[204:207], v[28:31]
	v_mfma_f32_16x16x32_bf16 v[24:27], v[154:157], v[204:207], v[24:27]
	v_mfma_f32_16x16x32_bf16 v[12:15], v[146:149], v[212:215], v[12:15]
	v_mfma_f32_16x16x32_bf16 v[8:11], v[154:157], v[212:215], v[8:11]
	v_mfma_f32_16x16x32_bf16 v[52:55], v[158:161], v[178:181], v[52:55]
	v_mfma_f32_16x16x32_bf16 v[48:51], v[170:173], v[178:181], v[48:51]
	v_mfma_f32_16x16x32_bf16 v[36:39], v[158:161], v[192:195], v[36:39]
	v_mfma_f32_16x16x32_bf16 v[32:35], v[170:173], v[192:195], v[32:35]
	v_mfma_f32_16x16x32_bf16 v[20:23], v[158:161], v[200:203], v[20:23]
	v_mfma_f32_16x16x32_bf16 v[16:19], v[170:173], v[200:203], v[16:19]
	v_mfma_f32_16x16x32_bf16 v[4:7], v[158:161], v[208:211], v[4:7]
	v_mfma_f32_16x16x32_bf16 v[0:3], v[170:173], v[208:211], v[0:3]
	v_mfma_f32_16x16x32_bf16 v[52:55], v[166:169], v[182:185], v[52:55]
	v_mfma_f32_16x16x32_bf16 v[48:51], v[174:177], v[182:185], v[48:51]
	v_mfma_f32_16x16x32_bf16 v[36:39], v[166:169], v[196:199], v[36:39]
	v_mfma_f32_16x16x32_bf16 v[32:35], v[174:177], v[196:199], v[32:35]
	v_mfma_f32_16x16x32_bf16 v[20:23], v[166:169], v[204:207], v[20:23]
	v_mfma_f32_16x16x32_bf16 v[16:19], v[174:177], v[204:207], v[16:19]
	v_mfma_f32_16x16x32_bf16 v[4:7], v[166:169], v[212:215], v[4:7]
	v_mfma_f32_16x16x32_bf16 v[0:3], v[174:177], v[212:215], v[0:3]
	s_barrier
	s_add_i32 s42, s42, 2
	s_cmp_gt_u32 s42, 41
	s_mov_b32 s46, s43
	s_cbranch_scc0 .LBB0_924
	s_andn2_b64 vcc, exec, s[4:5]
	s_cbranch_vccnz .LBB0_916
	v_mov_b32_e32 v0, 0
	s_mov_b32 s12, s36
	s_mov_b32 s19, s37
	s_mov_b32 s25, s17
	s_mov_b32 s26, s16
	s_mov_b32 s33, s38
	v_mov_b32_e32 v1, v0
	v_mov_b32_e32 v2, v0
	v_mov_b32_e32 v3, v0
	v_mov_b32_e32 v4, v0
	v_mov_b32_e32 v5, v0
	v_mov_b32_e32 v6, v0
	v_mov_b32_e32 v7, v0
	v_mov_b32_e32 v16, v0
	v_mov_b32_e32 v17, v0
	v_mov_b32_e32 v18, v0
	v_mov_b32_e32 v19, v0
	v_mov_b32_e32 v20, v0
	v_mov_b32_e32 v21, v0
	v_mov_b32_e32 v22, v0
	v_mov_b32_e32 v23, v0
	v_mov_b32_e32 v32, v0
	v_mov_b32_e32 v33, v0
	v_mov_b32_e32 v34, v0
	v_mov_b32_e32 v35, v0
	v_mov_b32_e32 v36, v0
	v_mov_b32_e32 v37, v0
	v_mov_b32_e32 v38, v0
	v_mov_b32_e32 v39, v0
	v_mov_b32_e32 v48, v0
	v_mov_b32_e32 v49, v0
	v_mov_b32_e32 v50, v0
	v_mov_b32_e32 v51, v0
	v_mov_b32_e32 v52, v0
	v_mov_b32_e32 v53, v0
	v_mov_b32_e32 v54, v0
	v_mov_b32_e32 v55, v0
	v_mov_b32_e32 v8, v0
	v_mov_b32_e32 v9, v0
	v_mov_b32_e32 v10, v0
	v_mov_b32_e32 v11, v0
	v_mov_b32_e32 v12, v0
	v_mov_b32_e32 v13, v0
	v_mov_b32_e32 v14, v0
	v_mov_b32_e32 v15, v0
	v_mov_b32_e32 v24, v0
	v_mov_b32_e32 v25, v0
	v_mov_b32_e32 v26, v0
	v_mov_b32_e32 v27, v0
	v_mov_b32_e32 v28, v0
	v_mov_b32_e32 v29, v0
	v_mov_b32_e32 v30, v0
	v_mov_b32_e32 v31, v0
	v_mov_b32_e32 v40, v0
	v_mov_b32_e32 v41, v0
	v_mov_b32_e32 v42, v0
	v_mov_b32_e32 v43, v0
	v_mov_b32_e32 v44, v0
	v_mov_b32_e32 v45, v0
	v_mov_b32_e32 v46, v0
	v_mov_b32_e32 v47, v0
	v_mov_b32_e32 v56, v0
	v_mov_b32_e32 v57, v0
	v_mov_b32_e32 v58, v0
	v_mov_b32_e32 v59, v0
	v_mov_b32_e32 v60, v0
	v_mov_b32_e32 v61, v0
	v_mov_b32_e32 v62, v0
	v_mov_b32_e32 v63, v0
	v_mov_b32_e32 v64, v0
	v_mov_b32_e32 v65, v0
	v_mov_b32_e32 v66, v0
	v_mov_b32_e32 v67, v0
	v_mov_b32_e32 v68, v0
	v_mov_b32_e32 v69, v0
	v_mov_b32_e32 v70, v0
	v_mov_b32_e32 v71, v0
	v_mov_b32_e32 v80, v0
	v_mov_b32_e32 v81, v0
	v_mov_b32_e32 v82, v0
	v_mov_b32_e32 v83, v0
	v_mov_b32_e32 v84, v0
	v_mov_b32_e32 v85, v0
	v_mov_b32_e32 v86, v0
	v_mov_b32_e32 v87, v0
	v_mov_b32_e32 v96, v0
	v_mov_b32_e32 v97, v0
	v_mov_b32_e32 v98, v0
	v_mov_b32_e32 v99, v0
	v_mov_b32_e32 v100, v0
	v_mov_b32_e32 v101, v0
	v_mov_b32_e32 v102, v0
	v_mov_b32_e32 v103, v0
	v_mov_b32_e32 v112, v0
	v_mov_b32_e32 v113, v0
	v_mov_b32_e32 v114, v0
	v_mov_b32_e32 v115, v0
	v_mov_b32_e32 v116, v0
	v_mov_b32_e32 v117, v0
	v_mov_b32_e32 v118, v0
	v_mov_b32_e32 v119, v0
	v_mov_b32_e32 v72, v0
	v_mov_b32_e32 v73, v0
	v_mov_b32_e32 v74, v0
	v_mov_b32_e32 v75, v0
	v_mov_b32_e32 v76, v0
	v_mov_b32_e32 v77, v0
	v_mov_b32_e32 v78, v0
	v_mov_b32_e32 v79, v0
	v_mov_b32_e32 v88, v0
	v_mov_b32_e32 v89, v0
	v_mov_b32_e32 v90, v0
	v_mov_b32_e32 v91, v0
	v_mov_b32_e32 v92, v0
	v_mov_b32_e32 v93, v0
	v_mov_b32_e32 v94, v0
	v_mov_b32_e32 v95, v0
	v_mov_b32_e32 v104, v0
	v_mov_b32_e32 v105, v0
	v_mov_b32_e32 v106, v0
	v_mov_b32_e32 v107, v0
	v_mov_b32_e32 v108, v0
	v_mov_b32_e32 v109, v0
	v_mov_b32_e32 v110, v0
	v_mov_b32_e32 v111, v0
	v_mov_b32_e32 v120, v0
	v_mov_b32_e32 v121, v0
	v_mov_b32_e32 v122, v0
	v_mov_b32_e32 v123, v0
	v_mov_b32_e32 v124, v0
	v_mov_b32_e32 v125, v0
	v_mov_b32_e32 v126, v0
	v_mov_b32_e32 v127, v0
	s_branch .LBB0_916
